# v28 + counted LDS-DMA waits moved to the barrier before each stage's first reader (vmcnt(10) x6 instead of vmcnt(6) x2) in all 8 GEMM loops
# speedup vs baseline: 1.0091x; 1.0091x over previous
.LBB0_412:
	ds_read_b128 v[128:131], v170
	ds_read_b128 v[132:135], v170 offset:1024
	ds_read_b128 v[164:167], v170 offset:2048
	ds_read_b128 v[176:179], v170 offset:3072
	s_add_u32 s8, s6, 0xfffc0080
	s_addc_u32 s9, s7, -1
	s_cmp_eq_u32 s38, 12
	s_cselect_b32 s11, s25, s9
	s_cselect_b32 s10, s31, s8
	s_cselect_b32 s9, s23, s36
	s_cselect_b32 s8, s34, s35
	v_lshl_add_u64 v[168:169], s[6:7], 0, v[158:159]
	s_add_i32 m0, s49, 0xc000
	ds_read_b128 v[180:183], v171
	ds_read_b128 v[184:187], v171 offset:1024
	ds_read_b128 v[188:191], v171 offset:2048
	ds_read_b128 v[192:195], v171 offset:3072
	ds_read_b128 v[196:199], v171 offset:4096
	ds_read_b128 v[200:203], v171 offset:5120
	ds_read_b128 v[204:207], v171 offset:6144
	ds_read_b128 v[208:211], v171 offset:7168
	global_load_lds_dwordx4 v[168:169], off
	v_lshl_add_u64 v[168:169], s[6:7], 0, v[156:157]
	s_add_i32 m0, s49, 0xe000
	s_nop 0
	global_load_lds_dwordx4 v[168:169], off
	s_waitcnt lgkmcnt(8)
	s_waitcnt vmcnt(10)
	s_barrier
	s_waitcnt lgkmcnt(0)
	s_setprio 1
	s_waitcnt lgkmcnt(0)
	v_mfma_f32_16x16x32_bf16 v[124:127], v[128:131], v[180:183], v[124:127]
	v_mfma_f32_16x16x32_bf16 v[120:123], v[164:167], v[180:183], v[120:123]
	v_mfma_f32_16x16x32_bf16 v[108:111], v[128:131], v[188:191], v[108:111]
	v_mfma_f32_16x16x32_bf16 v[104:107], v[164:167], v[188:191], v[104:107]
	v_mfma_f32_16x16x32_bf16 v[92:95], v[128:131], v[196:199], v[92:95]
	v_mfma_f32_16x16x32_bf16 v[88:91], v[164:167], v[196:199], v[88:91]
	v_mfma_f32_16x16x32_bf16 v[76:79], v[128:131], v[204:207], v[76:79]
	v_mfma_f32_16x16x32_bf16 v[72:75], v[164:167], v[204:207], v[72:75]
	v_mfma_f32_16x16x32_bf16 v[124:127], v[132:135], v[184:187], v[124:127]
	v_mfma_f32_16x16x32_bf16 v[120:123], v[176:179], v[184:187], v[120:123]
	v_mfma_f32_16x16x32_bf16 v[108:111], v[132:135], v[192:195], v[108:111]
	v_mfma_f32_16x16x32_bf16 v[104:107], v[176:179], v[192:195], v[104:107]
	v_mfma_f32_16x16x32_bf16 v[92:95], v[132:135], v[200:203], v[92:95]
	v_mfma_f32_16x16x32_bf16 v[88:91], v[176:179], v[200:203], v[88:91]
	v_mfma_f32_16x16x32_bf16 v[76:79], v[132:135], v[208:211], v[76:79]
	v_mfma_f32_16x16x32_bf16 v[72:75], v[176:179], v[208:211], v[72:75]
	s_setprio 0
	s_barrier
	s_add_i32 s39, s58, s48
	v_lshl_add_u64 v[168:169], s[8:9], 0, v[138:139]
	s_mov_b32 m0, s39
	ds_read_b128 v[212:215], v172
	ds_read_b128 v[216:219], v172 offset:1024
	ds_read_b128 v[220:223], v172 offset:2048
	ds_read_b128 v[224:227], v172 offset:3072
	global_load_lds_dwordx4 v[168:169], off
	v_lshl_add_u64 v[228:229], s[8:9], 0, v[136:137]
	s_add_i32 m0, s39, 0x2000
	s_nop 0
	global_load_lds_dwordx4 v[228:229], off
	s_waitcnt vmcnt(10)
	s_barrier
	s_waitcnt lgkmcnt(0)
	s_setprio 1
	s_waitcnt lgkmcnt(0)
	v_mfma_f32_16x16x32_bf16 v[116:119], v[212:215], v[180:183], v[116:119]
	v_mfma_f32_16x16x32_bf16 v[112:115], v[220:223], v[180:183], v[112:115]
	v_mfma_f32_16x16x32_bf16 v[100:103], v[212:215], v[188:191], v[100:103]
	v_mfma_f32_16x16x32_bf16 v[96:99], v[220:223], v[188:191], v[96:99]
	v_mfma_f32_16x16x32_bf16 v[84:87], v[212:215], v[196:199], v[84:87]
	v_mfma_f32_16x16x32_bf16 v[80:83], v[220:223], v[196:199], v[80:83]
	v_mfma_f32_16x16x32_bf16 v[68:71], v[212:215], v[204:207], v[68:71]
	v_mfma_f32_16x16x32_bf16 v[64:67], v[220:223], v[204:207], v[64:67]
	v_mfma_f32_16x16x32_bf16 v[116:119], v[216:219], v[184:187], v[116:119]
	v_mfma_f32_16x16x32_bf16 v[112:115], v[224:227], v[184:187], v[112:115]
	v_mfma_f32_16x16x32_bf16 v[100:103], v[216:219], v[192:195], v[100:103]
	v_mfma_f32_16x16x32_bf16 v[96:99], v[224:227], v[192:195], v[96:99]
	v_mfma_f32_16x16x32_bf16 v[84:87], v[216:219], v[200:203], v[84:87]
	v_mfma_f32_16x16x32_bf16 v[80:83], v[224:227], v[200:203], v[80:83]
	v_mfma_f32_16x16x32_bf16 v[68:71], v[216:219], v[208:211], v[68:71]
	v_mfma_f32_16x16x32_bf16 v[64:67], v[224:227], v[208:211], v[64:67]
	s_setprio 0
	s_mov_b32 m0, s49
	v_lshl_add_u64 v[230:231], s[10:11], 0, v[138:139]
	s_barrier
	ds_read_b128 v[180:183], v171 offset:16384
	ds_read_b128 v[184:187], v171 offset:17408
	ds_read_b128 v[188:191], v171 offset:18432
	ds_read_b128 v[192:195], v171 offset:19456
	ds_read_b128 v[196:199], v171 offset:20480
	ds_read_b128 v[200:203], v171 offset:21504
	ds_read_b128 v[204:207], v171 offset:22528
	ds_read_b128 v[208:211], v171 offset:23552
	global_load_lds_dwordx4 v[230:231], off
	v_lshl_add_u64 v[232:233], s[10:11], 0, v[136:137]
	s_mov_b32 m0, s50
	s_nop 0
	global_load_lds_dwordx4 v[232:233], off
	s_barrier
	s_waitcnt lgkmcnt(0)
	s_setprio 1
	s_waitcnt lgkmcnt(0)
	v_mfma_f32_16x16x32_bf16 v[60:63], v[128:131], v[180:183], v[60:63]
	v_mfma_f32_16x16x32_bf16 v[56:59], v[164:167], v[180:183], v[56:59]
	v_mfma_f32_16x16x32_bf16 v[44:47], v[128:131], v[188:191], v[44:47]
	v_mfma_f32_16x16x32_bf16 v[40:43], v[164:167], v[188:191], v[40:43]
	v_mfma_f32_16x16x32_bf16 v[28:31], v[128:131], v[196:199], v[28:31]
	v_mfma_f32_16x16x32_bf16 v[24:27], v[164:167], v[196:199], v[24:27]
	v_mfma_f32_16x16x32_bf16 v[12:15], v[128:131], v[204:207], v[12:15]
	v_mfma_f32_16x16x32_bf16 v[8:11], v[164:167], v[204:207], v[8:11]
	v_mfma_f32_16x16x32_bf16 v[60:63], v[132:135], v[184:187], v[60:63]
	v_mfma_f32_16x16x32_bf16 v[56:59], v[176:179], v[184:187], v[56:59]
	v_mfma_f32_16x16x32_bf16 v[44:47], v[132:135], v[192:195], v[44:47]
	v_mfma_f32_16x16x32_bf16 v[40:43], v[176:179], v[192:195], v[40:43]
	v_mfma_f32_16x16x32_bf16 v[28:31], v[132:135], v[200:203], v[28:31]
	v_mfma_f32_16x16x32_bf16 v[24:27], v[176:179], v[200:203], v[24:27]
	v_mfma_f32_16x16x32_bf16 v[12:15], v[132:135], v[208:211], v[12:15]
	v_mfma_f32_16x16x32_bf16 v[8:11], v[176:179], v[208:211], v[8:11]
	s_setprio 0
	s_barrier
	s_add_u32 s40, s8, 0x40000
	s_addc_u32 s41, s9, 0
	s_add_i32 s39, s59, s48
	v_lshl_add_u64 v[128:129], s[40:41], 0, v[138:139]
	s_mov_b32 m0, s39
	s_nop 0
	global_load_lds_dwordx4 v[128:129], off
	v_lshl_add_u64 v[128:129], s[40:41], 0, v[136:137]
	s_add_i32 m0, s39, 0x2000
	s_nop 0
	global_load_lds_dwordx4 v[128:129], off
	s_waitcnt vmcnt(10)
	s_barrier
	s_setprio 1
	v_mfma_f32_16x16x32_bf16 v[52:55], v[212:215], v[180:183], v[52:55]
	v_mfma_f32_16x16x32_bf16 v[48:51], v[220:223], v[180:183], v[48:51]
	v_mfma_f32_16x16x32_bf16 v[36:39], v[212:215], v[188:191], v[36:39]
	v_mfma_f32_16x16x32_bf16 v[32:35], v[220:223], v[188:191], v[32:35]
	v_mfma_f32_16x16x32_bf16 v[20:23], v[212:215], v[196:199], v[20:23]
	v_mfma_f32_16x16x32_bf16 v[16:19], v[220:223], v[196:199], v[16:19]
	v_mfma_f32_16x16x32_bf16 v[4:7], v[212:215], v[204:207], v[4:7]
	v_mfma_f32_16x16x32_bf16 v[0:3], v[220:223], v[204:207], v[0:3]
	v_mfma_f32_16x16x32_bf16 v[52:55], v[216:219], v[184:187], v[52:55]
	v_mfma_f32_16x16x32_bf16 v[48:51], v[224:227], v[184:187], v[48:51]
	v_mfma_f32_16x16x32_bf16 v[36:39], v[216:219], v[192:195], v[36:39]
	v_mfma_f32_16x16x32_bf16 v[32:35], v[224:227], v[192:195], v[32:35]
	v_mfma_f32_16x16x32_bf16 v[20:23], v[216:219], v[200:203], v[20:23]
	v_mfma_f32_16x16x32_bf16 v[16:19], v[224:227], v[200:203], v[16:19]
	v_mfma_f32_16x16x32_bf16 v[4:7], v[216:219], v[208:211], v[4:7]
	v_mfma_f32_16x16x32_bf16 v[0:3], v[224:227], v[208:211], v[0:3]
	s_setprio 0
	s_add_i32 s39, 0, 0x18000
	v_add_u32_e32 v176, s39, v149
	s_barrier
	ds_read_b128 v[128:131], v176
	ds_read_b128 v[132:135], v176 offset:1024
	ds_read_b128 v[164:167], v176 offset:2048
	ds_read_b128 v[176:179], v176 offset:3072
	s_add_u32 s10, s10, 0x40000
	s_addc_u32 s11, s11, 0
	s_mov_b32 m0, s51
	v_lshl_add_u64 v[212:213], s[10:11], 0, v[138:139]
	ds_read_b128 v[180:183], v171 offset:32768
	ds_read_b128 v[184:187], v171 offset:33792
	ds_read_b128 v[188:191], v171 offset:34816
	ds_read_b128 v[192:195], v171 offset:35840
	ds_read_b128 v[196:199], v171 offset:36864
	ds_read_b128 v[200:203], v171 offset:37888
	ds_read_b128 v[204:207], v171 offset:38912
	ds_read_b128 v[208:211], v171 offset:39936
	global_load_lds_dwordx4 v[212:213], off
	v_lshl_add_u64 v[212:213], s[10:11], 0, v[136:137]
	s_mov_b32 m0, s52
	s_nop 0
	global_load_lds_dwordx4 v[212:213], off
	s_waitcnt lgkmcnt(8)
	s_waitcnt vmcnt(10)
	s_barrier
	s_waitcnt lgkmcnt(0)
	s_setprio 1
	s_waitcnt lgkmcnt(0)
	v_mfma_f32_16x16x32_bf16 v[124:127], v[128:131], v[180:183], v[124:127]
	v_mfma_f32_16x16x32_bf16 v[120:123], v[164:167], v[180:183], v[120:123]
	v_mfma_f32_16x16x32_bf16 v[108:111], v[128:131], v[188:191], v[108:111]
	v_mfma_f32_16x16x32_bf16 v[104:107], v[164:167], v[188:191], v[104:107]
	v_mfma_f32_16x16x32_bf16 v[92:95], v[128:131], v[196:199], v[92:95]
	v_mfma_f32_16x16x32_bf16 v[88:91], v[164:167], v[196:199], v[88:91]
	v_mfma_f32_16x16x32_bf16 v[76:79], v[128:131], v[204:207], v[76:79]
	v_mfma_f32_16x16x32_bf16 v[72:75], v[164:167], v[204:207], v[72:75]
	v_mfma_f32_16x16x32_bf16 v[124:127], v[132:135], v[184:187], v[124:127]
	v_mfma_f32_16x16x32_bf16 v[120:123], v[176:179], v[184:187], v[120:123]
	v_mfma_f32_16x16x32_bf16 v[108:111], v[132:135], v[192:195], v[108:111]
	v_mfma_f32_16x16x32_bf16 v[104:107], v[176:179], v[192:195], v[104:107]
	v_mfma_f32_16x16x32_bf16 v[92:95], v[132:135], v[200:203], v[92:95]
	v_mfma_f32_16x16x32_bf16 v[88:91], v[176:179], v[200:203], v[88:91]
	v_mfma_f32_16x16x32_bf16 v[76:79], v[132:135], v[208:211], v[76:79]
	v_mfma_f32_16x16x32_bf16 v[72:75], v[176:179], v[208:211], v[72:75]
	s_setprio 0
	s_barrier
	s_add_i32 s10, 0, 0x1c000
	s_add_i32 s11, s39, s48
	v_add_u32_e32 v224, s10, v149
	v_lshl_add_u64 v[168:169], v[168:169], 0, s[16:17]
	s_mov_b32 m0, s11
	ds_read_b128 v[212:215], v224
	ds_read_b128 v[216:219], v224 offset:1024
	ds_read_b128 v[220:223], v224 offset:2048
	ds_read_b128 v[224:227], v224 offset:3072
	global_load_lds_dwordx4 v[168:169], off
	v_lshl_add_u64 v[168:169], v[228:229], 0, s[16:17]
	s_add_i32 m0, s11, 0x2000
	s_nop 0
	global_load_lds_dwordx4 v[168:169], off
	s_waitcnt vmcnt(10)
	s_barrier
	s_waitcnt lgkmcnt(0)
	s_setprio 1
	s_waitcnt lgkmcnt(0)
	v_mfma_f32_16x16x32_bf16 v[116:119], v[212:215], v[180:183], v[116:119]
	v_mfma_f32_16x16x32_bf16 v[112:115], v[220:223], v[180:183], v[112:115]
	v_mfma_f32_16x16x32_bf16 v[100:103], v[212:215], v[188:191], v[100:103]
	v_mfma_f32_16x16x32_bf16 v[96:99], v[220:223], v[188:191], v[96:99]
	v_mfma_f32_16x16x32_bf16 v[84:87], v[212:215], v[196:199], v[84:87]
	v_mfma_f32_16x16x32_bf16 v[80:83], v[220:223], v[196:199], v[80:83]
	v_mfma_f32_16x16x32_bf16 v[68:71], v[212:215], v[204:207], v[68:71]
	v_mfma_f32_16x16x32_bf16 v[64:67], v[220:223], v[204:207], v[64:67]
	v_mfma_f32_16x16x32_bf16 v[116:119], v[216:219], v[184:187], v[116:119]
	v_mfma_f32_16x16x32_bf16 v[112:115], v[224:227], v[184:187], v[112:115]
	v_mfma_f32_16x16x32_bf16 v[100:103], v[216:219], v[192:195], v[100:103]
	v_mfma_f32_16x16x32_bf16 v[96:99], v[224:227], v[192:195], v[96:99]
	v_mfma_f32_16x16x32_bf16 v[84:87], v[216:219], v[200:203], v[84:87]
	v_mfma_f32_16x16x32_bf16 v[80:83], v[224:227], v[200:203], v[80:83]
	v_mfma_f32_16x16x32_bf16 v[68:71], v[216:219], v[208:211], v[68:71]
	v_mfma_f32_16x16x32_bf16 v[64:67], v[224:227], v[208:211], v[64:67]
	s_setprio 0
	s_mov_b32 m0, s56
	v_lshl_add_u64 v[168:169], v[230:231], 0, s[16:17]
	s_barrier
	ds_read_b128 v[180:183], v171 offset:49152
	ds_read_b128 v[184:187], v171 offset:50176
	ds_read_b128 v[188:191], v171 offset:51200
	ds_read_b128 v[192:195], v171 offset:52224
	ds_read_b128 v[196:199], v171 offset:53248
	ds_read_b128 v[200:203], v171 offset:54272
	ds_read_b128 v[204:207], v171 offset:55296
	ds_read_b128 v[208:211], v171 offset:56320
	global_load_lds_dwordx4 v[168:169], off
	v_lshl_add_u64 v[168:169], v[232:233], 0, s[16:17]
	s_mov_b32 m0, s57
	s_nop 0
	global_load_lds_dwordx4 v[168:169], off
	s_barrier
	s_waitcnt lgkmcnt(0)
	s_setprio 1
	s_waitcnt lgkmcnt(0)
	v_mfma_f32_16x16x32_bf16 v[60:63], v[128:131], v[180:183], v[60:63]
	v_mfma_f32_16x16x32_bf16 v[56:59], v[164:167], v[180:183], v[56:59]
	v_mfma_f32_16x16x32_bf16 v[44:47], v[128:131], v[188:191], v[44:47]
	v_mfma_f32_16x16x32_bf16 v[40:43], v[164:167], v[188:191], v[40:43]
	v_mfma_f32_16x16x32_bf16 v[28:31], v[128:131], v[196:199], v[28:31]
	v_mfma_f32_16x16x32_bf16 v[24:27], v[164:167], v[196:199], v[24:27]
	v_mfma_f32_16x16x32_bf16 v[12:15], v[128:131], v[204:207], v[12:15]
	v_mfma_f32_16x16x32_bf16 v[8:11], v[164:167], v[204:207], v[8:11]
	v_mfma_f32_16x16x32_bf16 v[60:63], v[132:135], v[184:187], v[60:63]
	v_mfma_f32_16x16x32_bf16 v[56:59], v[176:179], v[184:187], v[56:59]
	v_mfma_f32_16x16x32_bf16 v[44:47], v[132:135], v[192:195], v[44:47]
	v_mfma_f32_16x16x32_bf16 v[40:43], v[176:179], v[192:195], v[40:43]
	v_mfma_f32_16x16x32_bf16 v[28:31], v[132:135], v[200:203], v[28:31]
	v_mfma_f32_16x16x32_bf16 v[24:27], v[176:179], v[200:203], v[24:27]
	v_mfma_f32_16x16x32_bf16 v[12:15], v[132:135], v[208:211], v[12:15]
	v_mfma_f32_16x16x32_bf16 v[8:11], v[176:179], v[208:211], v[8:11]
	s_setprio 0
	s_barrier
	s_add_u32 s8, s8, 0x40080
	s_addc_u32 s9, s9, 0
	s_add_i32 s10, s10, s48
	v_lshl_add_u64 v[128:129], s[8:9], 0, v[138:139]
	s_mov_b32 m0, s10
	s_nop 0
	global_load_lds_dwordx4 v[128:129], off
	v_lshl_add_u64 v[128:129], s[8:9], 0, v[136:137]
	s_add_i32 m0, s10, 0x2000
	s_nop 0
	global_load_lds_dwordx4 v[128:129], off
	s_waitcnt vmcnt(10)
	s_barrier
	s_setprio 1
	v_mfma_f32_16x16x32_bf16 v[52:55], v[212:215], v[180:183], v[52:55]
	v_mfma_f32_16x16x32_bf16 v[48:51], v[220:223], v[180:183], v[48:51]
	v_mfma_f32_16x16x32_bf16 v[36:39], v[212:215], v[188:191], v[36:39]
	v_mfma_f32_16x16x32_bf16 v[32:35], v[220:223], v[188:191], v[32:35]
	v_mfma_f32_16x16x32_bf16 v[20:23], v[212:215], v[196:199], v[20:23]
	v_mfma_f32_16x16x32_bf16 v[16:19], v[220:223], v[196:199], v[16:19]
	v_mfma_f32_16x16x32_bf16 v[4:7], v[212:215], v[204:207], v[4:7]
	v_mfma_f32_16x16x32_bf16 v[0:3], v[220:223], v[204:207], v[0:3]
	v_mfma_f32_16x16x32_bf16 v[52:55], v[216:219], v[184:187], v[52:55]
	v_mfma_f32_16x16x32_bf16 v[48:51], v[224:227], v[184:187], v[48:51]
	v_mfma_f32_16x16x32_bf16 v[36:39], v[216:219], v[192:195], v[36:39]
	v_mfma_f32_16x16x32_bf16 v[32:35], v[224:227], v[192:195], v[32:35]
	v_mfma_f32_16x16x32_bf16 v[20:23], v[216:219], v[200:203], v[20:23]
	v_mfma_f32_16x16x32_bf16 v[16:19], v[224:227], v[200:203], v[16:19]
	v_mfma_f32_16x16x32_bf16 v[4:7], v[216:219], v[208:211], v[4:7]
	v_mfma_f32_16x16x32_bf16 v[0:3], v[224:227], v[208:211], v[0:3]
	s_setprio 0
	s_add_i32 s38, s38, 2
	s_add_u32 s35, s35, 0x100
	s_addc_u32 s36, s36, 0
	s_add_u32 s6, s6, 0x100
	s_addc_u32 s7, s7, 0
	s_cmp_gt_u32 s38, 13
	s_barrier
	s_cbranch_scc0 .LBB0_412
	s_lshl_b32 s36, s37, 1
	s_add_i32 s6, s36, 0xffffff80
	s_lshr_b32 s63, s6, 4
	s_lshl_b32 s6, s30, 8
	s_add_i32 s63, s63, 4
	s_ashr_i32 s64, s37, 4
	s_or_b32 s23, s6, s55
	s_and_b32 s6, s30, 0xfffffe
	s_cmp_eq_u32 s6, 6
	s_cselect_b64 s[34:35], -1, 0
	s_cmp_eq_u32 s30, 7
	s_cselect_b64 s[30:31], -1, 0
	s_lshl_b32 s6, s37, 8
	s_cmp_lt_i32 s37, 64
	s_movk_i32 s7, 0xf00
	s_cselect_b32 s7, s7, 0x700
	s_cselect_b32 s8, s64, s63
	s_cselect_b32 s25, s60, 0x800
	s_cselect_b32 s65, 12, 11
	s_and_b32 s66, s7, s6
	s_lshl_b32 s7, s8, 11
	s_lshl_b32 s6, s8, 12
	s_addk_i32 s7, 0x2000
	s_cmp_lt_i32 s8, 4
	s_cselect_b32 s6, s6, s7
	s_ashr_i32 s7, s6, 31
	s_lshl_b64 s[6:7], s[6:7], 10
	s_add_u32 s38, s53, s6
	s_addc_u32 s39, s54, s7
	s_ashr_i32 s37, s36, 31
	v_add_u32_e32 v176, s66, v142
	s_lshl_b64 s[40:41], s[36:37], 7
	v_mul_lo_u32 v130, v176, 56
	s_lshr_b32 s67, s25, 1
	v_lshl_add_u64 v[128:129], s[40:41], 0, v[142:143]
	v_ashrrev_i32_e32 v131, 31, v130
	v_lshl_add_u64 v[168:169], v[130:131], 3, s[14:15]
	v_mad_u64_u32 v[164:165], s[8:9], v128, s61, 0
	s_cmpk_gt_i32 s23, 0x1ff
	v_mad_i32_i24 v165, v129, s61, v165
	v_lshl_add_u64 v[128:129], v[168:169], 0, s[18:19]
	s_cselect_b64 s[10:11], -1, 0
	v_cmp_lt_i32_e64 s[6:7], s67, v176
	v_lshl_add_u64 v[166:167], v[128:129], 0, v[140:141]
	s_mov_b64 s[8:9], -1
	s_and_b64 vcc, exec, s[10:11]
	s_cbranch_vccz .LBB0_424
	s_cmpk_gt_u32 s23, 0x109f
	s_cbranch_scc1 .LBB0_423
	s_add_i32 s8, s23, 0xfffffe00
	s_cmpk_gt_u32 s8, 0x1ff
	s_mov_b64 s[42:43], -1
	s_cbranch_scc0 .LBB0_421
	s_add_i32 s9, s23, 0xfffff700
	s_cmpk_lt_u32 s9, 0x400
	s_cselect_b64 s[42:43], -1, 0
	s_or_b64 s[42:43], s[34:35], s[42:43]
	v_mov_b64_e32 v[134:135], v[126:127]
	v_mov_b64_e32 v[130:131], v[122:123]
	s_andn2_b64 vcc, exec, s[42:43]
	v_mov_b64_e32 v[132:133], v[124:125]
	v_mov_b64_e32 v[128:129], v[120:121]
	s_cbranch_vccnz .LBB0_420
	s_andn2_b64 vcc, exec, s[20:21]
	v_mov_b32_e32 v128, v124
	v_mov_b32_e32 v129, v125
	v_mov_b32_e32 v130, v126
	v_mov_b32_e32 v131, v127
	s_cbranch_vccnz .LBB0_419
	v_and_b32_e32 v129, 64, v173
	v_xor_b32_e32 v128, 32, v173
	v_add_u32_e32 v129, 64, v129
	v_cmp_lt_i32_e32 vcc, v128, v129
	v_mov_b32_e32 v129, v141
	s_nop 0
	v_cndmask_b32_e32 v128, v173, v128, vcc
	v_lshlrev_b32_e32 v177, 2, v128
	v_lshlrev_b32_e32 v128, 3, v146
	v_lshl_add_u64 v[132:133], v[168:169], 0, v[128:129]
	s_waitcnt vmcnt(0)
	global_load_dwordx4 v[128:131], v[132:133], off offset:128
	ds_bpermute_b32 v134, v177, v124
	ds_bpermute_b32 v135, v177, v125
	s_waitcnt vmcnt(0) lgkmcnt(0)
	v_mov_b32_e32 v179, v130
	v_mov_b32_e32 v130, v129
	v_mov_b32_e32 v178, v128
	v_pk_mul_f32 v[128:129], v[130:131], v[134:135]
	global_load_dwordx4 v[130:133], v[132:133], off offset:144
	ds_bpermute_b32 v134, v177, v126
	ds_bpermute_b32 v135, v177, v127
	v_cndmask_b32_e64 v129, v129, -v129, s[0:1]
	v_cndmask_b32_e64 v128, v128, -v128, s[0:1]
	v_pk_fma_f32 v[128:129], v[124:125], v[178:179], v[128:129]
	s_waitcnt vmcnt(0) lgkmcnt(0)
	v_mov_b32_e32 v179, v132
	v_mov_b32_e32 v132, v131
	v_mov_b32_e32 v178, v130
	v_pk_mul_f32 v[130:131], v[132:133], v[134:135]
	s_nop 0
	v_cndmask_b32_e64 v131, v131, -v131, s[0:1]
	v_cndmask_b32_e64 v130, v130, -v130, s[0:1]
	v_pk_fma_f32 v[130:131], v[126:127], v[178:179], v[130:131]

.LBB0_1051:
	ds_read_b128 v[152:155], v149
	ds_read_b128 v[156:159], v149 offset:1024
	ds_read_b128 v[160:163], v149 offset:2048
	ds_read_b128 v[164:167], v149 offset:3072
	s_add_u32 s4, s18, 0x100
	s_addc_u32 s5, s19, 0
	s_cmp_eq_u32 s45, 12
	s_cselect_b32 s23, s15, s5
	s_cselect_b32 s22, s14, s4
	s_cselect_b32 s21, s13, s44
	s_cselect_b32 s20, s42, s43
	v_lshl_add_u64 v[168:169], s[18:19], 0, v[140:141]
	s_add_i32 m0, s29, 0xc000
	ds_read_b128 v[172:175], v150
	ds_read_b128 v[176:179], v150 offset:1024
	ds_read_b128 v[180:183], v150 offset:2048
	ds_read_b128 v[184:187], v150 offset:3072
	ds_read_b128 v[188:191], v150 offset:4096
	ds_read_b128 v[192:195], v150 offset:5120
	ds_read_b128 v[196:199], v150 offset:6144
	ds_read_b128 v[200:203], v150 offset:7168
	global_load_lds_dwordx4 v[168:169], off
	v_lshl_add_u64 v[168:169], s[18:19], 0, v[138:139]
	s_add_i32 m0, s29, 0xe000
	s_nop 0
	global_load_lds_dwordx4 v[168:169], off
	s_waitcnt lgkmcnt(8)
	s_waitcnt vmcnt(10)
	s_barrier
	s_waitcnt lgkmcnt(0)
	s_setprio 1
	s_waitcnt lgkmcnt(0)
	v_mfma_f32_16x16x32_bf16 v[124:127], v[152:155], v[172:175], v[124:127]
	v_mfma_f32_16x16x32_bf16 v[120:123], v[160:163], v[172:175], v[120:123]
	v_mfma_f32_16x16x32_bf16 v[116:119], v[152:155], v[180:183], v[116:119]
	v_mfma_f32_16x16x32_bf16 v[108:111], v[160:163], v[180:183], v[108:111]
	v_mfma_f32_16x16x32_bf16 v[100:103], v[152:155], v[188:191], v[100:103]
	v_mfma_f32_16x16x32_bf16 v[92:95], v[160:163], v[188:191], v[92:95]
	v_mfma_f32_16x16x32_bf16 v[84:87], v[152:155], v[196:199], v[84:87]
	v_mfma_f32_16x16x32_bf16 v[76:79], v[160:163], v[196:199], v[76:79]
	v_mfma_f32_16x16x32_bf16 v[124:127], v[156:159], v[176:179], v[124:127]
	v_mfma_f32_16x16x32_bf16 v[120:123], v[164:167], v[176:179], v[120:123]
	v_mfma_f32_16x16x32_bf16 v[116:119], v[156:159], v[184:187], v[116:119]
	v_mfma_f32_16x16x32_bf16 v[108:111], v[164:167], v[184:187], v[108:111]
	v_mfma_f32_16x16x32_bf16 v[100:103], v[156:159], v[192:195], v[100:103]
	v_mfma_f32_16x16x32_bf16 v[92:95], v[164:167], v[192:195], v[92:95]
	v_mfma_f32_16x16x32_bf16 v[84:87], v[156:159], v[200:203], v[84:87]
	v_mfma_f32_16x16x32_bf16 v[76:79], v[164:167], v[200:203], v[76:79]
	s_setprio 0
	s_barrier
	s_add_i32 s18, s36, s28
	v_lshl_add_u64 v[168:169], s[20:21], 0, v[132:133]
	s_mov_b32 m0, s18
	ds_read_b128 v[204:207], v151
	ds_read_b128 v[208:211], v151 offset:1024
	ds_read_b128 v[212:215], v151 offset:2048
	ds_read_b128 v[216:219], v151 offset:3072
	global_load_lds_dwordx4 v[168:169], off
	v_lshl_add_u64 v[220:221], s[20:21], 0, v[128:129]
	s_add_i32 m0, s18, 0x2000
	s_nop 0
	global_load_lds_dwordx4 v[220:221], off
	s_waitcnt vmcnt(10)
	s_barrier
	s_waitcnt lgkmcnt(0)
	s_setprio 1
	s_waitcnt lgkmcnt(0)
	v_mfma_f32_16x16x32_bf16 v[112:115], v[204:207], v[172:175], v[112:115]
	v_mfma_f32_16x16x32_bf16 v[104:107], v[212:215], v[172:175], v[104:107]
	v_mfma_f32_16x16x32_bf16 v[96:99], v[204:207], v[180:183], v[96:99]
	v_mfma_f32_16x16x32_bf16 v[88:91], v[212:215], v[180:183], v[88:91]
	v_mfma_f32_16x16x32_bf16 v[80:83], v[204:207], v[188:191], v[80:83]
	v_mfma_f32_16x16x32_bf16 v[72:75], v[212:215], v[188:191], v[72:75]
	v_mfma_f32_16x16x32_bf16 v[68:71], v[204:207], v[196:199], v[68:71]
	v_mfma_f32_16x16x32_bf16 v[64:67], v[212:215], v[196:199], v[64:67]
	v_mfma_f32_16x16x32_bf16 v[112:115], v[208:211], v[176:179], v[112:115]
	v_mfma_f32_16x16x32_bf16 v[104:107], v[216:219], v[176:179], v[104:107]
	v_mfma_f32_16x16x32_bf16 v[96:99], v[208:211], v[184:187], v[96:99]
	v_mfma_f32_16x16x32_bf16 v[88:91], v[216:219], v[184:187], v[88:91]
	v_mfma_f32_16x16x32_bf16 v[80:83], v[208:211], v[192:195], v[80:83]
	v_mfma_f32_16x16x32_bf16 v[72:75], v[216:219], v[192:195], v[72:75]
	v_mfma_f32_16x16x32_bf16 v[68:71], v[208:211], v[200:203], v[68:71]
	v_mfma_f32_16x16x32_bf16 v[64:67], v[216:219], v[200:203], v[64:67]
	s_setprio 0
	s_mov_b32 m0, s29
	v_lshl_add_u64 v[222:223], s[22:23], 0, v[134:135]
	s_barrier
	ds_read_b128 v[172:175], v150 offset:16384
	ds_read_b128 v[176:179], v150 offset:17408
	ds_read_b128 v[180:183], v150 offset:18432
	ds_read_b128 v[184:187], v150 offset:19456
	ds_read_b128 v[188:191], v150 offset:20480
	ds_read_b128 v[192:195], v150 offset:21504
	ds_read_b128 v[196:199], v150 offset:22528
	ds_read_b128 v[200:203], v150 offset:23552
	global_load_lds_dwordx4 v[222:223], off
	v_lshl_add_u64 v[224:225], s[22:23], 0, v[130:131]
	s_mov_b32 m0, s30
	s_nop 0
	global_load_lds_dwordx4 v[224:225], off
	s_barrier
	s_waitcnt lgkmcnt(0)
	s_setprio 1
	s_waitcnt lgkmcnt(0)
	v_mfma_f32_16x16x32_bf16 v[60:63], v[152:155], v[172:175], v[60:63]
	v_mfma_f32_16x16x32_bf16 v[56:59], v[160:163], v[172:175], v[56:59]
	v_mfma_f32_16x16x32_bf16 v[52:55], v[152:155], v[180:183], v[52:55]
	v_mfma_f32_16x16x32_bf16 v[44:47], v[160:163], v[180:183], v[44:47]
	v_mfma_f32_16x16x32_bf16 v[36:39], v[152:155], v[188:191], v[36:39]
	v_mfma_f32_16x16x32_bf16 v[28:31], v[160:163], v[188:191], v[28:31]
	v_mfma_f32_16x16x32_bf16 v[20:23], v[152:155], v[196:199], v[20:23]
	v_mfma_f32_16x16x32_bf16 v[12:15], v[160:163], v[196:199], v[12:15]
	v_mfma_f32_16x16x32_bf16 v[60:63], v[156:159], v[176:179], v[60:63]
	v_mfma_f32_16x16x32_bf16 v[56:59], v[164:167], v[176:179], v[56:59]
	v_mfma_f32_16x16x32_bf16 v[52:55], v[156:159], v[184:187], v[52:55]
	v_mfma_f32_16x16x32_bf16 v[44:47], v[164:167], v[184:187], v[44:47]
	v_mfma_f32_16x16x32_bf16 v[36:39], v[156:159], v[192:195], v[36:39]
	v_mfma_f32_16x16x32_bf16 v[28:31], v[164:167], v[192:195], v[28:31]
	v_mfma_f32_16x16x32_bf16 v[20:23], v[156:159], v[200:203], v[20:23]
	v_mfma_f32_16x16x32_bf16 v[12:15], v[164:167], v[200:203], v[12:15]
	s_setprio 0
	s_barrier
	s_add_u32 s18, s20, 0x40000
	s_addc_u32 s19, s21, 0
	s_add_i32 s46, s37, s28
	v_lshl_add_u64 v[152:153], s[18:19], 0, v[132:133]
	s_mov_b32 m0, s46
	s_nop 0
	global_load_lds_dwordx4 v[152:153], off
	v_lshl_add_u64 v[152:153], s[18:19], 0, v[128:129]
	s_add_i32 m0, s46, 0x2000
	s_nop 0
	global_load_lds_dwordx4 v[152:153], off
	s_waitcnt vmcnt(10)
	s_barrier
	s_setprio 1
	v_mfma_f32_16x16x32_bf16 v[48:51], v[204:207], v[172:175], v[48:51]
	v_mfma_f32_16x16x32_bf16 v[40:43], v[212:215], v[172:175], v[40:43]
	v_mfma_f32_16x16x32_bf16 v[32:35], v[204:207], v[180:183], v[32:35]
	v_mfma_f32_16x16x32_bf16 v[24:27], v[212:215], v[180:183], v[24:27]
	v_mfma_f32_16x16x32_bf16 v[16:19], v[204:207], v[188:191], v[16:19]
	v_mfma_f32_16x16x32_bf16 v[8:11], v[212:215], v[188:191], v[8:11]
	v_mfma_f32_16x16x32_bf16 v[4:7], v[204:207], v[196:199], v[4:7]
	v_mfma_f32_16x16x32_bf16 v[0:3], v[212:215], v[196:199], v[0:3]
	v_mfma_f32_16x16x32_bf16 v[48:51], v[208:211], v[176:179], v[48:51]
	v_mfma_f32_16x16x32_bf16 v[40:43], v[216:219], v[176:179], v[40:43]
	v_mfma_f32_16x16x32_bf16 v[32:35], v[208:211], v[184:187], v[32:35]
	v_mfma_f32_16x16x32_bf16 v[24:27], v[216:219], v[184:187], v[24:27]
	v_mfma_f32_16x16x32_bf16 v[16:19], v[208:211], v[192:195], v[16:19]
	v_mfma_f32_16x16x32_bf16 v[8:11], v[216:219], v[192:195], v[8:11]
	v_mfma_f32_16x16x32_bf16 v[4:7], v[208:211], v[200:203], v[4:7]
	v_mfma_f32_16x16x32_bf16 v[0:3], v[216:219], v[200:203], v[0:3]
	s_setprio 0
	s_add_i32 s46, 0, 0x18000
	v_add_u32_e32 v164, s46, v148
	s_barrier
	ds_read_b128 v[152:155], v164
	ds_read_b128 v[156:159], v164 offset:1024
	ds_read_b128 v[160:163], v164 offset:2048
	ds_read_b128 v[164:167], v164 offset:3072
	s_add_u32 s18, s22, 0xea000
	s_addc_u32 s19, s23, 0
	s_mov_b32 m0, s31
	v_lshl_add_u64 v[204:205], s[18:19], 0, v[134:135]
	ds_read_b128 v[172:175], v150 offset:32768
	ds_read_b128 v[176:179], v150 offset:33792
	ds_read_b128 v[180:183], v150 offset:34816
	ds_read_b128 v[184:187], v150 offset:35840
	ds_read_b128 v[188:191], v150 offset:36864
	ds_read_b128 v[192:195], v150 offset:37888
	ds_read_b128 v[196:199], v150 offset:38912
	ds_read_b128 v[200:203], v150 offset:39936
	global_load_lds_dwordx4 v[204:205], off
	v_lshl_add_u64 v[204:205], s[18:19], 0, v[130:131]
	s_mov_b32 m0, s33
	s_nop 0
	global_load_lds_dwordx4 v[204:205], off
	s_waitcnt lgkmcnt(8)
	s_waitcnt vmcnt(10)
	s_barrier
	s_waitcnt lgkmcnt(0)
	s_setprio 1
	s_waitcnt lgkmcnt(0)
	v_mfma_f32_16x16x32_bf16 v[124:127], v[152:155], v[172:175], v[124:127]
	v_mfma_f32_16x16x32_bf16 v[120:123], v[160:163], v[172:175], v[120:123]
	v_mfma_f32_16x16x32_bf16 v[116:119], v[152:155], v[180:183], v[116:119]
	v_mfma_f32_16x16x32_bf16 v[108:111], v[160:163], v[180:183], v[108:111]
	v_mfma_f32_16x16x32_bf16 v[100:103], v[152:155], v[188:191], v[100:103]
	v_mfma_f32_16x16x32_bf16 v[92:95], v[160:163], v[188:191], v[92:95]
	v_mfma_f32_16x16x32_bf16 v[84:87], v[152:155], v[196:199], v[84:87]
	v_mfma_f32_16x16x32_bf16 v[76:79], v[160:163], v[196:199], v[76:79]
	v_mfma_f32_16x16x32_bf16 v[124:127], v[156:159], v[176:179], v[124:127]
	v_mfma_f32_16x16x32_bf16 v[120:123], v[164:167], v[176:179], v[120:123]
	v_mfma_f32_16x16x32_bf16 v[116:119], v[156:159], v[184:187], v[116:119]
	v_mfma_f32_16x16x32_bf16 v[108:111], v[164:167], v[184:187], v[108:111]
	v_mfma_f32_16x16x32_bf16 v[100:103], v[156:159], v[192:195], v[100:103]
	v_mfma_f32_16x16x32_bf16 v[92:95], v[164:167], v[192:195], v[92:95]
	v_mfma_f32_16x16x32_bf16 v[84:87], v[156:159], v[200:203], v[84:87]
	v_mfma_f32_16x16x32_bf16 v[76:79], v[164:167], v[200:203], v[76:79]
	s_setprio 0
	s_barrier
	s_add_i32 s22, 0, 0x1c000
	s_add_i32 s18, s46, s28
	v_add_u32_e32 v171, s22, v148
	v_lshl_add_u64 v[168:169], v[168:169], 0, s[10:11]
	s_mov_b32 m0, s18
	ds_read_b128 v[204:207], v171
	ds_read_b128 v[208:211], v171 offset:1024
	ds_read_b128 v[212:215], v171 offset:2048
	ds_read_b128 v[216:219], v171 offset:3072
	global_load_lds_dwordx4 v[168:169], off
	v_lshl_add_u64 v[168:169], v[220:221], 0, s[10:11]
	s_add_i32 m0, s18, 0x2000
	s_nop 0
	global_load_lds_dwordx4 v[168:169], off
	s_waitcnt vmcnt(10)
	s_barrier
	s_waitcnt lgkmcnt(0)
	s_setprio 1
	s_waitcnt lgkmcnt(0)
	v_mfma_f32_16x16x32_bf16 v[112:115], v[204:207], v[172:175], v[112:115]
	v_mfma_f32_16x16x32_bf16 v[104:107], v[212:215], v[172:175], v[104:107]
	v_mfma_f32_16x16x32_bf16 v[96:99], v[204:207], v[180:183], v[96:99]
	v_mfma_f32_16x16x32_bf16 v[88:91], v[212:215], v[180:183], v[88:91]
	v_mfma_f32_16x16x32_bf16 v[80:83], v[204:207], v[188:191], v[80:83]
	v_mfma_f32_16x16x32_bf16 v[72:75], v[212:215], v[188:191], v[72:75]
	v_mfma_f32_16x16x32_bf16 v[68:71], v[204:207], v[196:199], v[68:71]
	v_mfma_f32_16x16x32_bf16 v[64:67], v[212:215], v[196:199], v[64:67]
	v_mfma_f32_16x16x32_bf16 v[112:115], v[208:211], v[176:179], v[112:115]
	v_mfma_f32_16x16x32_bf16 v[104:107], v[216:219], v[176:179], v[104:107]
	v_mfma_f32_16x16x32_bf16 v[96:99], v[208:211], v[184:187], v[96:99]
	v_mfma_f32_16x16x32_bf16 v[88:91], v[216:219], v[184:187], v[88:91]
	v_mfma_f32_16x16x32_bf16 v[80:83], v[208:211], v[192:195], v[80:83]
	v_mfma_f32_16x16x32_bf16 v[72:75], v[216:219], v[192:195], v[72:75]
	v_mfma_f32_16x16x32_bf16 v[68:71], v[208:211], v[200:203], v[68:71]
	v_mfma_f32_16x16x32_bf16 v[64:67], v[216:219], v[200:203], v[64:67]
	s_setprio 0
	s_mov_b32 m0, s34
	v_lshl_add_u64 v[168:169], v[222:223], 0, s[10:11]
	s_barrier
	ds_read_b128 v[172:175], v150 offset:49152
	ds_read_b128 v[176:179], v150 offset:50176
	ds_read_b128 v[180:183], v150 offset:51200
	ds_read_b128 v[184:187], v150 offset:52224
	ds_read_b128 v[188:191], v150 offset:53248
	ds_read_b128 v[192:195], v150 offset:54272
	ds_read_b128 v[196:199], v150 offset:55296
	ds_read_b128 v[200:203], v150 offset:56320
	global_load_lds_dwordx4 v[168:169], off
	v_lshl_add_u64 v[168:169], v[224:225], 0, s[10:11]
	s_mov_b32 m0, s35
	s_nop 0
	global_load_lds_dwordx4 v[168:169], off
	s_barrier
	s_waitcnt lgkmcnt(0)
	s_setprio 1
	s_waitcnt lgkmcnt(0)
	v_mfma_f32_16x16x32_bf16 v[60:63], v[152:155], v[172:175], v[60:63]
	v_mfma_f32_16x16x32_bf16 v[56:59], v[160:163], v[172:175], v[56:59]
	v_mfma_f32_16x16x32_bf16 v[52:55], v[152:155], v[180:183], v[52:55]
	v_mfma_f32_16x16x32_bf16 v[44:47], v[160:163], v[180:183], v[44:47]
	v_mfma_f32_16x16x32_bf16 v[36:39], v[152:155], v[188:191], v[36:39]
	v_mfma_f32_16x16x32_bf16 v[28:31], v[160:163], v[188:191], v[28:31]
	v_mfma_f32_16x16x32_bf16 v[20:23], v[152:155], v[196:199], v[20:23]
	v_mfma_f32_16x16x32_bf16 v[12:15], v[160:163], v[196:199], v[12:15]
	v_mfma_f32_16x16x32_bf16 v[60:63], v[156:159], v[176:179], v[60:63]
	v_mfma_f32_16x16x32_bf16 v[56:59], v[164:167], v[176:179], v[56:59]
	v_mfma_f32_16x16x32_bf16 v[52:55], v[156:159], v[184:187], v[52:55]
	v_mfma_f32_16x16x32_bf16 v[44:47], v[164:167], v[184:187], v[44:47]
	v_mfma_f32_16x16x32_bf16 v[36:39], v[156:159], v[192:195], v[36:39]
	v_mfma_f32_16x16x32_bf16 v[28:31], v[164:167], v[192:195], v[28:31]
	v_mfma_f32_16x16x32_bf16 v[20:23], v[156:159], v[200:203], v[20:23]
	v_mfma_f32_16x16x32_bf16 v[12:15], v[164:167], v[200:203], v[12:15]
	s_setprio 0
	s_barrier
	s_add_u32 s18, s20, 0x40080
	s_addc_u32 s19, s21, 0
	s_add_i32 s20, s22, s28
	v_lshl_add_u64 v[152:153], s[18:19], 0, v[132:133]
	s_mov_b32 m0, s20
	s_nop 0
	global_load_lds_dwordx4 v[152:153], off
	v_lshl_add_u64 v[152:153], s[18:19], 0, v[128:129]
	s_add_i32 m0, s20, 0x2000
	s_nop 0
	global_load_lds_dwordx4 v[152:153], off
	s_waitcnt vmcnt(10)
	s_barrier
	s_setprio 1
	v_mfma_f32_16x16x32_bf16 v[48:51], v[204:207], v[172:175], v[48:51]
	v_mfma_f32_16x16x32_bf16 v[40:43], v[212:215], v[172:175], v[40:43]
	v_mfma_f32_16x16x32_bf16 v[32:35], v[204:207], v[180:183], v[32:35]
	v_mfma_f32_16x16x32_bf16 v[24:27], v[212:215], v[180:183], v[24:27]
	v_mfma_f32_16x16x32_bf16 v[16:19], v[204:207], v[188:191], v[16:19]
	v_mfma_f32_16x16x32_bf16 v[8:11], v[212:215], v[188:191], v[8:11]
	v_mfma_f32_16x16x32_bf16 v[4:7], v[204:207], v[196:199], v[4:7]
	v_mfma_f32_16x16x32_bf16 v[0:3], v[212:215], v[196:199], v[0:3]
	v_mfma_f32_16x16x32_bf16 v[48:51], v[208:211], v[176:179], v[48:51]
	v_mfma_f32_16x16x32_bf16 v[40:43], v[216:219], v[176:179], v[40:43]
	v_mfma_f32_16x16x32_bf16 v[32:35], v[208:211], v[184:187], v[32:35]
	v_mfma_f32_16x16x32_bf16 v[24:27], v[216:219], v[184:187], v[24:27]
	v_mfma_f32_16x16x32_bf16 v[16:19], v[208:211], v[192:195], v[16:19]
	v_mfma_f32_16x16x32_bf16 v[8:11], v[216:219], v[192:195], v[8:11]
	v_mfma_f32_16x16x32_bf16 v[4:7], v[208:211], v[200:203], v[4:7]
	v_mfma_f32_16x16x32_bf16 v[0:3], v[216:219], v[200:203], v[0:3]
	s_setprio 0
	s_add_i32 s45, s45, 2
	s_add_u32 s43, s43, 0x100
	s_addc_u32 s44, s44, 0
	s_cmp_gt_u32 s45, 13
	s_mov_b64 s[18:19], s[4:5]
	s_barrier
	s_cbranch_scc0 .LBB0_1051
	v_lshl_add_u32 v152, s41, 8, v147
	s_lshl_b32 s4, s40, 8
	v_ashrrev_i32_e32 v153, 31, v152
	s_ashr_i32 s5, s4, 31
	v_lshlrev_b64 v[154:155], 11, v[152:153]
	v_lshl_add_u64 v[154:155], s[6:7], 0, v[154:155]
	s_lshl_b64 s[4:5], s[4:5], 1
	v_lshl_add_u64 v[154:155], v[154:155], 0, s[4:5]
	v_lshl_add_u64 v[154:155], v[154:155], 0, s[8:9]
	v_lshl_add_u64 v[154:155], v[154:155], 0, v[136:137]
	v_mbcnt_lo_u32_b32 v237, -1, 0
	v_mbcnt_hi_u32_b32 v237, -1, v237
	v_bfe_i32 v237, v237, 4, 1
	v_and_b32_e32 v244, 24, v237
	v_add_co_u32_e32 v248, vcc, v244, v154
	s_nop 1
	v_addc_co_u32_e32 v249, vcc, 0, v155, vcc
	v_cvt_pk_bf16_f32 v124, v124, v125
	v_cvt_pk_bf16_f32 v125, v126, v127
	v_cvt_pk_bf16_f32 v120, v120, v121
	v_cvt_pk_bf16_f32 v121, v122, v123
	v_bfi_b32 v244, v237, v124, v120
	v_bfi_b32 v245, v237, v125, v121
	ds_swizzle_b32 v250, v244 offset:0x401f
	ds_swizzle_b32 v251, v245 offset:0x401f
	v_cvt_pk_bf16_f32 v112, v112, v113
	v_cvt_pk_bf16_f32 v113, v114, v115
	v_cvt_pk_bf16_f32 v104, v104, v105
	v_cvt_pk_bf16_f32 v105, v106, v107
	v_bfi_b32 v246, v237, v112, v104
	v_bfi_b32 v247, v237, v113, v105
	ds_swizzle_b32 v252, v246 offset:0x401f
	ds_swizzle_b32 v253, v247 offset:0x401f
	s_waitcnt lgkmcnt(0)
	v_bfi_b32 v240, v237, v250, v124
	v_bfi_b32 v241, v237, v251, v125
	v_bfi_b32 v242, v237, v120, v250
	v_bfi_b32 v243, v237, v121, v251
	global_store_dwordx4 v[248:249], v[240:243], off
	s_nop 1
	v_bfi_b32 v240, v237, v252, v112
	v_bfi_b32 v241, v237, v253, v113
	v_bfi_b32 v242, v237, v104, v252
	v_bfi_b32 v243, v237, v105, v253
	global_store_dwordx4 v[248:249], v[240:243], off offset:256
	s_nop 1
	v_add_co_u32_e32 v238, vcc, 0x8000, v248
	s_nop 1
	v_addc_co_u32_e32 v239, vcc, 0, v249, vcc
	v_cvt_pk_bf16_f32 v116, v116, v117
	v_cvt_pk_bf16_f32 v117, v118, v119
	v_cvt_pk_bf16_f32 v108, v108, v109
	v_cvt_pk_bf16_f32 v109, v110, v111
	v_bfi_b32 v244, v237, v116, v108
	v_bfi_b32 v245, v237, v117, v109
	ds_swizzle_b32 v250, v244 offset:0x401f
	ds_swizzle_b32 v251, v245 offset:0x401f
	v_cvt_pk_bf16_f32 v96, v96, v97
	v_cvt_pk_bf16_f32 v97, v98, v99
	v_cvt_pk_bf16_f32 v88, v88, v89
	v_cvt_pk_bf16_f32 v89, v90, v91
	v_bfi_b32 v246, v237, v96, v88
	v_bfi_b32 v247, v237, v97, v89
	ds_swizzle_b32 v252, v246 offset:0x401f
	ds_swizzle_b32 v253, v247 offset:0x401f
	s_waitcnt lgkmcnt(0)
	v_bfi_b32 v240, v237, v250, v116
	v_bfi_b32 v241, v237, v251, v117
	v_bfi_b32 v242, v237, v108, v250
	v_bfi_b32 v243, v237, v109, v251
	global_store_dwordx4 v[238:239], v[240:243], off
	s_nop 1
	v_bfi_b32 v240, v237, v252, v96
	v_bfi_b32 v241, v237, v253, v97
	v_bfi_b32 v242, v237, v88, v252
	v_bfi_b32 v243, v237, v89, v253
	global_store_dwordx4 v[238:239], v[240:243], off offset:256
	s_nop 1
	v_add_co_u32_e32 v238, vcc, 0x10000, v248
	s_nop 1
	v_addc_co_u32_e32 v239, vcc, 0, v249, vcc
	v_cvt_pk_bf16_f32 v100, v100, v101
	v_cvt_pk_bf16_f32 v101, v102, v103
	v_cvt_pk_bf16_f32 v92, v92, v93
	v_cvt_pk_bf16_f32 v93, v94, v95
	v_bfi_b32 v244, v237, v100, v92
	v_bfi_b32 v245, v237, v101, v93
	ds_swizzle_b32 v250, v244 offset:0x401f
	ds_swizzle_b32 v251, v245 offset:0x401f
	v_cvt_pk_bf16_f32 v80, v80, v81
	v_cvt_pk_bf16_f32 v81, v82, v83
	v_cvt_pk_bf16_f32 v72, v72, v73
	v_cvt_pk_bf16_f32 v73, v74, v75
	v_bfi_b32 v246, v237, v80, v72
	v_bfi_b32 v247, v237, v81, v73
	ds_swizzle_b32 v252, v246 offset:0x401f
	ds_swizzle_b32 v253, v247 offset:0x401f
	s_waitcnt lgkmcnt(0)
	v_bfi_b32 v240, v237, v250, v100
	v_bfi_b32 v241, v237, v251, v101
	v_bfi_b32 v242, v237, v92, v250
	v_bfi_b32 v243, v237, v93, v251
	global_store_dwordx4 v[238:239], v[240:243], off
	s_nop 1
	v_bfi_b32 v240, v237, v252, v80
	v_bfi_b32 v241, v237, v253, v81
	v_bfi_b32 v242, v237, v72, v252
	v_bfi_b32 v243, v237, v73, v253
	global_store_dwordx4 v[238:239], v[240:243], off offset:256
	s_nop 1
	v_add_co_u32_e32 v238, vcc, 0x18000, v248
	s_nop 1
	v_addc_co_u32_e32 v239, vcc, 0, v249, vcc
	v_cvt_pk_bf16_f32 v84, v84, v85
	v_cvt_pk_bf16_f32 v85, v86, v87
	v_cvt_pk_bf16_f32 v76, v76, v77
	v_cvt_pk_bf16_f32 v77, v78, v79
	v_bfi_b32 v244, v237, v84, v76
	v_bfi_b32 v245, v237, v85, v77
	ds_swizzle_b32 v250, v244 offset:0x401f
	ds_swizzle_b32 v251, v245 offset:0x401f
	v_cvt_pk_bf16_f32 v68, v68, v69
	v_cvt_pk_bf16_f32 v69, v70, v71
	v_cvt_pk_bf16_f32 v64, v64, v65
	v_cvt_pk_bf16_f32 v65, v66, v67
	v_bfi_b32 v246, v237, v68, v64
	v_bfi_b32 v247, v237, v69, v65
	ds_swizzle_b32 v252, v246 offset:0x401f
	ds_swizzle_b32 v253, v247 offset:0x401f
	s_waitcnt lgkmcnt(0)
	v_bfi_b32 v240, v237, v250, v84
	v_bfi_b32 v241, v237, v251, v85
	v_bfi_b32 v242, v237, v76, v250
	v_bfi_b32 v243, v237, v77, v251
	global_store_dwordx4 v[238:239], v[240:243], off
	s_nop 1
	v_bfi_b32 v240, v237, v252, v68
	v_bfi_b32 v241, v237, v253, v69
	v_bfi_b32 v242, v237, v64, v252
	v_bfi_b32 v243, v237, v65, v253
	global_store_dwordx4 v[238:239], v[240:243], off offset:256
	s_nop 1
	v_add_co_u32_e32 v238, vcc, 0x40000, v248
	s_nop 1
	v_addc_co_u32_e32 v239, vcc, 0, v249, vcc
	v_cvt_pk_bf16_f32 v60, v60, v61
	v_cvt_pk_bf16_f32 v61, v62, v63
	v_cvt_pk_bf16_f32 v56, v56, v57
	v_cvt_pk_bf16_f32 v57, v58, v59
	v_bfi_b32 v244, v237, v60, v56
	v_bfi_b32 v245, v237, v61, v57
	ds_swizzle_b32 v250, v244 offset:0x401f
	ds_swizzle_b32 v251, v245 offset:0x401f
	v_cvt_pk_bf16_f32 v48, v48, v49
	v_cvt_pk_bf16_f32 v49, v50, v51
	v_cvt_pk_bf16_f32 v40, v40, v41
	v_cvt_pk_bf16_f32 v41, v42, v43
	v_bfi_b32 v246, v237, v48, v40
	v_bfi_b32 v247, v237, v49, v41
	ds_swizzle_b32 v252, v246 offset:0x401f
	ds_swizzle_b32 v253, v247 offset:0x401f
	s_waitcnt lgkmcnt(0)
	v_bfi_b32 v240, v237, v250, v60
	v_bfi_b32 v241, v237, v251, v61
	v_bfi_b32 v242, v237, v56, v250
	v_bfi_b32 v243, v237, v57, v251
	global_store_dwordx4 v[238:239], v[240:243], off
	s_nop 1
	v_bfi_b32 v240, v237, v252, v48
	v_bfi_b32 v241, v237, v253, v49
	v_bfi_b32 v242, v237, v40, v252
	v_bfi_b32 v243, v237, v41, v253
	global_store_dwordx4 v[238:239], v[240:243], off offset:256
	s_nop 1
	v_add_co_u32_e32 v238, vcc, 0x48000, v248
	s_nop 1
	v_addc_co_u32_e32 v239, vcc, 0, v249, vcc
	v_cvt_pk_bf16_f32 v52, v52, v53
	v_cvt_pk_bf16_f32 v53, v54, v55
	v_cvt_pk_bf16_f32 v44, v44, v45
	v_cvt_pk_bf16_f32 v45, v46, v47
	v_bfi_b32 v244, v237, v52, v44
	v_bfi_b32 v245, v237, v53, v45
	ds_swizzle_b32 v250, v244 offset:0x401f
	ds_swizzle_b32 v251, v245 offset:0x401f
	v_cvt_pk_bf16_f32 v32, v32, v33
	v_cvt_pk_bf16_f32 v33, v34, v35
	v_cvt_pk_bf16_f32 v24, v24, v25
	v_cvt_pk_bf16_f32 v25, v26, v27
	v_bfi_b32 v246, v237, v32, v24
	v_bfi_b32 v247, v237, v33, v25
	ds_swizzle_b32 v252, v246 offset:0x401f
	ds_swizzle_b32 v253, v247 offset:0x401f
	s_waitcnt lgkmcnt(0)
	v_bfi_b32 v240, v237, v250, v52
	v_bfi_b32 v241, v237, v251, v53
	v_bfi_b32 v242, v237, v44, v250
	v_bfi_b32 v243, v237, v45, v251
	global_store_dwordx4 v[238:239], v[240:243], off
	s_nop 1
	v_bfi_b32 v240, v237, v252, v32
	v_bfi_b32 v241, v237, v253, v33
	v_bfi_b32 v242, v237, v24, v252
	v_bfi_b32 v243, v237, v25, v253
	global_store_dwordx4 v[238:239], v[240:243], off offset:256
	s_nop 1
	v_add_co_u32_e32 v238, vcc, 0x50000, v248
	s_nop 1
	v_addc_co_u32_e32 v239, vcc, 0, v249, vcc
	v_cvt_pk_bf16_f32 v36, v36, v37
	v_cvt_pk_bf16_f32 v37, v38, v39
	v_cvt_pk_bf16_f32 v28, v28, v29
	v_cvt_pk_bf16_f32 v29, v30, v31
	v_bfi_b32 v244, v237, v36, v28
	v_bfi_b32 v245, v237, v37, v29
	ds_swizzle_b32 v250, v244 offset:0x401f
	ds_swizzle_b32 v251, v245 offset:0x401f
	v_cvt_pk_bf16_f32 v16, v16, v17
	v_cvt_pk_bf16_f32 v17, v18, v19
	v_cvt_pk_bf16_f32 v8, v8, v9
	v_cvt_pk_bf16_f32 v9, v10, v11
	v_bfi_b32 v246, v237, v16, v8
	v_bfi_b32 v247, v237, v17, v9
	ds_swizzle_b32 v252, v246 offset:0x401f
	ds_swizzle_b32 v253, v247 offset:0x401f
	s_waitcnt lgkmcnt(0)
	v_bfi_b32 v240, v237, v250, v36
	v_bfi_b32 v241, v237, v251, v37
	v_bfi_b32 v242, v237, v28, v250
	v_bfi_b32 v243, v237, v29, v251
	global_store_dwordx4 v[238:239], v[240:243], off
	s_nop 1
	v_bfi_b32 v240, v237, v252, v16
	v_bfi_b32 v241, v237, v253, v17
	v_bfi_b32 v242, v237, v8, v252
	v_bfi_b32 v243, v237, v9, v253
	global_store_dwordx4 v[238:239], v[240:243], off offset:256
	s_nop 1
	v_add_co_u32_e32 v238, vcc, 0x58000, v248
	s_nop 1
	v_addc_co_u32_e32 v239, vcc, 0, v249, vcc
	v_cvt_pk_bf16_f32 v20, v20, v21
	v_cvt_pk_bf16_f32 v21, v22, v23
	v_cvt_pk_bf16_f32 v12, v12, v13
	v_cvt_pk_bf16_f32 v13, v14, v15
	v_bfi_b32 v244, v237, v20, v12
	v_bfi_b32 v245, v237, v21, v13
	ds_swizzle_b32 v250, v244 offset:0x401f
	ds_swizzle_b32 v251, v245 offset:0x401f
	v_cvt_pk_bf16_f32 v4, v4, v5
	v_cvt_pk_bf16_f32 v5, v6, v7
	v_cvt_pk_bf16_f32 v0, v0, v1
	v_cvt_pk_bf16_f32 v1, v2, v3
	v_bfi_b32 v246, v237, v4, v0
	v_bfi_b32 v247, v237, v5, v1
	ds_swizzle_b32 v252, v246 offset:0x401f
	ds_swizzle_b32 v253, v247 offset:0x401f
	s_waitcnt lgkmcnt(0)
	v_bfi_b32 v240, v237, v250, v20
	v_bfi_b32 v241, v237, v251, v21
	v_bfi_b32 v242, v237, v12, v250
	v_bfi_b32 v243, v237, v13, v251
	global_store_dwordx4 v[238:239], v[240:243], off
	s_nop 1
	v_bfi_b32 v240, v237, v252, v4
	v_bfi_b32 v241, v237, v253, v5
	v_bfi_b32 v242, v237, v0, v252
	v_bfi_b32 v243, v237, v1, v253
	global_store_dwordx4 v[238:239], v[240:243], off offset:256
	s_nop 1
	s_and_b64 vcc, exec, s[0:1]
	s_mov_b32 s40, s12
	s_mov_b32 s41, s39
	s_mov_b64 s[20:21], s[16:17]
	s_mov_b64 s[18:19], s[14:15]
	s_cbranch_vccz .LBB0_1046
	s_waitcnt vmcnt(0)
	s_cmpk_gt_u32 s3, 0xff
	s_cbranch_scc1 .LBB0_1055
	s_barrier

.LBB0_1188:
	ds_read_b128 v[146:149], v143
	ds_read_b128 v[150:153], v143 offset:1024
	ds_read_b128 v[154:157], v143 offset:2048
	ds_read_b128 v[158:161], v143 offset:3072
	s_add_u32 s10, s8, 0xfffc0080
	s_addc_u32 s11, s9, -1
	s_cmp_eq_u32 s34, 12
	s_cselect_b32 s13, s1, s11
	s_cselect_b32 s12, s23, s10
	s_cselect_b32 s11, s21, s31
	s_cselect_b32 s10, s29, s30
	v_lshl_add_u64 v[196:197], s[8:9], 0, v[134:135]
	s_add_i32 m0, s40, 0xc000
	ds_read_b128 v[162:165], v144
	ds_read_b128 v[166:169], v144 offset:1024
	ds_read_b128 v[172:175], v144 offset:2048
	ds_read_b128 v[176:179], v144 offset:3072
	ds_read_b128 v[180:183], v144 offset:4096
	ds_read_b128 v[184:187], v144 offset:5120
	ds_read_b128 v[188:191], v144 offset:6144
	ds_read_b128 v[192:195], v144 offset:7168
	global_load_lds_dwordx4 v[196:197], off
	v_lshl_add_u64 v[196:197], s[8:9], 0, v[132:133]
	s_add_i32 m0, s40, 0xe000
	s_nop 0
	global_load_lds_dwordx4 v[196:197], off
	s_waitcnt lgkmcnt(8)
	s_waitcnt vmcnt(10)
	s_barrier
	s_waitcnt lgkmcnt(0)
	s_setprio 1
	s_waitcnt lgkmcnt(0)
	v_mfma_f32_16x16x32_bf16 v[124:127], v[146:149], v[162:165], v[124:127]
	v_mfma_f32_16x16x32_bf16 v[108:111], v[154:157], v[162:165], v[108:111]
	v_mfma_f32_16x16x32_bf16 v[120:123], v[146:149], v[172:175], v[120:123]
	v_mfma_f32_16x16x32_bf16 v[96:99], v[154:157], v[172:175], v[96:99]
	v_mfma_f32_16x16x32_bf16 v[116:119], v[146:149], v[180:183], v[116:119]
	v_mfma_f32_16x16x32_bf16 v[88:91], v[154:157], v[180:183], v[88:91]
	v_mfma_f32_16x16x32_bf16 v[104:107], v[146:149], v[188:191], v[104:107]
	v_mfma_f32_16x16x32_bf16 v[76:79], v[154:157], v[188:191], v[76:79]
	v_mfma_f32_16x16x32_bf16 v[124:127], v[150:153], v[166:169], v[124:127]
	v_mfma_f32_16x16x32_bf16 v[108:111], v[158:161], v[166:169], v[108:111]
	v_mfma_f32_16x16x32_bf16 v[120:123], v[150:153], v[176:179], v[120:123]
	v_mfma_f32_16x16x32_bf16 v[96:99], v[158:161], v[176:179], v[96:99]
	v_mfma_f32_16x16x32_bf16 v[116:119], v[150:153], v[184:187], v[116:119]
	v_mfma_f32_16x16x32_bf16 v[88:91], v[158:161], v[184:187], v[88:91]
	v_mfma_f32_16x16x32_bf16 v[104:107], v[150:153], v[192:195], v[104:107]
	v_mfma_f32_16x16x32_bf16 v[76:79], v[158:161], v[192:195], v[76:79]
	s_setprio 0
	s_barrier
	s_add_i32 s35, s48, s39
	v_lshl_add_u64 v[212:213], s[10:11], 0, v[128:129]
	s_mov_b32 m0, s35
	ds_read_b128 v[196:199], v145
	ds_read_b128 v[200:203], v145 offset:1024
	ds_read_b128 v[204:207], v145 offset:2048
	ds_read_b128 v[208:211], v145 offset:3072
	global_load_lds_dwordx4 v[212:213], off
	v_lshl_add_u64 v[214:215], s[10:11], 0, v[130:131]
	s_add_i32 m0, s35, 0x2000
	s_nop 0
	global_load_lds_dwordx4 v[214:215], off
	s_waitcnt vmcnt(10)
	s_barrier
	s_waitcnt lgkmcnt(0)
	s_setprio 1
	s_waitcnt lgkmcnt(0)
	v_mfma_f32_16x16x32_bf16 v[112:115], v[196:199], v[162:165], v[112:115]
	v_mfma_f32_16x16x32_bf16 v[84:87], v[204:207], v[162:165], v[84:87]
	v_mfma_f32_16x16x32_bf16 v[100:103], v[196:199], v[172:175], v[100:103]
	v_mfma_f32_16x16x32_bf16 v[68:71], v[204:207], v[172:175], v[68:71]
	v_mfma_f32_16x16x32_bf16 v[92:95], v[196:199], v[180:183], v[92:95]
	v_mfma_f32_16x16x32_bf16 v[60:63], v[204:207], v[180:183], v[60:63]
	v_mfma_f32_16x16x32_bf16 v[80:83], v[196:199], v[188:191], v[80:83]
	v_mfma_f32_16x16x32_bf16 v[52:55], v[204:207], v[188:191], v[52:55]
	v_mfma_f32_16x16x32_bf16 v[112:115], v[200:203], v[166:169], v[112:115]
	v_mfma_f32_16x16x32_bf16 v[84:87], v[208:211], v[166:169], v[84:87]
	v_mfma_f32_16x16x32_bf16 v[100:103], v[200:203], v[176:179], v[100:103]
	v_mfma_f32_16x16x32_bf16 v[68:71], v[208:211], v[176:179], v[68:71]
	v_mfma_f32_16x16x32_bf16 v[92:95], v[200:203], v[184:187], v[92:95]
	v_mfma_f32_16x16x32_bf16 v[60:63], v[208:211], v[184:187], v[60:63]
	v_mfma_f32_16x16x32_bf16 v[80:83], v[200:203], v[192:195], v[80:83]
	v_mfma_f32_16x16x32_bf16 v[52:55], v[208:211], v[192:195], v[52:55]
	s_setprio 0
	s_mov_b32 m0, s40
	v_lshl_add_u64 v[216:217], s[12:13], 0, v[128:129]
	s_barrier
	ds_read_b128 v[162:165], v144 offset:16384
	ds_read_b128 v[166:169], v144 offset:17408
	ds_read_b128 v[172:175], v144 offset:18432
	ds_read_b128 v[176:179], v144 offset:19456
	ds_read_b128 v[180:183], v144 offset:20480
	ds_read_b128 v[184:187], v144 offset:21504
	ds_read_b128 v[188:191], v144 offset:22528
	ds_read_b128 v[192:195], v144 offset:23552
	global_load_lds_dwordx4 v[216:217], off
	v_lshl_add_u64 v[218:219], s[12:13], 0, v[130:131]
	s_mov_b32 m0, s41
	s_nop 0
	global_load_lds_dwordx4 v[218:219], off
	s_barrier
	s_waitcnt lgkmcnt(0)
	s_setprio 1
	s_waitcnt lgkmcnt(0)
	v_mfma_f32_16x16x32_bf16 v[72:75], v[146:149], v[162:165], v[72:75]
	v_mfma_f32_16x16x32_bf16 v[44:47], v[154:157], v[162:165], v[44:47]
	v_mfma_f32_16x16x32_bf16 v[64:67], v[146:149], v[172:175], v[64:67]
	v_mfma_f32_16x16x32_bf16 v[32:35], v[154:157], v[172:175], v[32:35]
	v_mfma_f32_16x16x32_bf16 v[56:59], v[146:149], v[180:183], v[56:59]
	v_mfma_f32_16x16x32_bf16 v[24:27], v[154:157], v[180:183], v[24:27]
	v_mfma_f32_16x16x32_bf16 v[40:43], v[146:149], v[188:191], v[40:43]
	v_mfma_f32_16x16x32_bf16 v[12:15], v[154:157], v[188:191], v[12:15]
	v_mfma_f32_16x16x32_bf16 v[72:75], v[150:153], v[166:169], v[72:75]
	v_mfma_f32_16x16x32_bf16 v[44:47], v[158:161], v[166:169], v[44:47]
	v_mfma_f32_16x16x32_bf16 v[64:67], v[150:153], v[176:179], v[64:67]
	v_mfma_f32_16x16x32_bf16 v[32:35], v[158:161], v[176:179], v[32:35]
	v_mfma_f32_16x16x32_bf16 v[56:59], v[150:153], v[184:187], v[56:59]
	v_mfma_f32_16x16x32_bf16 v[24:27], v[158:161], v[184:187], v[24:27]
	v_mfma_f32_16x16x32_bf16 v[40:43], v[150:153], v[192:195], v[40:43]
	v_mfma_f32_16x16x32_bf16 v[12:15], v[158:161], v[192:195], v[12:15]
	s_setprio 0
	s_barrier
	s_add_u32 s52, s10, 0x40000
	s_addc_u32 s53, s11, 0
	s_add_i32 s35, s49, s39
	v_lshl_add_u64 v[146:147], s[52:53], 0, v[128:129]
	s_mov_b32 m0, s35
	s_nop 0
	global_load_lds_dwordx4 v[146:147], off
	v_lshl_add_u64 v[146:147], s[52:53], 0, v[130:131]
	s_add_i32 m0, s35, 0x2000
	s_nop 0
	global_load_lds_dwordx4 v[146:147], off
	s_waitcnt vmcnt(10)
	s_barrier
	s_setprio 1
	v_mfma_f32_16x16x32_bf16 v[48:51], v[196:199], v[162:165], v[48:51]
	v_mfma_f32_16x16x32_bf16 v[20:23], v[204:207], v[162:165], v[20:23]
	v_mfma_f32_16x16x32_bf16 v[36:39], v[196:199], v[172:175], v[36:39]
	v_mfma_f32_16x16x32_bf16 v[8:11], v[204:207], v[172:175], v[8:11]
	v_mfma_f32_16x16x32_bf16 v[28:31], v[196:199], v[180:183], v[28:31]
	v_mfma_f32_16x16x32_bf16 v[4:7], v[204:207], v[180:183], v[4:7]
	v_mfma_f32_16x16x32_bf16 v[16:19], v[196:199], v[188:191], v[16:19]
	v_mfma_f32_16x16x32_bf16 v[0:3], v[204:207], v[188:191], v[0:3]
	v_mfma_f32_16x16x32_bf16 v[48:51], v[200:203], v[166:169], v[48:51]
	v_mfma_f32_16x16x32_bf16 v[20:23], v[208:211], v[166:169], v[20:23]
	v_mfma_f32_16x16x32_bf16 v[36:39], v[200:203], v[176:179], v[36:39]
	v_mfma_f32_16x16x32_bf16 v[8:11], v[208:211], v[176:179], v[8:11]
	v_mfma_f32_16x16x32_bf16 v[28:31], v[200:203], v[184:187], v[28:31]
	v_mfma_f32_16x16x32_bf16 v[4:7], v[208:211], v[184:187], v[4:7]
	v_mfma_f32_16x16x32_bf16 v[16:19], v[200:203], v[192:195], v[16:19]
	v_mfma_f32_16x16x32_bf16 v[0:3], v[208:211], v[192:195], v[0:3]
	s_setprio 0
	s_add_i32 s35, 0, 0x18000
	v_add_u32_e32 v158, s35, v141
	s_barrier
	ds_read_b128 v[146:149], v158
	ds_read_b128 v[150:153], v158 offset:1024
	ds_read_b128 v[154:157], v158 offset:2048
	ds_read_b128 v[158:161], v158 offset:3072
	s_add_u32 s12, s12, 0x40000
	s_addc_u32 s13, s13, 0
	s_mov_b32 m0, s42
	v_lshl_add_u64 v[196:197], s[12:13], 0, v[128:129]
	ds_read_b128 v[162:165], v144 offset:32768
	ds_read_b128 v[166:169], v144 offset:33792
	ds_read_b128 v[172:175], v144 offset:34816
	ds_read_b128 v[176:179], v144 offset:35840
	ds_read_b128 v[180:183], v144 offset:36864
	ds_read_b128 v[184:187], v144 offset:37888
	ds_read_b128 v[188:191], v144 offset:38912
	ds_read_b128 v[192:195], v144 offset:39936
	global_load_lds_dwordx4 v[196:197], off
	v_lshl_add_u64 v[196:197], s[12:13], 0, v[130:131]
	s_mov_b32 m0, s43
	s_nop 0
	global_load_lds_dwordx4 v[196:197], off
	s_waitcnt lgkmcnt(8)
	s_waitcnt vmcnt(10)
	s_barrier
	s_waitcnt lgkmcnt(0)
	s_setprio 1
	s_waitcnt lgkmcnt(0)
	v_mfma_f32_16x16x32_bf16 v[124:127], v[146:149], v[162:165], v[124:127]
	v_mfma_f32_16x16x32_bf16 v[108:111], v[154:157], v[162:165], v[108:111]
	v_mfma_f32_16x16x32_bf16 v[120:123], v[146:149], v[172:175], v[120:123]
	v_mfma_f32_16x16x32_bf16 v[96:99], v[154:157], v[172:175], v[96:99]
	v_mfma_f32_16x16x32_bf16 v[116:119], v[146:149], v[180:183], v[116:119]
	v_mfma_f32_16x16x32_bf16 v[88:91], v[154:157], v[180:183], v[88:91]
	v_mfma_f32_16x16x32_bf16 v[104:107], v[146:149], v[188:191], v[104:107]
	v_mfma_f32_16x16x32_bf16 v[76:79], v[154:157], v[188:191], v[76:79]
	v_mfma_f32_16x16x32_bf16 v[124:127], v[150:153], v[166:169], v[124:127]
	v_mfma_f32_16x16x32_bf16 v[108:111], v[158:161], v[166:169], v[108:111]
	v_mfma_f32_16x16x32_bf16 v[120:123], v[150:153], v[176:179], v[120:123]
	v_mfma_f32_16x16x32_bf16 v[96:99], v[158:161], v[176:179], v[96:99]
	v_mfma_f32_16x16x32_bf16 v[116:119], v[150:153], v[184:187], v[116:119]
	v_mfma_f32_16x16x32_bf16 v[88:91], v[158:161], v[184:187], v[88:91]
	v_mfma_f32_16x16x32_bf16 v[104:107], v[150:153], v[192:195], v[104:107]
	v_mfma_f32_16x16x32_bf16 v[76:79], v[158:161], v[192:195], v[76:79]
	s_setprio 0
	s_barrier
	s_add_i32 s12, 0, 0x1c000
	s_add_i32 s13, s35, s39
	v_add_u32_e32 v171, s12, v141
	v_lshl_add_u64 v[212:213], v[212:213], 0, s[16:17]
	s_mov_b32 m0, s13
	ds_read_b128 v[196:199], v171
	ds_read_b128 v[200:203], v171 offset:1024
	ds_read_b128 v[204:207], v171 offset:2048
	ds_read_b128 v[208:211], v171 offset:3072
	global_load_lds_dwordx4 v[212:213], off
	v_lshl_add_u64 v[212:213], v[214:215], 0, s[16:17]
	s_add_i32 m0, s13, 0x2000
	s_nop 0
	global_load_lds_dwordx4 v[212:213], off
	s_waitcnt vmcnt(10)
	s_barrier
	s_waitcnt lgkmcnt(0)
	s_setprio 1
	s_waitcnt lgkmcnt(0)
	v_mfma_f32_16x16x32_bf16 v[112:115], v[196:199], v[162:165], v[112:115]
	v_mfma_f32_16x16x32_bf16 v[84:87], v[204:207], v[162:165], v[84:87]
	v_mfma_f32_16x16x32_bf16 v[100:103], v[196:199], v[172:175], v[100:103]
	v_mfma_f32_16x16x32_bf16 v[68:71], v[204:207], v[172:175], v[68:71]
	v_mfma_f32_16x16x32_bf16 v[92:95], v[196:199], v[180:183], v[92:95]
	v_mfma_f32_16x16x32_bf16 v[60:63], v[204:207], v[180:183], v[60:63]
	v_mfma_f32_16x16x32_bf16 v[80:83], v[196:199], v[188:191], v[80:83]
	v_mfma_f32_16x16x32_bf16 v[52:55], v[204:207], v[188:191], v[52:55]
	v_mfma_f32_16x16x32_bf16 v[112:115], v[200:203], v[166:169], v[112:115]
	v_mfma_f32_16x16x32_bf16 v[84:87], v[208:211], v[166:169], v[84:87]
	v_mfma_f32_16x16x32_bf16 v[100:103], v[200:203], v[176:179], v[100:103]
	v_mfma_f32_16x16x32_bf16 v[68:71], v[208:211], v[176:179], v[68:71]
	v_mfma_f32_16x16x32_bf16 v[92:95], v[200:203], v[184:187], v[92:95]
	v_mfma_f32_16x16x32_bf16 v[60:63], v[208:211], v[184:187], v[60:63]
	v_mfma_f32_16x16x32_bf16 v[80:83], v[200:203], v[192:195], v[80:83]
	v_mfma_f32_16x16x32_bf16 v[52:55], v[208:211], v[192:195], v[52:55]
	s_setprio 0
	s_mov_b32 m0, s45
	v_lshl_add_u64 v[212:213], v[216:217], 0, s[16:17]
	s_barrier
	ds_read_b128 v[162:165], v144 offset:49152
	ds_read_b128 v[166:169], v144 offset:50176
	ds_read_b128 v[172:175], v144 offset:51200
	ds_read_b128 v[176:179], v144 offset:52224
	ds_read_b128 v[180:183], v144 offset:53248
	ds_read_b128 v[184:187], v144 offset:54272
	ds_read_b128 v[188:191], v144 offset:55296
	ds_read_b128 v[192:195], v144 offset:56320
	global_load_lds_dwordx4 v[212:213], off
	v_lshl_add_u64 v[212:213], v[218:219], 0, s[16:17]
	s_mov_b32 m0, s46
	s_nop 0
	global_load_lds_dwordx4 v[212:213], off
	s_barrier
	s_waitcnt lgkmcnt(0)
	s_setprio 1
	s_waitcnt lgkmcnt(0)
	v_mfma_f32_16x16x32_bf16 v[72:75], v[146:149], v[162:165], v[72:75]
	v_mfma_f32_16x16x32_bf16 v[44:47], v[154:157], v[162:165], v[44:47]
	v_mfma_f32_16x16x32_bf16 v[64:67], v[146:149], v[172:175], v[64:67]
	v_mfma_f32_16x16x32_bf16 v[32:35], v[154:157], v[172:175], v[32:35]
	v_mfma_f32_16x16x32_bf16 v[56:59], v[146:149], v[180:183], v[56:59]
	v_mfma_f32_16x16x32_bf16 v[24:27], v[154:157], v[180:183], v[24:27]
	v_mfma_f32_16x16x32_bf16 v[40:43], v[146:149], v[188:191], v[40:43]
	v_mfma_f32_16x16x32_bf16 v[12:15], v[154:157], v[188:191], v[12:15]
	v_mfma_f32_16x16x32_bf16 v[72:75], v[150:153], v[166:169], v[72:75]
	v_mfma_f32_16x16x32_bf16 v[44:47], v[158:161], v[166:169], v[44:47]
	v_mfma_f32_16x16x32_bf16 v[64:67], v[150:153], v[176:179], v[64:67]
	v_mfma_f32_16x16x32_bf16 v[32:35], v[158:161], v[176:179], v[32:35]
	v_mfma_f32_16x16x32_bf16 v[56:59], v[150:153], v[184:187], v[56:59]
	v_mfma_f32_16x16x32_bf16 v[24:27], v[158:161], v[184:187], v[24:27]
	v_mfma_f32_16x16x32_bf16 v[40:43], v[150:153], v[192:195], v[40:43]
	v_mfma_f32_16x16x32_bf16 v[12:15], v[158:161], v[192:195], v[12:15]
	s_setprio 0
	s_barrier
	s_add_u32 s10, s10, 0x40080
	s_addc_u32 s11, s11, 0
	s_add_i32 s12, s12, s39
	v_lshl_add_u64 v[146:147], s[10:11], 0, v[128:129]
	s_mov_b32 m0, s12
	s_nop 0
	global_load_lds_dwordx4 v[146:147], off
	v_lshl_add_u64 v[146:147], s[10:11], 0, v[130:131]
	s_add_i32 m0, s12, 0x2000
	s_nop 0
	global_load_lds_dwordx4 v[146:147], off
	s_waitcnt vmcnt(10)
	s_barrier
	s_setprio 1
	v_mfma_f32_16x16x32_bf16 v[48:51], v[196:199], v[162:165], v[48:51]
	v_mfma_f32_16x16x32_bf16 v[20:23], v[204:207], v[162:165], v[20:23]
	v_mfma_f32_16x16x32_bf16 v[36:39], v[196:199], v[172:175], v[36:39]
	v_mfma_f32_16x16x32_bf16 v[8:11], v[204:207], v[172:175], v[8:11]
	v_mfma_f32_16x16x32_bf16 v[28:31], v[196:199], v[180:183], v[28:31]
	v_mfma_f32_16x16x32_bf16 v[4:7], v[204:207], v[180:183], v[4:7]
	v_mfma_f32_16x16x32_bf16 v[16:19], v[196:199], v[188:191], v[16:19]
	v_mfma_f32_16x16x32_bf16 v[0:3], v[204:207], v[188:191], v[0:3]
	v_mfma_f32_16x16x32_bf16 v[48:51], v[200:203], v[166:169], v[48:51]
	v_mfma_f32_16x16x32_bf16 v[20:23], v[208:211], v[166:169], v[20:23]
	v_mfma_f32_16x16x32_bf16 v[36:39], v[200:203], v[176:179], v[36:39]
	v_mfma_f32_16x16x32_bf16 v[8:11], v[208:211], v[176:179], v[8:11]
	v_mfma_f32_16x16x32_bf16 v[28:31], v[200:203], v[184:187], v[28:31]
	v_mfma_f32_16x16x32_bf16 v[4:7], v[208:211], v[184:187], v[4:7]
	v_mfma_f32_16x16x32_bf16 v[16:19], v[200:203], v[192:195], v[16:19]
	v_mfma_f32_16x16x32_bf16 v[0:3], v[208:211], v[192:195], v[0:3]
	s_setprio 0
	s_add_i32 s34, s34, 2
	s_add_u32 s30, s30, 0x100
	s_addc_u32 s31, s31, 0
	s_add_u32 s8, s8, 0x100
	s_addc_u32 s9, s9, 0
	s_cmp_gt_u32 s34, 13
	s_barrier
	s_cbranch_scc0 .LBB0_1188
	v_mbcnt_lo_u32_b32 v146, -1, 0
	v_mbcnt_hi_u32_b32 v146, -1, v146
	s_mul_i32 s98, s0, 0xfe
	s_mulk_i32 s0, 0xfe
	v_or_b32_e32 v146, s3, v146
	v_mov_b32_e32 v150, 0
	v_ashrrev_i32_e32 v147, 1, v146
	v_add_u32_e32 v149, -1, v147
	v_add_u32_e32 v148, s0, v149
	s_movk_i32 s0, 0xfe
	v_cmp_gt_u32_e32 vcc, s0, v149
	s_mov_b32 s0, 0x14000
	v_cmp_gt_i32_e64 s[0:1], s0, v148
	s_and_b64 s[0:1], vcc, s[0:1]
	v_mov_b32_e32 v151, 0xfff
	s_and_saveexec_b64 s[8:9], s[0:1]
	s_cbranch_execz .LBB0_1195
	s_movk_i32 s10, 0x3fff
	v_cmp_lt_i32_e32 vcc, s10, v148
	s_and_saveexec_b64 s[10:11], vcc
	s_xor_b64 s[10:11], exec, s[10:11]
	v_and_b32_e32 v150, 0x7ff, v148
	s_or_saveexec_b64 s[10:11], s[10:11]
	v_mov_b32_e32 v151, 0x7ff
	s_xor_b64 exec, exec, s[10:11]
	v_mov_b32_e32 v151, 0xfff
	v_and_b32_e32 v150, 0xfff, v148
	s_or_b64 exec, exec, s[10:11]

.LBB0_1284:
	ds_read_b128 v[148:151], v145
	ds_read_b128 v[152:155], v145 offset:1024
	ds_read_b128 v[156:159], v145 offset:2048
	ds_read_b128 v[160:163], v145 offset:3072
	s_add_u32 s14, s12, 0x100
	s_addc_u32 s15, s13, 0
	s_cmp_eq_u32 s44, 40
	s_cselect_b32 s19, s9, s15
	s_cselect_b32 s18, s8, s14
	s_cselect_b32 s17, s1, s43
	s_cselect_b32 s16, s0, s42
	s_mov_b32 m0, s35
	v_lshl_add_u64 v[168:169], s[12:13], 0, v[136:137]
	ds_read_b128 v[164:167], v146
	ds_read_b128 v[172:175], v146 offset:1024
	ds_read_b128 v[176:179], v146 offset:2048
	ds_read_b128 v[180:183], v146 offset:3072
	ds_read_b128 v[184:187], v146 offset:4096
	ds_read_b128 v[188:191], v146 offset:5120
	ds_read_b128 v[192:195], v146 offset:6144
	ds_read_b128 v[196:199], v146 offset:7168
	global_load_lds_dwordx4 v[168:169], off
	v_lshl_add_u64 v[168:169], s[12:13], 0, v[134:135]
	s_mov_b32 m0, s36
	s_nop 0
	global_load_lds_dwordx4 v[168:169], off
	s_waitcnt lgkmcnt(8)
	s_waitcnt vmcnt(10)
	s_barrier
	s_waitcnt lgkmcnt(0)
	s_setprio 1
	s_waitcnt lgkmcnt(0)
	v_mfma_f32_16x16x32_bf16 v[124:127], v[148:151], v[164:167], v[124:127]
	v_mfma_f32_16x16x32_bf16 v[120:123], v[156:159], v[164:167], v[120:123]
	v_mfma_f32_16x16x32_bf16 v[116:119], v[148:151], v[176:179], v[116:119]
	v_mfma_f32_16x16x32_bf16 v[108:111], v[156:159], v[176:179], v[108:111]
	v_mfma_f32_16x16x32_bf16 v[100:103], v[148:151], v[184:187], v[100:103]
	v_mfma_f32_16x16x32_bf16 v[92:95], v[156:159], v[184:187], v[92:95]
	v_mfma_f32_16x16x32_bf16 v[84:87], v[148:151], v[192:195], v[84:87]
	v_mfma_f32_16x16x32_bf16 v[76:79], v[156:159], v[192:195], v[76:79]
	v_mfma_f32_16x16x32_bf16 v[124:127], v[152:155], v[172:175], v[124:127]
	v_mfma_f32_16x16x32_bf16 v[120:123], v[160:163], v[172:175], v[120:123]
	v_mfma_f32_16x16x32_bf16 v[116:119], v[152:155], v[180:183], v[116:119]
	v_mfma_f32_16x16x32_bf16 v[108:111], v[160:163], v[180:183], v[108:111]
	v_mfma_f32_16x16x32_bf16 v[100:103], v[152:155], v[188:191], v[100:103]
	v_mfma_f32_16x16x32_bf16 v[92:95], v[160:163], v[188:191], v[92:95]
	v_mfma_f32_16x16x32_bf16 v[84:87], v[152:155], v[196:199], v[84:87]
	v_mfma_f32_16x16x32_bf16 v[76:79], v[160:163], v[196:199], v[76:79]
	s_setprio 0
	s_barrier
	s_add_i32 s12, s33, s25
	v_lshl_add_u64 v[168:169], s[16:17], 0, v[130:131]
	s_mov_b32 m0, s12
	ds_read_b128 v[200:203], v147
	ds_read_b128 v[204:207], v147 offset:1024
	ds_read_b128 v[208:211], v147 offset:2048
	ds_read_b128 v[212:215], v147 offset:3072
	global_load_lds_dwordx4 v[168:169], off
	v_lshl_add_u64 v[216:217], s[16:17], 0, v[128:129]
	s_add_i32 m0, s12, 0x2000
	s_nop 0
	global_load_lds_dwordx4 v[216:217], off
	s_waitcnt vmcnt(10)
	s_barrier
	s_waitcnt lgkmcnt(0)
	s_setprio 1
	s_waitcnt lgkmcnt(0)
	v_mfma_f32_16x16x32_bf16 v[112:115], v[200:203], v[164:167], v[112:115]
	v_mfma_f32_16x16x32_bf16 v[104:107], v[208:211], v[164:167], v[104:107]
	v_mfma_f32_16x16x32_bf16 v[96:99], v[200:203], v[176:179], v[96:99]
	v_mfma_f32_16x16x32_bf16 v[88:91], v[208:211], v[176:179], v[88:91]
	v_mfma_f32_16x16x32_bf16 v[80:83], v[200:203], v[184:187], v[80:83]
	v_mfma_f32_16x16x32_bf16 v[72:75], v[208:211], v[184:187], v[72:75]
	v_mfma_f32_16x16x32_bf16 v[68:71], v[200:203], v[192:195], v[68:71]
	v_mfma_f32_16x16x32_bf16 v[64:67], v[208:211], v[192:195], v[64:67]
	v_mfma_f32_16x16x32_bf16 v[112:115], v[204:207], v[172:175], v[112:115]
	v_mfma_f32_16x16x32_bf16 v[104:107], v[212:215], v[172:175], v[104:107]
	v_mfma_f32_16x16x32_bf16 v[96:99], v[204:207], v[180:183], v[96:99]
	v_mfma_f32_16x16x32_bf16 v[88:91], v[212:215], v[180:183], v[88:91]
	v_mfma_f32_16x16x32_bf16 v[80:83], v[204:207], v[188:191], v[80:83]
	v_mfma_f32_16x16x32_bf16 v[72:75], v[212:215], v[188:191], v[72:75]
	v_mfma_f32_16x16x32_bf16 v[68:71], v[204:207], v[196:199], v[68:71]
	v_mfma_f32_16x16x32_bf16 v[64:67], v[212:215], v[196:199], v[64:67]
	s_setprio 0
	s_mov_b32 m0, s26
	v_lshl_add_u64 v[218:219], s[18:19], 0, v[130:131]
	s_barrier
	ds_read_b128 v[164:167], v146 offset:16384
	ds_read_b128 v[172:175], v146 offset:17408
	ds_read_b128 v[176:179], v146 offset:18432
	ds_read_b128 v[180:183], v146 offset:19456
	ds_read_b128 v[184:187], v146 offset:20480
	ds_read_b128 v[188:191], v146 offset:21504
	ds_read_b128 v[192:195], v146 offset:22528
	ds_read_b128 v[196:199], v146 offset:23552
	global_load_lds_dwordx4 v[218:219], off
	v_lshl_add_u64 v[220:221], s[18:19], 0, v[128:129]
	s_mov_b32 m0, s27
	s_nop 0
	global_load_lds_dwordx4 v[220:221], off
	s_barrier
	s_waitcnt lgkmcnt(0)
	s_setprio 1
	s_waitcnt lgkmcnt(0)
	v_mfma_f32_16x16x32_bf16 v[60:63], v[148:151], v[164:167], v[60:63]
	v_mfma_f32_16x16x32_bf16 v[56:59], v[156:159], v[164:167], v[56:59]
	v_mfma_f32_16x16x32_bf16 v[52:55], v[148:151], v[176:179], v[52:55]
	v_mfma_f32_16x16x32_bf16 v[44:47], v[156:159], v[176:179], v[44:47]
	v_mfma_f32_16x16x32_bf16 v[36:39], v[148:151], v[184:187], v[36:39]
	v_mfma_f32_16x16x32_bf16 v[28:31], v[156:159], v[184:187], v[28:31]
	v_mfma_f32_16x16x32_bf16 v[20:23], v[148:151], v[192:195], v[20:23]
	v_mfma_f32_16x16x32_bf16 v[12:15], v[156:159], v[192:195], v[12:15]
	v_mfma_f32_16x16x32_bf16 v[60:63], v[152:155], v[172:175], v[60:63]
	v_mfma_f32_16x16x32_bf16 v[56:59], v[160:163], v[172:175], v[56:59]
	v_mfma_f32_16x16x32_bf16 v[52:55], v[152:155], v[180:183], v[52:55]
	v_mfma_f32_16x16x32_bf16 v[44:47], v[160:163], v[180:183], v[44:47]
	v_mfma_f32_16x16x32_bf16 v[36:39], v[152:155], v[188:191], v[36:39]
	v_mfma_f32_16x16x32_bf16 v[28:31], v[160:163], v[188:191], v[28:31]
	v_mfma_f32_16x16x32_bf16 v[20:23], v[152:155], v[196:199], v[20:23]
	v_mfma_f32_16x16x32_bf16 v[12:15], v[160:163], v[196:199], v[12:15]
	s_setprio 0
	s_barrier
	s_add_u32 s12, s16, 0xb0000
	s_addc_u32 s13, s17, 0
	s_add_i32 s45, s34, s25
	v_lshl_add_u64 v[148:149], s[12:13], 0, v[130:131]
	s_mov_b32 m0, s45
	s_nop 0
	global_load_lds_dwordx4 v[148:149], off
	v_lshl_add_u64 v[148:149], s[12:13], 0, v[128:129]
	s_add_i32 m0, s45, 0x2000
	s_nop 0
	global_load_lds_dwordx4 v[148:149], off
	s_waitcnt vmcnt(10)
	s_barrier
	s_setprio 1
	v_mfma_f32_16x16x32_bf16 v[48:51], v[200:203], v[164:167], v[48:51]
	v_mfma_f32_16x16x32_bf16 v[40:43], v[208:211], v[164:167], v[40:43]
	v_mfma_f32_16x16x32_bf16 v[32:35], v[200:203], v[176:179], v[32:35]
	v_mfma_f32_16x16x32_bf16 v[24:27], v[208:211], v[176:179], v[24:27]
	v_mfma_f32_16x16x32_bf16 v[16:19], v[200:203], v[184:187], v[16:19]
	v_mfma_f32_16x16x32_bf16 v[8:11], v[208:211], v[184:187], v[8:11]
	v_mfma_f32_16x16x32_bf16 v[4:7], v[200:203], v[192:195], v[4:7]
	v_mfma_f32_16x16x32_bf16 v[0:3], v[208:211], v[192:195], v[0:3]
	v_mfma_f32_16x16x32_bf16 v[48:51], v[204:207], v[172:175], v[48:51]
	v_mfma_f32_16x16x32_bf16 v[40:43], v[212:215], v[172:175], v[40:43]
	v_mfma_f32_16x16x32_bf16 v[32:35], v[204:207], v[180:183], v[32:35]
	v_mfma_f32_16x16x32_bf16 v[24:27], v[212:215], v[180:183], v[24:27]
	v_mfma_f32_16x16x32_bf16 v[16:19], v[204:207], v[188:191], v[16:19]
	v_mfma_f32_16x16x32_bf16 v[8:11], v[212:215], v[188:191], v[8:11]
	v_mfma_f32_16x16x32_bf16 v[4:7], v[204:207], v[196:199], v[4:7]
	v_mfma_f32_16x16x32_bf16 v[0:3], v[212:215], v[196:199], v[0:3]
	s_setprio 0
	s_add_i32 s45, 0, 0x18000
	v_add_u32_e32 v160, s45, v144
	s_barrier
	ds_read_b128 v[148:151], v160
	ds_read_b128 v[152:155], v160 offset:1024
	ds_read_b128 v[156:159], v160 offset:2048
	ds_read_b128 v[160:163], v160 offset:3072
	s_add_u32 s12, s18, 0xb0000
	s_addc_u32 s13, s19, 0
	s_mov_b32 m0, s28
	v_lshl_add_u64 v[200:201], s[12:13], 0, v[130:131]
	ds_read_b128 v[164:167], v146 offset:32768
	ds_read_b128 v[172:175], v146 offset:33792
	ds_read_b128 v[176:179], v146 offset:34816
	ds_read_b128 v[180:183], v146 offset:35840
	ds_read_b128 v[184:187], v146 offset:36864
	ds_read_b128 v[188:191], v146 offset:37888
	ds_read_b128 v[192:195], v146 offset:38912
	ds_read_b128 v[196:199], v146 offset:39936
	global_load_lds_dwordx4 v[200:201], off
	v_lshl_add_u64 v[200:201], s[12:13], 0, v[128:129]
	s_mov_b32 m0, s29
	s_nop 0
	global_load_lds_dwordx4 v[200:201], off
	s_waitcnt lgkmcnt(8)
	s_waitcnt vmcnt(10)
	s_barrier
	s_waitcnt lgkmcnt(0)
	s_setprio 1
	s_waitcnt lgkmcnt(0)
	v_mfma_f32_16x16x32_bf16 v[124:127], v[148:151], v[164:167], v[124:127]
	v_mfma_f32_16x16x32_bf16 v[120:123], v[156:159], v[164:167], v[120:123]
	v_mfma_f32_16x16x32_bf16 v[116:119], v[148:151], v[176:179], v[116:119]
	v_mfma_f32_16x16x32_bf16 v[108:111], v[156:159], v[176:179], v[108:111]
	v_mfma_f32_16x16x32_bf16 v[100:103], v[148:151], v[184:187], v[100:103]
	v_mfma_f32_16x16x32_bf16 v[92:95], v[156:159], v[184:187], v[92:95]
	v_mfma_f32_16x16x32_bf16 v[84:87], v[148:151], v[192:195], v[84:87]
	v_mfma_f32_16x16x32_bf16 v[76:79], v[156:159], v[192:195], v[76:79]
	v_mfma_f32_16x16x32_bf16 v[124:127], v[152:155], v[172:175], v[124:127]
	v_mfma_f32_16x16x32_bf16 v[120:123], v[160:163], v[172:175], v[120:123]
	v_mfma_f32_16x16x32_bf16 v[116:119], v[152:155], v[180:183], v[116:119]
	v_mfma_f32_16x16x32_bf16 v[108:111], v[160:163], v[180:183], v[108:111]
	v_mfma_f32_16x16x32_bf16 v[100:103], v[152:155], v[188:191], v[100:103]
	v_mfma_f32_16x16x32_bf16 v[92:95], v[160:163], v[188:191], v[92:95]
	v_mfma_f32_16x16x32_bf16 v[84:87], v[152:155], v[196:199], v[84:87]
	v_mfma_f32_16x16x32_bf16 v[76:79], v[160:163], v[196:199], v[76:79]
	s_setprio 0
	s_barrier
	s_add_i32 s18, 0, 0x1c000
	s_add_i32 s12, s45, s25
	v_add_u32_e32 v171, s18, v144
	v_lshl_add_u64 v[168:169], v[168:169], 0, s[10:11]
	s_mov_b32 m0, s12
	ds_read_b128 v[200:203], v171
	ds_read_b128 v[204:207], v171 offset:1024
	ds_read_b128 v[208:211], v171 offset:2048
	ds_read_b128 v[212:215], v171 offset:3072
	global_load_lds_dwordx4 v[168:169], off
	v_lshl_add_u64 v[168:169], v[216:217], 0, s[10:11]
	s_add_i32 m0, s12, 0x2000
	s_nop 0
	global_load_lds_dwordx4 v[168:169], off
	s_waitcnt vmcnt(10)
	s_barrier
	s_waitcnt lgkmcnt(0)
	s_setprio 1
	s_waitcnt lgkmcnt(0)
	v_mfma_f32_16x16x32_bf16 v[112:115], v[200:203], v[164:167], v[112:115]
	v_mfma_f32_16x16x32_bf16 v[104:107], v[208:211], v[164:167], v[104:107]
	v_mfma_f32_16x16x32_bf16 v[96:99], v[200:203], v[176:179], v[96:99]
	v_mfma_f32_16x16x32_bf16 v[88:91], v[208:211], v[176:179], v[88:91]
	v_mfma_f32_16x16x32_bf16 v[80:83], v[200:203], v[184:187], v[80:83]
	v_mfma_f32_16x16x32_bf16 v[72:75], v[208:211], v[184:187], v[72:75]
	v_mfma_f32_16x16x32_bf16 v[68:71], v[200:203], v[192:195], v[68:71]
	v_mfma_f32_16x16x32_bf16 v[64:67], v[208:211], v[192:195], v[64:67]
	v_mfma_f32_16x16x32_bf16 v[112:115], v[204:207], v[172:175], v[112:115]
	v_mfma_f32_16x16x32_bf16 v[104:107], v[212:215], v[172:175], v[104:107]
	v_mfma_f32_16x16x32_bf16 v[96:99], v[204:207], v[180:183], v[96:99]
	v_mfma_f32_16x16x32_bf16 v[88:91], v[212:215], v[180:183], v[88:91]
	v_mfma_f32_16x16x32_bf16 v[80:83], v[204:207], v[188:191], v[80:83]
	v_mfma_f32_16x16x32_bf16 v[72:75], v[212:215], v[188:191], v[72:75]
	v_mfma_f32_16x16x32_bf16 v[68:71], v[204:207], v[196:199], v[68:71]
	v_mfma_f32_16x16x32_bf16 v[64:67], v[212:215], v[196:199], v[64:67]
	s_setprio 0
	s_mov_b32 m0, s30
	v_lshl_add_u64 v[168:169], v[218:219], 0, s[10:11]
	s_barrier
	ds_read_b128 v[164:167], v146 offset:49152
	ds_read_b128 v[172:175], v146 offset:50176
	ds_read_b128 v[176:179], v146 offset:51200
	ds_read_b128 v[180:183], v146 offset:52224
	ds_read_b128 v[184:187], v146 offset:53248
	ds_read_b128 v[188:191], v146 offset:54272
	ds_read_b128 v[192:195], v146 offset:55296
	ds_read_b128 v[196:199], v146 offset:56320
	global_load_lds_dwordx4 v[168:169], off
	v_lshl_add_u64 v[168:169], v[220:221], 0, s[10:11]
	s_mov_b32 m0, s31
	s_nop 0
	global_load_lds_dwordx4 v[168:169], off
	s_barrier
	s_waitcnt lgkmcnt(0)
	s_setprio 1
	s_waitcnt lgkmcnt(0)
	v_mfma_f32_16x16x32_bf16 v[60:63], v[148:151], v[164:167], v[60:63]
	v_mfma_f32_16x16x32_bf16 v[56:59], v[156:159], v[164:167], v[56:59]
	v_mfma_f32_16x16x32_bf16 v[52:55], v[148:151], v[176:179], v[52:55]
	v_mfma_f32_16x16x32_bf16 v[44:47], v[156:159], v[176:179], v[44:47]
	v_mfma_f32_16x16x32_bf16 v[36:39], v[148:151], v[184:187], v[36:39]
	v_mfma_f32_16x16x32_bf16 v[28:31], v[156:159], v[184:187], v[28:31]
	v_mfma_f32_16x16x32_bf16 v[20:23], v[148:151], v[192:195], v[20:23]
	v_mfma_f32_16x16x32_bf16 v[12:15], v[156:159], v[192:195], v[12:15]
	v_mfma_f32_16x16x32_bf16 v[60:63], v[152:155], v[172:175], v[60:63]
	v_mfma_f32_16x16x32_bf16 v[56:59], v[160:163], v[172:175], v[56:59]
	v_mfma_f32_16x16x32_bf16 v[52:55], v[152:155], v[180:183], v[52:55]
	v_mfma_f32_16x16x32_bf16 v[44:47], v[160:163], v[180:183], v[44:47]
	v_mfma_f32_16x16x32_bf16 v[36:39], v[152:155], v[188:191], v[36:39]
	v_mfma_f32_16x16x32_bf16 v[28:31], v[160:163], v[188:191], v[28:31]
	v_mfma_f32_16x16x32_bf16 v[20:23], v[152:155], v[196:199], v[20:23]
	v_mfma_f32_16x16x32_bf16 v[12:15], v[160:163], v[196:199], v[12:15]
	s_setprio 0
	s_barrier
	s_add_u32 s12, s16, 0xb0080
	s_addc_u32 s13, s17, 0
	s_add_i32 s16, s18, s25
	v_lshl_add_u64 v[148:149], s[12:13], 0, v[130:131]
	s_mov_b32 m0, s16
	s_nop 0
	global_load_lds_dwordx4 v[148:149], off
	v_lshl_add_u64 v[148:149], s[12:13], 0, v[128:129]
	s_add_i32 m0, s16, 0x2000
	s_nop 0
	global_load_lds_dwordx4 v[148:149], off
	s_waitcnt vmcnt(10)
	s_barrier
	s_setprio 1
	v_mfma_f32_16x16x32_bf16 v[48:51], v[200:203], v[164:167], v[48:51]
	v_mfma_f32_16x16x32_bf16 v[40:43], v[208:211], v[164:167], v[40:43]
	v_mfma_f32_16x16x32_bf16 v[32:35], v[200:203], v[176:179], v[32:35]
	v_mfma_f32_16x16x32_bf16 v[24:27], v[208:211], v[176:179], v[24:27]
	v_mfma_f32_16x16x32_bf16 v[16:19], v[200:203], v[184:187], v[16:19]
	v_mfma_f32_16x16x32_bf16 v[8:11], v[208:211], v[184:187], v[8:11]
	v_mfma_f32_16x16x32_bf16 v[4:7], v[200:203], v[192:195], v[4:7]
	v_mfma_f32_16x16x32_bf16 v[0:3], v[208:211], v[192:195], v[0:3]
	v_mfma_f32_16x16x32_bf16 v[48:51], v[204:207], v[172:175], v[48:51]
	v_mfma_f32_16x16x32_bf16 v[40:43], v[212:215], v[172:175], v[40:43]
	v_mfma_f32_16x16x32_bf16 v[32:35], v[204:207], v[180:183], v[32:35]
	v_mfma_f32_16x16x32_bf16 v[24:27], v[212:215], v[180:183], v[24:27]
	v_mfma_f32_16x16x32_bf16 v[16:19], v[204:207], v[188:191], v[16:19]
	v_mfma_f32_16x16x32_bf16 v[8:11], v[212:215], v[188:191], v[8:11]
	v_mfma_f32_16x16x32_bf16 v[4:7], v[204:207], v[196:199], v[4:7]
	v_mfma_f32_16x16x32_bf16 v[0:3], v[212:215], v[196:199], v[0:3]
	s_setprio 0
	s_add_i32 s44, s44, 2
	s_add_u32 s42, s42, 0x100
	s_addc_u32 s43, s43, 0
	s_cmp_gt_u32 s44, 41
	s_mov_b64 s[12:13], s[14:15]
	s_barrier
	s_cbranch_scc0 .LBB0_1284
	v_lshl_add_u32 v148, s41, 8, v143
	s_lshl_b32 s12, s40, 8
	v_ashrrev_i32_e32 v149, 31, v148
	s_ashr_i32 s13, s12, 31
	v_lshlrev_b64 v[150:151], 11, v[148:149]
	v_lshl_add_u64 v[150:151], s[4:5], 0, v[150:151]
	s_lshl_b64 s[12:13], s[12:13], 1
	v_lshl_add_u64 v[150:151], v[150:151], 0, s[12:13]
	v_lshl_add_u64 v[150:151], v[150:151], 0, s[2:3]
	v_lshl_add_u64 v[150:151], v[150:151], 0, v[132:133]
	v_mbcnt_lo_u32_b32 v237, -1, 0
	v_mbcnt_hi_u32_b32 v237, -1, v237
	v_bfe_i32 v237, v237, 4, 1
	v_and_b32_e32 v244, 24, v237
	v_add_co_u32_e32 v248, vcc, v244, v150
	s_nop 1
	v_addc_co_u32_e32 v249, vcc, 0, v151, vcc
	v_cvt_pk_bf16_f32 v124, v124, v125
	v_cvt_pk_bf16_f32 v125, v126, v127
	v_cvt_pk_bf16_f32 v120, v120, v121
	v_cvt_pk_bf16_f32 v121, v122, v123
	v_bfi_b32 v244, v237, v124, v120
	v_bfi_b32 v245, v237, v125, v121
	ds_swizzle_b32 v250, v244 offset:0x401f
	ds_swizzle_b32 v251, v245 offset:0x401f
	v_cvt_pk_bf16_f32 v112, v112, v113
	v_cvt_pk_bf16_f32 v113, v114, v115
	v_cvt_pk_bf16_f32 v104, v104, v105
	v_cvt_pk_bf16_f32 v105, v106, v107
	v_bfi_b32 v246, v237, v112, v104
	v_bfi_b32 v247, v237, v113, v105
	ds_swizzle_b32 v252, v246 offset:0x401f
	ds_swizzle_b32 v253, v247 offset:0x401f
	s_waitcnt lgkmcnt(0)
	v_bfi_b32 v240, v237, v250, v124
	v_bfi_b32 v241, v237, v251, v125
	v_bfi_b32 v242, v237, v120, v250
	v_bfi_b32 v243, v237, v121, v251
	global_store_dwordx4 v[248:249], v[240:243], off
	s_nop 1
	v_bfi_b32 v240, v237, v252, v112
	v_bfi_b32 v241, v237, v253, v113
	v_bfi_b32 v242, v237, v104, v252
	v_bfi_b32 v243, v237, v105, v253
	global_store_dwordx4 v[248:249], v[240:243], off offset:256
	s_nop 1
	v_add_co_u32_e32 v238, vcc, 0x8000, v248
	s_nop 1
	v_addc_co_u32_e32 v239, vcc, 0, v249, vcc
	v_cvt_pk_bf16_f32 v116, v116, v117
	v_cvt_pk_bf16_f32 v117, v118, v119
	v_cvt_pk_bf16_f32 v108, v108, v109
	v_cvt_pk_bf16_f32 v109, v110, v111
	v_bfi_b32 v244, v237, v116, v108
	v_bfi_b32 v245, v237, v117, v109
	ds_swizzle_b32 v250, v244 offset:0x401f
	ds_swizzle_b32 v251, v245 offset:0x401f
	v_cvt_pk_bf16_f32 v96, v96, v97
	v_cvt_pk_bf16_f32 v97, v98, v99
	v_cvt_pk_bf16_f32 v88, v88, v89
	v_cvt_pk_bf16_f32 v89, v90, v91
	v_bfi_b32 v246, v237, v96, v88
	v_bfi_b32 v247, v237, v97, v89
	ds_swizzle_b32 v252, v246 offset:0x401f
	ds_swizzle_b32 v253, v247 offset:0x401f
	s_waitcnt lgkmcnt(0)
	v_bfi_b32 v240, v237, v250, v116
	v_bfi_b32 v241, v237, v251, v117
	v_bfi_b32 v242, v237, v108, v250
	v_bfi_b32 v243, v237, v109, v251
	global_store_dwordx4 v[238:239], v[240:243], off
	s_nop 1
	v_bfi_b32 v240, v237, v252, v96
	v_bfi_b32 v241, v237, v253, v97
	v_bfi_b32 v242, v237, v88, v252
	v_bfi_b32 v243, v237, v89, v253
	global_store_dwordx4 v[238:239], v[240:243], off offset:256
	s_nop 1
	v_add_co_u32_e32 v238, vcc, 0x10000, v248
	s_nop 1
	v_addc_co_u32_e32 v239, vcc, 0, v249, vcc
	v_cvt_pk_bf16_f32 v100, v100, v101
	v_cvt_pk_bf16_f32 v101, v102, v103
	v_cvt_pk_bf16_f32 v92, v92, v93
	v_cvt_pk_bf16_f32 v93, v94, v95
	v_bfi_b32 v244, v237, v100, v92
	v_bfi_b32 v245, v237, v101, v93
	ds_swizzle_b32 v250, v244 offset:0x401f
	ds_swizzle_b32 v251, v245 offset:0x401f
	v_cvt_pk_bf16_f32 v80, v80, v81
	v_cvt_pk_bf16_f32 v81, v82, v83
	v_cvt_pk_bf16_f32 v72, v72, v73
	v_cvt_pk_bf16_f32 v73, v74, v75
	v_bfi_b32 v246, v237, v80, v72
	v_bfi_b32 v247, v237, v81, v73
	ds_swizzle_b32 v252, v246 offset:0x401f
	ds_swizzle_b32 v253, v247 offset:0x401f
	s_waitcnt lgkmcnt(0)
	v_bfi_b32 v240, v237, v250, v100
	v_bfi_b32 v241, v237, v251, v101
	v_bfi_b32 v242, v237, v92, v250
	v_bfi_b32 v243, v237, v93, v251
	global_store_dwordx4 v[238:239], v[240:243], off
	s_nop 1
	v_bfi_b32 v240, v237, v252, v80
	v_bfi_b32 v241, v237, v253, v81
	v_bfi_b32 v242, v237, v72, v252
	v_bfi_b32 v243, v237, v73, v253
	global_store_dwordx4 v[238:239], v[240:243], off offset:256
	s_nop 1
	v_add_co_u32_e32 v238, vcc, 0x18000, v248
	s_nop 1
	v_addc_co_u32_e32 v239, vcc, 0, v249, vcc
	v_cvt_pk_bf16_f32 v84, v84, v85
	v_cvt_pk_bf16_f32 v85, v86, v87
	v_cvt_pk_bf16_f32 v76, v76, v77
	v_cvt_pk_bf16_f32 v77, v78, v79
	v_bfi_b32 v244, v237, v84, v76
	v_bfi_b32 v245, v237, v85, v77
	ds_swizzle_b32 v250, v244 offset:0x401f
	ds_swizzle_b32 v251, v245 offset:0x401f
	v_cvt_pk_bf16_f32 v68, v68, v69
	v_cvt_pk_bf16_f32 v69, v70, v71
	v_cvt_pk_bf16_f32 v64, v64, v65
	v_cvt_pk_bf16_f32 v65, v66, v67
	v_bfi_b32 v246, v237, v68, v64
	v_bfi_b32 v247, v237, v69, v65
	ds_swizzle_b32 v252, v246 offset:0x401f
	ds_swizzle_b32 v253, v247 offset:0x401f
	s_waitcnt lgkmcnt(0)
	v_bfi_b32 v240, v237, v250, v84
	v_bfi_b32 v241, v237, v251, v85
	v_bfi_b32 v242, v237, v76, v250
	v_bfi_b32 v243, v237, v77, v251
	global_store_dwordx4 v[238:239], v[240:243], off
	s_nop 1
	v_bfi_b32 v240, v237, v252, v68
	v_bfi_b32 v241, v237, v253, v69
	v_bfi_b32 v242, v237, v64, v252
	v_bfi_b32 v243, v237, v65, v253
	global_store_dwordx4 v[238:239], v[240:243], off offset:256
	s_nop 1
	v_add_co_u32_e32 v238, vcc, 0x40000, v248
	s_nop 1
	v_addc_co_u32_e32 v239, vcc, 0, v249, vcc
	v_cvt_pk_bf16_f32 v60, v60, v61
	v_cvt_pk_bf16_f32 v61, v62, v63
	v_cvt_pk_bf16_f32 v56, v56, v57
	v_cvt_pk_bf16_f32 v57, v58, v59
	v_bfi_b32 v244, v237, v60, v56
	v_bfi_b32 v245, v237, v61, v57
	ds_swizzle_b32 v250, v244 offset:0x401f
	ds_swizzle_b32 v251, v245 offset:0x401f
	v_cvt_pk_bf16_f32 v48, v48, v49
	v_cvt_pk_bf16_f32 v49, v50, v51
	v_cvt_pk_bf16_f32 v40, v40, v41
	v_cvt_pk_bf16_f32 v41, v42, v43
	v_bfi_b32 v246, v237, v48, v40
	v_bfi_b32 v247, v237, v49, v41
	ds_swizzle_b32 v252, v246 offset:0x401f
	ds_swizzle_b32 v253, v247 offset:0x401f
	s_waitcnt lgkmcnt(0)
	v_bfi_b32 v240, v237, v250, v60
	v_bfi_b32 v241, v237, v251, v61
	v_bfi_b32 v242, v237, v56, v250
	v_bfi_b32 v243, v237, v57, v251
	global_store_dwordx4 v[238:239], v[240:243], off
	s_nop 1
	v_bfi_b32 v240, v237, v252, v48
	v_bfi_b32 v241, v237, v253, v49
	v_bfi_b32 v242, v237, v40, v252
	v_bfi_b32 v243, v237, v41, v253
	global_store_dwordx4 v[238:239], v[240:243], off offset:256
	s_nop 1
	v_add_co_u32_e32 v238, vcc, 0x48000, v248
	s_nop 1
	v_addc_co_u32_e32 v239, vcc, 0, v249, vcc
	v_cvt_pk_bf16_f32 v52, v52, v53
	v_cvt_pk_bf16_f32 v53, v54, v55
	v_cvt_pk_bf16_f32 v44, v44, v45
	v_cvt_pk_bf16_f32 v45, v46, v47
	v_bfi_b32 v244, v237, v52, v44
	v_bfi_b32 v245, v237, v53, v45
	ds_swizzle_b32 v250, v244 offset:0x401f
	ds_swizzle_b32 v251, v245 offset:0x401f
	v_cvt_pk_bf16_f32 v32, v32, v33
	v_cvt_pk_bf16_f32 v33, v34, v35
	v_cvt_pk_bf16_f32 v24, v24, v25
	v_cvt_pk_bf16_f32 v25, v26, v27
	v_bfi_b32 v246, v237, v32, v24
	v_bfi_b32 v247, v237, v33, v25
	ds_swizzle_b32 v252, v246 offset:0x401f
	ds_swizzle_b32 v253, v247 offset:0x401f
	s_waitcnt lgkmcnt(0)
	v_bfi_b32 v240, v237, v250, v52
	v_bfi_b32 v241, v237, v251, v53
	v_bfi_b32 v242, v237, v44, v250
	v_bfi_b32 v243, v237, v45, v251
	global_store_dwordx4 v[238:239], v[240:243], off
	s_nop 1
	v_bfi_b32 v240, v237, v252, v32
	v_bfi_b32 v241, v237, v253, v33
	v_bfi_b32 v242, v237, v24, v252
	v_bfi_b32 v243, v237, v25, v253
	global_store_dwordx4 v[238:239], v[240:243], off offset:256
	s_nop 1
	v_add_co_u32_e32 v238, vcc, 0x50000, v248
	s_nop 1
	v_addc_co_u32_e32 v239, vcc, 0, v249, vcc
	v_cvt_pk_bf16_f32 v36, v36, v37
	v_cvt_pk_bf16_f32 v37, v38, v39
	v_cvt_pk_bf16_f32 v28, v28, v29
	v_cvt_pk_bf16_f32 v29, v30, v31
	v_bfi_b32 v244, v237, v36, v28
	v_bfi_b32 v245, v237, v37, v29
	ds_swizzle_b32 v250, v244 offset:0x401f
	ds_swizzle_b32 v251, v245 offset:0x401f
	v_cvt_pk_bf16_f32 v16, v16, v17
	v_cvt_pk_bf16_f32 v17, v18, v19
	v_cvt_pk_bf16_f32 v8, v8, v9
	v_cvt_pk_bf16_f32 v9, v10, v11
	v_bfi_b32 v246, v237, v16, v8
	v_bfi_b32 v247, v237, v17, v9
	ds_swizzle_b32 v252, v246 offset:0x401f
	ds_swizzle_b32 v253, v247 offset:0x401f
	s_waitcnt lgkmcnt(0)
	v_bfi_b32 v240, v237, v250, v36
	v_bfi_b32 v241, v237, v251, v37
	v_bfi_b32 v242, v237, v28, v250
	v_bfi_b32 v243, v237, v29, v251
	global_store_dwordx4 v[238:239], v[240:243], off
	s_nop 1
	v_bfi_b32 v240, v237, v252, v16
	v_bfi_b32 v241, v237, v253, v17
	v_bfi_b32 v242, v237, v8, v252
	v_bfi_b32 v243, v237, v9, v253
	global_store_dwordx4 v[238:239], v[240:243], off offset:256
	s_nop 1
	v_add_co_u32_e32 v238, vcc, 0x58000, v248
	s_nop 1
	v_addc_co_u32_e32 v239, vcc, 0, v249, vcc
	v_cvt_pk_bf16_f32 v20, v20, v21
	v_cvt_pk_bf16_f32 v21, v22, v23
	v_cvt_pk_bf16_f32 v12, v12, v13
	v_cvt_pk_bf16_f32 v13, v14, v15
	v_bfi_b32 v244, v237, v20, v12
	v_bfi_b32 v245, v237, v21, v13
	ds_swizzle_b32 v250, v244 offset:0x401f
	ds_swizzle_b32 v251, v245 offset:0x401f
	v_cvt_pk_bf16_f32 v4, v4, v5
	v_cvt_pk_bf16_f32 v5, v6, v7
	v_cvt_pk_bf16_f32 v0, v0, v1
	v_cvt_pk_bf16_f32 v1, v2, v3
	v_bfi_b32 v246, v237, v4, v0
	v_bfi_b32 v247, v237, v5, v1
	ds_swizzle_b32 v252, v246 offset:0x401f
	ds_swizzle_b32 v253, v247 offset:0x401f
	s_waitcnt lgkmcnt(0)
	v_bfi_b32 v240, v237, v250, v20
	v_bfi_b32 v241, v237, v251, v21
	v_bfi_b32 v242, v237, v12, v250
	v_bfi_b32 v243, v237, v13, v251
	global_store_dwordx4 v[238:239], v[240:243], off
	s_nop 1
	v_bfi_b32 v240, v237, v252, v4
	v_bfi_b32 v241, v237, v253, v5
	v_bfi_b32 v242, v237, v0, v252
	v_bfi_b32 v243, v237, v1, v253
	global_store_dwordx4 v[238:239], v[240:243], off offset:256
	s_nop 1
	s_and_b64 vcc, exec, s[6:7]
	s_mov_b32 s40, s38
	s_mov_b32 s41, s39
	s_mov_b64 s[14:15], s[0:1]
	s_mov_b64 s[12:13], s[8:9]
	s_cbranch_vccz .LBB0_1277
	s_waitcnt vmcnt(0)
	s_cmpk_gt_u32 s20, 0xff
	s_cbranch_scc1 .LBB0_1288
	s_barrier

.LBB0_1407:
	ds_read_b128 v[128:131], v149
	ds_read_b128 v[132:135], v149 offset:1024
	ds_read_b128 v[164:167], v149 offset:2048
	ds_read_b128 v[176:179], v149 offset:3072
	s_add_u32 s12, s10, 0xfffc0080
	s_addc_u32 s13, s11, -1
	s_cmp_eq_u32 s36, 12
	s_cselect_b32 s15, s25, s13
	s_cselect_b32 s14, s30, s12
	s_cselect_b32 s13, s23, s35
	s_cselect_b32 s12, s31, s34
	v_lshl_add_u64 v[168:169], s[10:11], 0, v[158:159]
	s_add_i32 m0, s49, 0xc000
	ds_read_b128 v[180:183], v171
	ds_read_b128 v[184:187], v171 offset:1024
	ds_read_b128 v[188:191], v171 offset:2048
	ds_read_b128 v[192:195], v171 offset:3072
	ds_read_b128 v[196:199], v171 offset:4096
	ds_read_b128 v[200:203], v171 offset:5120
	ds_read_b128 v[204:207], v171 offset:6144
	ds_read_b128 v[208:211], v171 offset:7168
	global_load_lds_dwordx4 v[168:169], off
	v_lshl_add_u64 v[168:169], s[10:11], 0, v[156:157]
	s_add_i32 m0, s49, 0xe000
	s_nop 0
	global_load_lds_dwordx4 v[168:169], off
	s_waitcnt lgkmcnt(8)
	s_waitcnt vmcnt(10)
	s_barrier
	s_waitcnt lgkmcnt(0)
	s_setprio 1
	s_waitcnt lgkmcnt(0)
	v_mfma_f32_16x16x32_bf16 v[124:127], v[128:131], v[180:183], v[124:127]
	v_mfma_f32_16x16x32_bf16 v[120:123], v[164:167], v[180:183], v[120:123]
	v_mfma_f32_16x16x32_bf16 v[108:111], v[128:131], v[188:191], v[108:111]
	v_mfma_f32_16x16x32_bf16 v[104:107], v[164:167], v[188:191], v[104:107]
	v_mfma_f32_16x16x32_bf16 v[92:95], v[128:131], v[196:199], v[92:95]
	v_mfma_f32_16x16x32_bf16 v[88:91], v[164:167], v[196:199], v[88:91]
	v_mfma_f32_16x16x32_bf16 v[76:79], v[128:131], v[204:207], v[76:79]
	v_mfma_f32_16x16x32_bf16 v[72:75], v[164:167], v[204:207], v[72:75]
	v_mfma_f32_16x16x32_bf16 v[124:127], v[132:135], v[184:187], v[124:127]
	v_mfma_f32_16x16x32_bf16 v[120:123], v[176:179], v[184:187], v[120:123]
	v_mfma_f32_16x16x32_bf16 v[108:111], v[132:135], v[192:195], v[108:111]
	v_mfma_f32_16x16x32_bf16 v[104:107], v[176:179], v[192:195], v[104:107]
	v_mfma_f32_16x16x32_bf16 v[92:95], v[132:135], v[200:203], v[92:95]
	v_mfma_f32_16x16x32_bf16 v[88:91], v[176:179], v[200:203], v[88:91]
	v_mfma_f32_16x16x32_bf16 v[76:79], v[132:135], v[208:211], v[76:79]
	v_mfma_f32_16x16x32_bf16 v[72:75], v[176:179], v[208:211], v[72:75]
	s_setprio 0
	s_barrier
	s_add_i32 s37, s58, s48
	v_lshl_add_u64 v[168:169], s[12:13], 0, v[138:139]
	s_mov_b32 m0, s37
	ds_read_b128 v[212:215], v172
	ds_read_b128 v[216:219], v172 offset:1024
	ds_read_b128 v[220:223], v172 offset:2048
	ds_read_b128 v[224:227], v172 offset:3072
	global_load_lds_dwordx4 v[168:169], off
	v_lshl_add_u64 v[228:229], s[12:13], 0, v[136:137]
	s_add_i32 m0, s37, 0x2000
	s_nop 0
	global_load_lds_dwordx4 v[228:229], off
	s_waitcnt vmcnt(10)
	s_barrier
	s_waitcnt lgkmcnt(0)
	s_setprio 1
	s_waitcnt lgkmcnt(0)
	v_mfma_f32_16x16x32_bf16 v[116:119], v[212:215], v[180:183], v[116:119]
	v_mfma_f32_16x16x32_bf16 v[112:115], v[220:223], v[180:183], v[112:115]
	v_mfma_f32_16x16x32_bf16 v[100:103], v[212:215], v[188:191], v[100:103]
	v_mfma_f32_16x16x32_bf16 v[96:99], v[220:223], v[188:191], v[96:99]
	v_mfma_f32_16x16x32_bf16 v[84:87], v[212:215], v[196:199], v[84:87]
	v_mfma_f32_16x16x32_bf16 v[80:83], v[220:223], v[196:199], v[80:83]
	v_mfma_f32_16x16x32_bf16 v[68:71], v[212:215], v[204:207], v[68:71]
	v_mfma_f32_16x16x32_bf16 v[64:67], v[220:223], v[204:207], v[64:67]
	v_mfma_f32_16x16x32_bf16 v[116:119], v[216:219], v[184:187], v[116:119]
	v_mfma_f32_16x16x32_bf16 v[112:115], v[224:227], v[184:187], v[112:115]
	v_mfma_f32_16x16x32_bf16 v[100:103], v[216:219], v[192:195], v[100:103]
	v_mfma_f32_16x16x32_bf16 v[96:99], v[224:227], v[192:195], v[96:99]
	v_mfma_f32_16x16x32_bf16 v[84:87], v[216:219], v[200:203], v[84:87]
	v_mfma_f32_16x16x32_bf16 v[80:83], v[224:227], v[200:203], v[80:83]
	v_mfma_f32_16x16x32_bf16 v[68:71], v[216:219], v[208:211], v[68:71]
	v_mfma_f32_16x16x32_bf16 v[64:67], v[224:227], v[208:211], v[64:67]
	s_setprio 0
	s_mov_b32 m0, s49
	v_lshl_add_u64 v[230:231], s[14:15], 0, v[138:139]
	s_barrier
	ds_read_b128 v[180:183], v171 offset:16384
	ds_read_b128 v[184:187], v171 offset:17408
	ds_read_b128 v[188:191], v171 offset:18432
	ds_read_b128 v[192:195], v171 offset:19456
	ds_read_b128 v[196:199], v171 offset:20480
	ds_read_b128 v[200:203], v171 offset:21504
	ds_read_b128 v[204:207], v171 offset:22528
	ds_read_b128 v[208:211], v171 offset:23552
	global_load_lds_dwordx4 v[230:231], off
	v_lshl_add_u64 v[232:233], s[14:15], 0, v[136:137]
	s_mov_b32 m0, s50
	s_nop 0
	global_load_lds_dwordx4 v[232:233], off
	s_barrier
	s_waitcnt lgkmcnt(0)
	s_setprio 1
	s_waitcnt lgkmcnt(0)
	v_mfma_f32_16x16x32_bf16 v[60:63], v[128:131], v[180:183], v[60:63]
	v_mfma_f32_16x16x32_bf16 v[56:59], v[164:167], v[180:183], v[56:59]
	v_mfma_f32_16x16x32_bf16 v[44:47], v[128:131], v[188:191], v[44:47]
	v_mfma_f32_16x16x32_bf16 v[40:43], v[164:167], v[188:191], v[40:43]
	v_mfma_f32_16x16x32_bf16 v[28:31], v[128:131], v[196:199], v[28:31]
	v_mfma_f32_16x16x32_bf16 v[24:27], v[164:167], v[196:199], v[24:27]
	v_mfma_f32_16x16x32_bf16 v[12:15], v[128:131], v[204:207], v[12:15]
	v_mfma_f32_16x16x32_bf16 v[8:11], v[164:167], v[204:207], v[8:11]
	v_mfma_f32_16x16x32_bf16 v[60:63], v[132:135], v[184:187], v[60:63]
	v_mfma_f32_16x16x32_bf16 v[56:59], v[176:179], v[184:187], v[56:59]
	v_mfma_f32_16x16x32_bf16 v[44:47], v[132:135], v[192:195], v[44:47]
	v_mfma_f32_16x16x32_bf16 v[40:43], v[176:179], v[192:195], v[40:43]
	v_mfma_f32_16x16x32_bf16 v[28:31], v[132:135], v[200:203], v[28:31]
	v_mfma_f32_16x16x32_bf16 v[24:27], v[176:179], v[200:203], v[24:27]
	v_mfma_f32_16x16x32_bf16 v[12:15], v[132:135], v[208:211], v[12:15]
	v_mfma_f32_16x16x32_bf16 v[8:11], v[176:179], v[208:211], v[8:11]
	s_setprio 0
	s_barrier
	s_add_u32 s38, s12, 0x40000
	s_addc_u32 s39, s13, 0
	s_add_i32 s37, s59, s48
	v_lshl_add_u64 v[128:129], s[38:39], 0, v[138:139]
	s_mov_b32 m0, s37
	s_nop 0
	global_load_lds_dwordx4 v[128:129], off
	v_lshl_add_u64 v[128:129], s[38:39], 0, v[136:137]
	s_add_i32 m0, s37, 0x2000
	s_nop 0
	global_load_lds_dwordx4 v[128:129], off
	s_waitcnt vmcnt(10)
	s_barrier
	s_setprio 1
	v_mfma_f32_16x16x32_bf16 v[52:55], v[212:215], v[180:183], v[52:55]
	v_mfma_f32_16x16x32_bf16 v[48:51], v[220:223], v[180:183], v[48:51]
	v_mfma_f32_16x16x32_bf16 v[36:39], v[212:215], v[188:191], v[36:39]
	v_mfma_f32_16x16x32_bf16 v[32:35], v[220:223], v[188:191], v[32:35]
	v_mfma_f32_16x16x32_bf16 v[20:23], v[212:215], v[196:199], v[20:23]
	v_mfma_f32_16x16x32_bf16 v[16:19], v[220:223], v[196:199], v[16:19]
	v_mfma_f32_16x16x32_bf16 v[4:7], v[212:215], v[204:207], v[4:7]
	v_mfma_f32_16x16x32_bf16 v[0:3], v[220:223], v[204:207], v[0:3]
	v_mfma_f32_16x16x32_bf16 v[52:55], v[216:219], v[184:187], v[52:55]
	v_mfma_f32_16x16x32_bf16 v[48:51], v[224:227], v[184:187], v[48:51]
	v_mfma_f32_16x16x32_bf16 v[36:39], v[216:219], v[192:195], v[36:39]
	v_mfma_f32_16x16x32_bf16 v[32:35], v[224:227], v[192:195], v[32:35]
	v_mfma_f32_16x16x32_bf16 v[20:23], v[216:219], v[200:203], v[20:23]
	v_mfma_f32_16x16x32_bf16 v[16:19], v[224:227], v[200:203], v[16:19]
	v_mfma_f32_16x16x32_bf16 v[4:7], v[216:219], v[208:211], v[4:7]
	v_mfma_f32_16x16x32_bf16 v[0:3], v[224:227], v[208:211], v[0:3]
	s_setprio 0
	s_add_i32 s37, 0, 0x18000
	v_add_u32_e32 v175, s37, v147
	s_barrier
	ds_read_b128 v[128:131], v175
	ds_read_b128 v[132:135], v175 offset:1024
	ds_read_b128 v[164:167], v175 offset:2048
	ds_read_b128 v[176:179], v175 offset:3072
	s_add_u32 s14, s14, 0x40000
	s_addc_u32 s15, s15, 0
	s_mov_b32 m0, s51
	v_lshl_add_u64 v[212:213], s[14:15], 0, v[138:139]
	ds_read_b128 v[180:183], v171 offset:32768
	ds_read_b128 v[184:187], v171 offset:33792
	ds_read_b128 v[188:191], v171 offset:34816
	ds_read_b128 v[192:195], v171 offset:35840
	ds_read_b128 v[196:199], v171 offset:36864
	ds_read_b128 v[200:203], v171 offset:37888
	ds_read_b128 v[204:207], v171 offset:38912
	ds_read_b128 v[208:211], v171 offset:39936
	global_load_lds_dwordx4 v[212:213], off
	v_lshl_add_u64 v[212:213], s[14:15], 0, v[136:137]
	s_mov_b32 m0, s52
	s_nop 0
	global_load_lds_dwordx4 v[212:213], off
	s_waitcnt lgkmcnt(8)
	s_waitcnt vmcnt(10)
	s_barrier
	s_waitcnt lgkmcnt(0)
	s_setprio 1
	s_waitcnt lgkmcnt(0)
	v_mfma_f32_16x16x32_bf16 v[124:127], v[128:131], v[180:183], v[124:127]
	v_mfma_f32_16x16x32_bf16 v[120:123], v[164:167], v[180:183], v[120:123]
	v_mfma_f32_16x16x32_bf16 v[108:111], v[128:131], v[188:191], v[108:111]
	v_mfma_f32_16x16x32_bf16 v[104:107], v[164:167], v[188:191], v[104:107]
	v_mfma_f32_16x16x32_bf16 v[92:95], v[128:131], v[196:199], v[92:95]
	v_mfma_f32_16x16x32_bf16 v[88:91], v[164:167], v[196:199], v[88:91]
	v_mfma_f32_16x16x32_bf16 v[76:79], v[128:131], v[204:207], v[76:79]
	v_mfma_f32_16x16x32_bf16 v[72:75], v[164:167], v[204:207], v[72:75]
	v_mfma_f32_16x16x32_bf16 v[124:127], v[132:135], v[184:187], v[124:127]
	v_mfma_f32_16x16x32_bf16 v[120:123], v[176:179], v[184:187], v[120:123]
	v_mfma_f32_16x16x32_bf16 v[108:111], v[132:135], v[192:195], v[108:111]
	v_mfma_f32_16x16x32_bf16 v[104:107], v[176:179], v[192:195], v[104:107]
	v_mfma_f32_16x16x32_bf16 v[92:95], v[132:135], v[200:203], v[92:95]
	v_mfma_f32_16x16x32_bf16 v[88:91], v[176:179], v[200:203], v[88:91]
	v_mfma_f32_16x16x32_bf16 v[76:79], v[132:135], v[208:211], v[76:79]
	v_mfma_f32_16x16x32_bf16 v[72:75], v[176:179], v[208:211], v[72:75]
	s_setprio 0
	s_barrier
	s_add_i32 s14, 0, 0x1c000
	s_add_i32 s15, s37, s48
	v_add_u32_e32 v175, s14, v147
	v_lshl_add_u64 v[168:169], v[168:169], 0, s[18:19]
	s_mov_b32 m0, s15
	ds_read_b128 v[212:215], v175
	ds_read_b128 v[216:219], v175 offset:1024
	ds_read_b128 v[220:223], v175 offset:2048
	ds_read_b128 v[224:227], v175 offset:3072
	global_load_lds_dwordx4 v[168:169], off
	v_lshl_add_u64 v[168:169], v[228:229], 0, s[18:19]
	s_add_i32 m0, s15, 0x2000
	s_nop 0
	global_load_lds_dwordx4 v[168:169], off
	s_waitcnt vmcnt(10)
	s_barrier
	s_waitcnt lgkmcnt(0)
	s_setprio 1
	s_waitcnt lgkmcnt(0)
	v_mfma_f32_16x16x32_bf16 v[116:119], v[212:215], v[180:183], v[116:119]
	v_mfma_f32_16x16x32_bf16 v[112:115], v[220:223], v[180:183], v[112:115]
	v_mfma_f32_16x16x32_bf16 v[100:103], v[212:215], v[188:191], v[100:103]
	v_mfma_f32_16x16x32_bf16 v[96:99], v[220:223], v[188:191], v[96:99]
	v_mfma_f32_16x16x32_bf16 v[84:87], v[212:215], v[196:199], v[84:87]
	v_mfma_f32_16x16x32_bf16 v[80:83], v[220:223], v[196:199], v[80:83]
	v_mfma_f32_16x16x32_bf16 v[68:71], v[212:215], v[204:207], v[68:71]
	v_mfma_f32_16x16x32_bf16 v[64:67], v[220:223], v[204:207], v[64:67]
	v_mfma_f32_16x16x32_bf16 v[116:119], v[216:219], v[184:187], v[116:119]
	v_mfma_f32_16x16x32_bf16 v[112:115], v[224:227], v[184:187], v[112:115]
	v_mfma_f32_16x16x32_bf16 v[100:103], v[216:219], v[192:195], v[100:103]
	v_mfma_f32_16x16x32_bf16 v[96:99], v[224:227], v[192:195], v[96:99]
	v_mfma_f32_16x16x32_bf16 v[84:87], v[216:219], v[200:203], v[84:87]
	v_mfma_f32_16x16x32_bf16 v[80:83], v[224:227], v[200:203], v[80:83]
	v_mfma_f32_16x16x32_bf16 v[68:71], v[216:219], v[208:211], v[68:71]
	v_mfma_f32_16x16x32_bf16 v[64:67], v[224:227], v[208:211], v[64:67]
	s_setprio 0
	s_mov_b32 m0, s56
	v_lshl_add_u64 v[168:169], v[230:231], 0, s[18:19]
	s_barrier
	ds_read_b128 v[180:183], v171 offset:49152
	ds_read_b128 v[184:187], v171 offset:50176
	ds_read_b128 v[188:191], v171 offset:51200
	ds_read_b128 v[192:195], v171 offset:52224
	ds_read_b128 v[196:199], v171 offset:53248
	ds_read_b128 v[200:203], v171 offset:54272
	ds_read_b128 v[204:207], v171 offset:55296
	ds_read_b128 v[208:211], v171 offset:56320
	global_load_lds_dwordx4 v[168:169], off
	v_lshl_add_u64 v[168:169], v[232:233], 0, s[18:19]
	s_mov_b32 m0, s57
	s_nop 0
	global_load_lds_dwordx4 v[168:169], off
	s_barrier
	s_waitcnt lgkmcnt(0)
	s_setprio 1
	s_waitcnt lgkmcnt(0)
	v_mfma_f32_16x16x32_bf16 v[60:63], v[128:131], v[180:183], v[60:63]
	v_mfma_f32_16x16x32_bf16 v[56:59], v[164:167], v[180:183], v[56:59]
	v_mfma_f32_16x16x32_bf16 v[44:47], v[128:131], v[188:191], v[44:47]
	v_mfma_f32_16x16x32_bf16 v[40:43], v[164:167], v[188:191], v[40:43]
	v_mfma_f32_16x16x32_bf16 v[28:31], v[128:131], v[196:199], v[28:31]
	v_mfma_f32_16x16x32_bf16 v[24:27], v[164:167], v[196:199], v[24:27]
	v_mfma_f32_16x16x32_bf16 v[12:15], v[128:131], v[204:207], v[12:15]
	v_mfma_f32_16x16x32_bf16 v[8:11], v[164:167], v[204:207], v[8:11]
	v_mfma_f32_16x16x32_bf16 v[60:63], v[132:135], v[184:187], v[60:63]
	v_mfma_f32_16x16x32_bf16 v[56:59], v[176:179], v[184:187], v[56:59]
	v_mfma_f32_16x16x32_bf16 v[44:47], v[132:135], v[192:195], v[44:47]
	v_mfma_f32_16x16x32_bf16 v[40:43], v[176:179], v[192:195], v[40:43]
	v_mfma_f32_16x16x32_bf16 v[28:31], v[132:135], v[200:203], v[28:31]
	v_mfma_f32_16x16x32_bf16 v[24:27], v[176:179], v[200:203], v[24:27]
	v_mfma_f32_16x16x32_bf16 v[12:15], v[132:135], v[208:211], v[12:15]
	v_mfma_f32_16x16x32_bf16 v[8:11], v[176:179], v[208:211], v[8:11]
	s_setprio 0
	s_barrier
	s_add_u32 s12, s12, 0x40080
	s_addc_u32 s13, s13, 0
	s_add_i32 s14, s14, s48
	v_lshl_add_u64 v[128:129], s[12:13], 0, v[138:139]
	s_mov_b32 m0, s14
	s_nop 0
	global_load_lds_dwordx4 v[128:129], off
	v_lshl_add_u64 v[128:129], s[12:13], 0, v[136:137]
	s_add_i32 m0, s14, 0x2000
	s_nop 0
	global_load_lds_dwordx4 v[128:129], off
	s_waitcnt vmcnt(10)
	s_barrier
	s_setprio 1
	v_mfma_f32_16x16x32_bf16 v[52:55], v[212:215], v[180:183], v[52:55]
	v_mfma_f32_16x16x32_bf16 v[48:51], v[220:223], v[180:183], v[48:51]
	v_mfma_f32_16x16x32_bf16 v[36:39], v[212:215], v[188:191], v[36:39]
	v_mfma_f32_16x16x32_bf16 v[32:35], v[220:223], v[188:191], v[32:35]
	v_mfma_f32_16x16x32_bf16 v[20:23], v[212:215], v[196:199], v[20:23]
	v_mfma_f32_16x16x32_bf16 v[16:19], v[220:223], v[196:199], v[16:19]
	v_mfma_f32_16x16x32_bf16 v[4:7], v[212:215], v[204:207], v[4:7]
	v_mfma_f32_16x16x32_bf16 v[0:3], v[220:223], v[204:207], v[0:3]
	v_mfma_f32_16x16x32_bf16 v[52:55], v[216:219], v[184:187], v[52:55]
	v_mfma_f32_16x16x32_bf16 v[48:51], v[224:227], v[184:187], v[48:51]
	v_mfma_f32_16x16x32_bf16 v[36:39], v[216:219], v[192:195], v[36:39]
	v_mfma_f32_16x16x32_bf16 v[32:35], v[224:227], v[192:195], v[32:35]
	v_mfma_f32_16x16x32_bf16 v[20:23], v[216:219], v[200:203], v[20:23]
	v_mfma_f32_16x16x32_bf16 v[16:19], v[224:227], v[200:203], v[16:19]
	v_mfma_f32_16x16x32_bf16 v[4:7], v[216:219], v[208:211], v[4:7]
	v_mfma_f32_16x16x32_bf16 v[0:3], v[224:227], v[208:211], v[0:3]
	s_setprio 0
	s_add_i32 s36, s36, 2
	s_add_u32 s34, s34, 0x100
	s_addc_u32 s35, s35, 0
	s_add_u32 s10, s10, 0x100
	s_addc_u32 s11, s11, 0
	s_cmp_gt_u32 s36, 13
	s_barrier
	s_cbranch_scc0 .LBB0_1407
	s_lshl_b32 s36, s42, 1
	s_add_i32 s10, s36, 0xffffff80
	s_lshr_b32 s63, s10, 4
	s_lshl_b32 s10, s40, 8
	s_add_i32 s63, s63, 4
	s_ashr_i32 s64, s42, 4
	s_or_b32 s23, s10, s55
	s_and_b32 s10, s40, 0xfffffe
	s_cmp_eq_u32 s10, 6
	s_cselect_b64 s[34:35], -1, 0
	s_cmp_eq_u32 s40, 7
	s_cselect_b64 s[30:31], -1, 0
	s_lshl_b32 s10, s42, 8
	s_cmp_lt_i32 s42, 64
	s_movk_i32 s11, 0xf00
	s_cselect_b32 s11, s11, 0x700
	s_cselect_b32 s12, s64, s63
	s_cselect_b32 s25, s60, 0x800
	s_cselect_b32 s65, 12, 11
	s_and_b32 s66, s11, s10
	s_lshl_b32 s11, s12, 11
	s_lshl_b32 s10, s12, 12
	s_addk_i32 s11, 0x2000
	s_cmp_lt_i32 s12, 4
	s_cselect_b32 s10, s10, s11
	s_ashr_i32 s11, s10, 31
	s_lshl_b64 s[10:11], s[10:11], 10
	s_add_u32 s38, s53, s10
	s_addc_u32 s39, s54, s11
	s_ashr_i32 s37, s36, 31
	v_add_u32_e32 v175, s66, v142
	s_lshl_b64 s[40:41], s[36:37], 7
	v_mul_lo_u32 v130, v175, 56
	s_lshr_b32 s67, s25, 1
	v_lshl_add_u64 v[128:129], s[40:41], 0, v[142:143]
	v_ashrrev_i32_e32 v131, 31, v130
	v_lshl_add_u64 v[168:169], v[130:131], 3, s[16:17]
	v_mad_u64_u32 v[164:165], s[12:13], v128, s61, 0
	s_cmpk_gt_i32 s23, 0x1ff
	v_mad_i32_i24 v165, v129, s61, v165
	v_lshl_add_u64 v[128:129], v[168:169], 0, s[2:3]
	s_cselect_b64 s[14:15], -1, 0
	v_cmp_lt_i32_e64 s[10:11], s67, v175
	v_lshl_add_u64 v[166:167], v[128:129], 0, v[140:141]
	s_mov_b64 s[12:13], -1
	s_and_b64 vcc, exec, s[14:15]
	s_cbranch_vccz .LBB0_1419
	s_cmpk_gt_u32 s23, 0x109f
	s_cbranch_scc1 .LBB0_1418
	s_add_i32 s12, s23, 0xfffffe00
	s_cmpk_gt_u32 s12, 0x1ff
	s_mov_b64 s[42:43], -1
	s_cbranch_scc0 .LBB0_1416
	s_add_i32 s13, s23, 0xfffff700
	s_cmpk_lt_u32 s13, 0x400
	s_cselect_b64 s[42:43], -1, 0
	s_or_b64 s[42:43], s[34:35], s[42:43]
	v_mov_b64_e32 v[134:135], v[126:127]
	v_mov_b64_e32 v[130:131], v[122:123]
	s_andn2_b64 vcc, exec, s[42:43]
	v_mov_b64_e32 v[132:133], v[124:125]
	v_mov_b64_e32 v[128:129], v[120:121]
	s_cbranch_vccnz .LBB0_1415
	s_andn2_b64 vcc, exec, s[20:21]
	v_mov_b32_e32 v128, v124
	v_mov_b32_e32 v129, v125
	v_mov_b32_e32 v130, v126
	v_mov_b32_e32 v131, v127
	s_cbranch_vccnz .LBB0_1414
	v_and_b32_e32 v129, 64, v170
	v_xor_b32_e32 v128, 32, v170
	v_add_u32_e32 v129, 64, v129
	v_cmp_lt_i32_e32 vcc, v128, v129
	v_mov_b32_e32 v129, v141
	s_nop 0
	v_cndmask_b32_e32 v128, v170, v128, vcc
	v_lshlrev_b32_e32 v178, 2, v128
	v_lshlrev_b32_e32 v128, 3, v146
	v_lshl_add_u64 v[132:133], v[168:169], 0, v[128:129]
	s_waitcnt vmcnt(0)
	global_load_dwordx4 v[128:131], v[132:133], off offset:128
	ds_bpermute_b32 v134, v178, v124
	ds_bpermute_b32 v135, v178, v125
	s_waitcnt vmcnt(0) lgkmcnt(0)
	v_mov_b32_e32 v177, v130
	v_mov_b32_e32 v130, v129
	v_mov_b32_e32 v176, v128
	v_pk_mul_f32 v[128:129], v[130:131], v[134:135]
	global_load_dwordx4 v[130:133], v[132:133], off offset:144
	ds_bpermute_b32 v134, v178, v126
	ds_bpermute_b32 v135, v178, v127
	v_cndmask_b32_e64 v129, v129, -v129, s[6:7]
	v_cndmask_b32_e64 v128, v128, -v128, s[6:7]
	v_pk_fma_f32 v[128:129], v[124:125], v[176:177], v[128:129]
	s_waitcnt vmcnt(0) lgkmcnt(0)
	v_mov_b32_e32 v177, v132
	v_mov_b32_e32 v132, v131
	v_mov_b32_e32 v176, v130
	v_pk_mul_f32 v[130:131], v[132:133], v[134:135]
	s_nop 0
	v_cndmask_b32_e64 v131, v131, -v131, s[6:7]
	v_cndmask_b32_e64 v130, v130, -v130, s[6:7]
	v_pk_fma_f32 v[130:131], v[126:127], v[176:177], v[130:131]

.LBB0_2046:
	ds_read_b128 v[152:155], v149
	ds_read_b128 v[156:159], v149 offset:1024
	ds_read_b128 v[160:163], v149 offset:2048
	ds_read_b128 v[164:167], v149 offset:3072
	s_add_u32 s8, s16, 0x100
	s_addc_u32 s9, s17, 0
	s_cmp_eq_u32 s45, 12
	s_cselect_b32 s21, s13, s9
	s_cselect_b32 s20, s12, s8
	s_cselect_b32 s19, s11, s44
	s_cselect_b32 s18, s42, s43
	v_lshl_add_u64 v[168:169], s[16:17], 0, v[140:141]
	s_add_i32 m0, s28, 0xc000
	ds_read_b128 v[172:175], v150
	ds_read_b128 v[176:179], v150 offset:1024
	ds_read_b128 v[180:183], v150 offset:2048
	ds_read_b128 v[184:187], v150 offset:3072
	ds_read_b128 v[188:191], v150 offset:4096
	ds_read_b128 v[192:195], v150 offset:5120
	ds_read_b128 v[196:199], v150 offset:6144
	ds_read_b128 v[200:203], v150 offset:7168
	global_load_lds_dwordx4 v[168:169], off
	v_lshl_add_u64 v[168:169], s[16:17], 0, v[138:139]
	s_add_i32 m0, s28, 0xe000
	s_nop 0
	global_load_lds_dwordx4 v[168:169], off
	s_waitcnt lgkmcnt(8)
	s_waitcnt vmcnt(10)
	s_barrier
	s_waitcnt lgkmcnt(0)
	s_setprio 1
	s_waitcnt lgkmcnt(0)
	v_mfma_f32_16x16x32_bf16 v[124:127], v[152:155], v[172:175], v[124:127]
	v_mfma_f32_16x16x32_bf16 v[120:123], v[160:163], v[172:175], v[120:123]
	v_mfma_f32_16x16x32_bf16 v[116:119], v[152:155], v[180:183], v[116:119]
	v_mfma_f32_16x16x32_bf16 v[108:111], v[160:163], v[180:183], v[108:111]
	v_mfma_f32_16x16x32_bf16 v[100:103], v[152:155], v[188:191], v[100:103]
	v_mfma_f32_16x16x32_bf16 v[92:95], v[160:163], v[188:191], v[92:95]
	v_mfma_f32_16x16x32_bf16 v[84:87], v[152:155], v[196:199], v[84:87]
	v_mfma_f32_16x16x32_bf16 v[76:79], v[160:163], v[196:199], v[76:79]
	v_mfma_f32_16x16x32_bf16 v[124:127], v[156:159], v[176:179], v[124:127]
	v_mfma_f32_16x16x32_bf16 v[120:123], v[164:167], v[176:179], v[120:123]
	v_mfma_f32_16x16x32_bf16 v[116:119], v[156:159], v[184:187], v[116:119]
	v_mfma_f32_16x16x32_bf16 v[108:111], v[164:167], v[184:187], v[108:111]
	v_mfma_f32_16x16x32_bf16 v[100:103], v[156:159], v[192:195], v[100:103]
	v_mfma_f32_16x16x32_bf16 v[92:95], v[164:167], v[192:195], v[92:95]
	v_mfma_f32_16x16x32_bf16 v[84:87], v[156:159], v[200:203], v[84:87]
	v_mfma_f32_16x16x32_bf16 v[76:79], v[164:167], v[200:203], v[76:79]
	s_setprio 0
	s_barrier
	s_add_i32 s16, s36, s27
	v_lshl_add_u64 v[168:169], s[18:19], 0, v[132:133]
	s_mov_b32 m0, s16
	ds_read_b128 v[204:207], v151
	ds_read_b128 v[208:211], v151 offset:1024
	ds_read_b128 v[212:215], v151 offset:2048
	ds_read_b128 v[216:219], v151 offset:3072
	global_load_lds_dwordx4 v[168:169], off
	v_lshl_add_u64 v[220:221], s[18:19], 0, v[128:129]
	s_add_i32 m0, s16, 0x2000
	s_nop 0
	global_load_lds_dwordx4 v[220:221], off
	s_waitcnt vmcnt(10)
	s_barrier
	s_waitcnt lgkmcnt(0)
	s_setprio 1
	s_waitcnt lgkmcnt(0)
	v_mfma_f32_16x16x32_bf16 v[112:115], v[204:207], v[172:175], v[112:115]
	v_mfma_f32_16x16x32_bf16 v[104:107], v[212:215], v[172:175], v[104:107]
	v_mfma_f32_16x16x32_bf16 v[96:99], v[204:207], v[180:183], v[96:99]
	v_mfma_f32_16x16x32_bf16 v[88:91], v[212:215], v[180:183], v[88:91]
	v_mfma_f32_16x16x32_bf16 v[80:83], v[204:207], v[188:191], v[80:83]
	v_mfma_f32_16x16x32_bf16 v[72:75], v[212:215], v[188:191], v[72:75]
	v_mfma_f32_16x16x32_bf16 v[68:71], v[204:207], v[196:199], v[68:71]
	v_mfma_f32_16x16x32_bf16 v[64:67], v[212:215], v[196:199], v[64:67]
	v_mfma_f32_16x16x32_bf16 v[112:115], v[208:211], v[176:179], v[112:115]
	v_mfma_f32_16x16x32_bf16 v[104:107], v[216:219], v[176:179], v[104:107]
	v_mfma_f32_16x16x32_bf16 v[96:99], v[208:211], v[184:187], v[96:99]
	v_mfma_f32_16x16x32_bf16 v[88:91], v[216:219], v[184:187], v[88:91]
	v_mfma_f32_16x16x32_bf16 v[80:83], v[208:211], v[192:195], v[80:83]
	v_mfma_f32_16x16x32_bf16 v[72:75], v[216:219], v[192:195], v[72:75]
	v_mfma_f32_16x16x32_bf16 v[68:71], v[208:211], v[200:203], v[68:71]
	v_mfma_f32_16x16x32_bf16 v[64:67], v[216:219], v[200:203], v[64:67]
	s_setprio 0
	s_mov_b32 m0, s28
	v_lshl_add_u64 v[222:223], s[20:21], 0, v[134:135]
	s_barrier
	ds_read_b128 v[172:175], v150 offset:16384
	ds_read_b128 v[176:179], v150 offset:17408
	ds_read_b128 v[180:183], v150 offset:18432
	ds_read_b128 v[184:187], v150 offset:19456
	ds_read_b128 v[188:191], v150 offset:20480
	ds_read_b128 v[192:195], v150 offset:21504
	ds_read_b128 v[196:199], v150 offset:22528
	ds_read_b128 v[200:203], v150 offset:23552
	global_load_lds_dwordx4 v[222:223], off
	v_lshl_add_u64 v[224:225], s[20:21], 0, v[130:131]
	s_mov_b32 m0, s29
	s_nop 0
	global_load_lds_dwordx4 v[224:225], off
	s_barrier
	s_waitcnt lgkmcnt(0)
	s_setprio 1
	s_waitcnt lgkmcnt(0)
	v_mfma_f32_16x16x32_bf16 v[60:63], v[152:155], v[172:175], v[60:63]
	v_mfma_f32_16x16x32_bf16 v[56:59], v[160:163], v[172:175], v[56:59]
	v_mfma_f32_16x16x32_bf16 v[52:55], v[152:155], v[180:183], v[52:55]
	v_mfma_f32_16x16x32_bf16 v[44:47], v[160:163], v[180:183], v[44:47]
	v_mfma_f32_16x16x32_bf16 v[36:39], v[152:155], v[188:191], v[36:39]
	v_mfma_f32_16x16x32_bf16 v[28:31], v[160:163], v[188:191], v[28:31]
	v_mfma_f32_16x16x32_bf16 v[20:23], v[152:155], v[196:199], v[20:23]
	v_mfma_f32_16x16x32_bf16 v[12:15], v[160:163], v[196:199], v[12:15]
	v_mfma_f32_16x16x32_bf16 v[60:63], v[156:159], v[176:179], v[60:63]
	v_mfma_f32_16x16x32_bf16 v[56:59], v[164:167], v[176:179], v[56:59]
	v_mfma_f32_16x16x32_bf16 v[52:55], v[156:159], v[184:187], v[52:55]
	v_mfma_f32_16x16x32_bf16 v[44:47], v[164:167], v[184:187], v[44:47]
	v_mfma_f32_16x16x32_bf16 v[36:39], v[156:159], v[192:195], v[36:39]
	v_mfma_f32_16x16x32_bf16 v[28:31], v[164:167], v[192:195], v[28:31]
	v_mfma_f32_16x16x32_bf16 v[20:23], v[156:159], v[200:203], v[20:23]
	v_mfma_f32_16x16x32_bf16 v[12:15], v[164:167], v[200:203], v[12:15]
	s_setprio 0
	s_barrier
	s_add_u32 s16, s18, 0x40000
	s_addc_u32 s17, s19, 0
	s_add_i32 s46, s37, s27
	v_lshl_add_u64 v[152:153], s[16:17], 0, v[132:133]
	s_mov_b32 m0, s46
	s_nop 0
	global_load_lds_dwordx4 v[152:153], off
	v_lshl_add_u64 v[152:153], s[16:17], 0, v[128:129]
	s_add_i32 m0, s46, 0x2000
	s_nop 0
	global_load_lds_dwordx4 v[152:153], off
	s_waitcnt vmcnt(10)
	s_barrier
	s_setprio 1
	v_mfma_f32_16x16x32_bf16 v[48:51], v[204:207], v[172:175], v[48:51]
	v_mfma_f32_16x16x32_bf16 v[40:43], v[212:215], v[172:175], v[40:43]
	v_mfma_f32_16x16x32_bf16 v[32:35], v[204:207], v[180:183], v[32:35]
	v_mfma_f32_16x16x32_bf16 v[24:27], v[212:215], v[180:183], v[24:27]
	v_mfma_f32_16x16x32_bf16 v[16:19], v[204:207], v[188:191], v[16:19]
	v_mfma_f32_16x16x32_bf16 v[8:11], v[212:215], v[188:191], v[8:11]
	v_mfma_f32_16x16x32_bf16 v[4:7], v[204:207], v[196:199], v[4:7]
	v_mfma_f32_16x16x32_bf16 v[0:3], v[212:215], v[196:199], v[0:3]
	v_mfma_f32_16x16x32_bf16 v[48:51], v[208:211], v[176:179], v[48:51]
	v_mfma_f32_16x16x32_bf16 v[40:43], v[216:219], v[176:179], v[40:43]
	v_mfma_f32_16x16x32_bf16 v[32:35], v[208:211], v[184:187], v[32:35]
	v_mfma_f32_16x16x32_bf16 v[24:27], v[216:219], v[184:187], v[24:27]
	v_mfma_f32_16x16x32_bf16 v[16:19], v[208:211], v[192:195], v[16:19]
	v_mfma_f32_16x16x32_bf16 v[8:11], v[216:219], v[192:195], v[8:11]
	v_mfma_f32_16x16x32_bf16 v[4:7], v[208:211], v[200:203], v[4:7]
	v_mfma_f32_16x16x32_bf16 v[0:3], v[216:219], v[200:203], v[0:3]
	s_setprio 0
	s_add_i32 s46, 0, 0x18000
	v_add_u32_e32 v164, s46, v148
	s_barrier
	ds_read_b128 v[152:155], v164
	ds_read_b128 v[156:159], v164 offset:1024
	ds_read_b128 v[160:163], v164 offset:2048
	ds_read_b128 v[164:167], v164 offset:3072
	s_add_u32 s16, s20, 0xea000
	s_addc_u32 s17, s21, 0
	s_mov_b32 m0, s30
	v_lshl_add_u64 v[204:205], s[16:17], 0, v[134:135]
	ds_read_b128 v[172:175], v150 offset:32768
	ds_read_b128 v[176:179], v150 offset:33792
	ds_read_b128 v[180:183], v150 offset:34816
	ds_read_b128 v[184:187], v150 offset:35840
	ds_read_b128 v[188:191], v150 offset:36864
	ds_read_b128 v[192:195], v150 offset:37888
	ds_read_b128 v[196:199], v150 offset:38912
	ds_read_b128 v[200:203], v150 offset:39936
	global_load_lds_dwordx4 v[204:205], off
	v_lshl_add_u64 v[204:205], s[16:17], 0, v[130:131]
	s_mov_b32 m0, s31
	s_nop 0
	global_load_lds_dwordx4 v[204:205], off
	s_waitcnt lgkmcnt(8)
	s_waitcnt vmcnt(10)
	s_barrier
	s_waitcnt lgkmcnt(0)
	s_setprio 1
	s_waitcnt lgkmcnt(0)
	v_mfma_f32_16x16x32_bf16 v[124:127], v[152:155], v[172:175], v[124:127]
	v_mfma_f32_16x16x32_bf16 v[120:123], v[160:163], v[172:175], v[120:123]
	v_mfma_f32_16x16x32_bf16 v[116:119], v[152:155], v[180:183], v[116:119]
	v_mfma_f32_16x16x32_bf16 v[108:111], v[160:163], v[180:183], v[108:111]
	v_mfma_f32_16x16x32_bf16 v[100:103], v[152:155], v[188:191], v[100:103]
	v_mfma_f32_16x16x32_bf16 v[92:95], v[160:163], v[188:191], v[92:95]
	v_mfma_f32_16x16x32_bf16 v[84:87], v[152:155], v[196:199], v[84:87]
	v_mfma_f32_16x16x32_bf16 v[76:79], v[160:163], v[196:199], v[76:79]
	v_mfma_f32_16x16x32_bf16 v[124:127], v[156:159], v[176:179], v[124:127]
	v_mfma_f32_16x16x32_bf16 v[120:123], v[164:167], v[176:179], v[120:123]
	v_mfma_f32_16x16x32_bf16 v[116:119], v[156:159], v[184:187], v[116:119]
	v_mfma_f32_16x16x32_bf16 v[108:111], v[164:167], v[184:187], v[108:111]
	v_mfma_f32_16x16x32_bf16 v[100:103], v[156:159], v[192:195], v[100:103]
	v_mfma_f32_16x16x32_bf16 v[92:95], v[164:167], v[192:195], v[92:95]
	v_mfma_f32_16x16x32_bf16 v[84:87], v[156:159], v[200:203], v[84:87]
	v_mfma_f32_16x16x32_bf16 v[76:79], v[164:167], v[200:203], v[76:79]
	s_setprio 0
	s_barrier
	s_add_i32 s20, 0, 0x1c000
	s_add_i32 s16, s46, s27
	v_add_u32_e32 v171, s20, v148
	v_lshl_add_u64 v[168:169], v[168:169], 0, s[4:5]
	s_mov_b32 m0, s16
	ds_read_b128 v[204:207], v171
	ds_read_b128 v[208:211], v171 offset:1024
	ds_read_b128 v[212:215], v171 offset:2048
	ds_read_b128 v[216:219], v171 offset:3072
	global_load_lds_dwordx4 v[168:169], off
	v_lshl_add_u64 v[168:169], v[220:221], 0, s[4:5]
	s_add_i32 m0, s16, 0x2000
	s_nop 0
	global_load_lds_dwordx4 v[168:169], off
	s_waitcnt vmcnt(10)
	s_barrier
	s_waitcnt lgkmcnt(0)
	s_setprio 1
	s_waitcnt lgkmcnt(0)
	v_mfma_f32_16x16x32_bf16 v[112:115], v[204:207], v[172:175], v[112:115]
	v_mfma_f32_16x16x32_bf16 v[104:107], v[212:215], v[172:175], v[104:107]
	v_mfma_f32_16x16x32_bf16 v[96:99], v[204:207], v[180:183], v[96:99]
	v_mfma_f32_16x16x32_bf16 v[88:91], v[212:215], v[180:183], v[88:91]
	v_mfma_f32_16x16x32_bf16 v[80:83], v[204:207], v[188:191], v[80:83]
	v_mfma_f32_16x16x32_bf16 v[72:75], v[212:215], v[188:191], v[72:75]
	v_mfma_f32_16x16x32_bf16 v[68:71], v[204:207], v[196:199], v[68:71]
	v_mfma_f32_16x16x32_bf16 v[64:67], v[212:215], v[196:199], v[64:67]
	v_mfma_f32_16x16x32_bf16 v[112:115], v[208:211], v[176:179], v[112:115]
	v_mfma_f32_16x16x32_bf16 v[104:107], v[216:219], v[176:179], v[104:107]
	v_mfma_f32_16x16x32_bf16 v[96:99], v[208:211], v[184:187], v[96:99]
	v_mfma_f32_16x16x32_bf16 v[88:91], v[216:219], v[184:187], v[88:91]
	v_mfma_f32_16x16x32_bf16 v[80:83], v[208:211], v[192:195], v[80:83]
	v_mfma_f32_16x16x32_bf16 v[72:75], v[216:219], v[192:195], v[72:75]
	v_mfma_f32_16x16x32_bf16 v[68:71], v[208:211], v[200:203], v[68:71]
	v_mfma_f32_16x16x32_bf16 v[64:67], v[216:219], v[200:203], v[64:67]
	s_setprio 0
	s_mov_b32 m0, s33
	v_lshl_add_u64 v[168:169], v[222:223], 0, s[4:5]
	s_barrier
	ds_read_b128 v[172:175], v150 offset:49152
	ds_read_b128 v[176:179], v150 offset:50176
	ds_read_b128 v[180:183], v150 offset:51200
	ds_read_b128 v[184:187], v150 offset:52224
	ds_read_b128 v[188:191], v150 offset:53248
	ds_read_b128 v[192:195], v150 offset:54272
	ds_read_b128 v[196:199], v150 offset:55296
	ds_read_b128 v[200:203], v150 offset:56320
	global_load_lds_dwordx4 v[168:169], off
	v_lshl_add_u64 v[168:169], v[224:225], 0, s[4:5]
	s_mov_b32 m0, s34
	s_nop 0
	global_load_lds_dwordx4 v[168:169], off
	s_barrier
	s_waitcnt lgkmcnt(0)
	s_setprio 1
	s_waitcnt lgkmcnt(0)
	v_mfma_f32_16x16x32_bf16 v[60:63], v[152:155], v[172:175], v[60:63]
	v_mfma_f32_16x16x32_bf16 v[56:59], v[160:163], v[172:175], v[56:59]
	v_mfma_f32_16x16x32_bf16 v[52:55], v[152:155], v[180:183], v[52:55]
	v_mfma_f32_16x16x32_bf16 v[44:47], v[160:163], v[180:183], v[44:47]
	v_mfma_f32_16x16x32_bf16 v[36:39], v[152:155], v[188:191], v[36:39]
	v_mfma_f32_16x16x32_bf16 v[28:31], v[160:163], v[188:191], v[28:31]
	v_mfma_f32_16x16x32_bf16 v[20:23], v[152:155], v[196:199], v[20:23]
	v_mfma_f32_16x16x32_bf16 v[12:15], v[160:163], v[196:199], v[12:15]
	v_mfma_f32_16x16x32_bf16 v[60:63], v[156:159], v[176:179], v[60:63]
	v_mfma_f32_16x16x32_bf16 v[56:59], v[164:167], v[176:179], v[56:59]
	v_mfma_f32_16x16x32_bf16 v[52:55], v[156:159], v[184:187], v[52:55]
	v_mfma_f32_16x16x32_bf16 v[44:47], v[164:167], v[184:187], v[44:47]
	v_mfma_f32_16x16x32_bf16 v[36:39], v[156:159], v[192:195], v[36:39]
	v_mfma_f32_16x16x32_bf16 v[28:31], v[164:167], v[192:195], v[28:31]
	v_mfma_f32_16x16x32_bf16 v[20:23], v[156:159], v[200:203], v[20:23]
	v_mfma_f32_16x16x32_bf16 v[12:15], v[164:167], v[200:203], v[12:15]
	s_setprio 0
	s_barrier
	s_add_u32 s16, s18, 0x40080
	s_addc_u32 s17, s19, 0
	s_add_i32 s18, s20, s27
	v_lshl_add_u64 v[152:153], s[16:17], 0, v[132:133]
	s_mov_b32 m0, s18
	s_nop 0
	global_load_lds_dwordx4 v[152:153], off
	v_lshl_add_u64 v[152:153], s[16:17], 0, v[128:129]
	s_add_i32 m0, s18, 0x2000
	s_nop 0
	global_load_lds_dwordx4 v[152:153], off
	s_waitcnt vmcnt(10)
	s_barrier
	s_setprio 1
	v_mfma_f32_16x16x32_bf16 v[48:51], v[204:207], v[172:175], v[48:51]
	v_mfma_f32_16x16x32_bf16 v[40:43], v[212:215], v[172:175], v[40:43]
	v_mfma_f32_16x16x32_bf16 v[32:35], v[204:207], v[180:183], v[32:35]
	v_mfma_f32_16x16x32_bf16 v[24:27], v[212:215], v[180:183], v[24:27]
	v_mfma_f32_16x16x32_bf16 v[16:19], v[204:207], v[188:191], v[16:19]
	v_mfma_f32_16x16x32_bf16 v[8:11], v[212:215], v[188:191], v[8:11]
	v_mfma_f32_16x16x32_bf16 v[4:7], v[204:207], v[196:199], v[4:7]
	v_mfma_f32_16x16x32_bf16 v[0:3], v[212:215], v[196:199], v[0:3]
	v_mfma_f32_16x16x32_bf16 v[48:51], v[208:211], v[176:179], v[48:51]
	v_mfma_f32_16x16x32_bf16 v[40:43], v[216:219], v[176:179], v[40:43]
	v_mfma_f32_16x16x32_bf16 v[32:35], v[208:211], v[184:187], v[32:35]
	v_mfma_f32_16x16x32_bf16 v[24:27], v[216:219], v[184:187], v[24:27]
	v_mfma_f32_16x16x32_bf16 v[16:19], v[208:211], v[192:195], v[16:19]
	v_mfma_f32_16x16x32_bf16 v[8:11], v[216:219], v[192:195], v[8:11]
	v_mfma_f32_16x16x32_bf16 v[4:7], v[208:211], v[200:203], v[4:7]
	v_mfma_f32_16x16x32_bf16 v[0:3], v[216:219], v[200:203], v[0:3]
	s_setprio 0
	s_add_i32 s45, s45, 2
	s_add_u32 s43, s43, 0x100
	s_addc_u32 s44, s44, 0
	s_cmp_gt_u32 s45, 13
	s_mov_b64 s[16:17], s[8:9]
	s_barrier
	s_cbranch_scc0 .LBB0_2046
	v_lshl_add_u32 v152, s41, 8, v147
	s_lshl_b32 s8, s40, 8
	v_ashrrev_i32_e32 v153, 31, v152
	s_ashr_i32 s9, s8, 31
	v_lshlrev_b64 v[154:155], 11, v[152:153]
	v_lshl_add_u64 v[154:155], s[0:1], 0, v[154:155]
	s_lshl_b64 s[8:9], s[8:9], 1
	v_lshl_add_u64 v[154:155], v[154:155], 0, s[8:9]
	v_lshl_add_u64 v[154:155], v[154:155], 0, s[2:3]
	v_lshl_add_u64 v[154:155], v[154:155], 0, v[136:137]
	v_mbcnt_lo_u32_b32 v237, -1, 0
	v_mbcnt_hi_u32_b32 v237, -1, v237
	v_bfe_i32 v237, v237, 4, 1
	v_and_b32_e32 v244, 24, v237
	v_add_co_u32_e32 v248, vcc, v244, v154
	s_nop 1
	v_addc_co_u32_e32 v249, vcc, 0, v155, vcc
	v_cvt_pk_bf16_f32 v124, v124, v125
	v_cvt_pk_bf16_f32 v125, v126, v127
	v_cvt_pk_bf16_f32 v120, v120, v121
	v_cvt_pk_bf16_f32 v121, v122, v123
	v_bfi_b32 v244, v237, v124, v120
	v_bfi_b32 v245, v237, v125, v121
	ds_swizzle_b32 v250, v244 offset:0x401f
	ds_swizzle_b32 v251, v245 offset:0x401f
	v_cvt_pk_bf16_f32 v112, v112, v113
	v_cvt_pk_bf16_f32 v113, v114, v115
	v_cvt_pk_bf16_f32 v104, v104, v105
	v_cvt_pk_bf16_f32 v105, v106, v107
	v_bfi_b32 v246, v237, v112, v104
	v_bfi_b32 v247, v237, v113, v105
	ds_swizzle_b32 v252, v246 offset:0x401f
	ds_swizzle_b32 v253, v247 offset:0x401f
	s_waitcnt lgkmcnt(0)
	v_bfi_b32 v240, v237, v250, v124
	v_bfi_b32 v241, v237, v251, v125
	v_bfi_b32 v242, v237, v120, v250
	v_bfi_b32 v243, v237, v121, v251
	global_store_dwordx4 v[248:249], v[240:243], off
	s_nop 1
	v_bfi_b32 v240, v237, v252, v112
	v_bfi_b32 v241, v237, v253, v113
	v_bfi_b32 v242, v237, v104, v252
	v_bfi_b32 v243, v237, v105, v253
	global_store_dwordx4 v[248:249], v[240:243], off offset:256
	s_nop 1
	v_add_co_u32_e32 v238, vcc, 0x8000, v248
	s_nop 1
	v_addc_co_u32_e32 v239, vcc, 0, v249, vcc
	v_cvt_pk_bf16_f32 v116, v116, v117
	v_cvt_pk_bf16_f32 v117, v118, v119
	v_cvt_pk_bf16_f32 v108, v108, v109
	v_cvt_pk_bf16_f32 v109, v110, v111
	v_bfi_b32 v244, v237, v116, v108
	v_bfi_b32 v245, v237, v117, v109
	ds_swizzle_b32 v250, v244 offset:0x401f
	ds_swizzle_b32 v251, v245 offset:0x401f
	v_cvt_pk_bf16_f32 v96, v96, v97
	v_cvt_pk_bf16_f32 v97, v98, v99
	v_cvt_pk_bf16_f32 v88, v88, v89
	v_cvt_pk_bf16_f32 v89, v90, v91
	v_bfi_b32 v246, v237, v96, v88
	v_bfi_b32 v247, v237, v97, v89
	ds_swizzle_b32 v252, v246 offset:0x401f
	ds_swizzle_b32 v253, v247 offset:0x401f
	s_waitcnt lgkmcnt(0)
	v_bfi_b32 v240, v237, v250, v116
	v_bfi_b32 v241, v237, v251, v117
	v_bfi_b32 v242, v237, v108, v250
	v_bfi_b32 v243, v237, v109, v251
	global_store_dwordx4 v[238:239], v[240:243], off
	s_nop 1
	v_bfi_b32 v240, v237, v252, v96
	v_bfi_b32 v241, v237, v253, v97
	v_bfi_b32 v242, v237, v88, v252
	v_bfi_b32 v243, v237, v89, v253
	global_store_dwordx4 v[238:239], v[240:243], off offset:256
	s_nop 1
	v_add_co_u32_e32 v238, vcc, 0x10000, v248
	s_nop 1
	v_addc_co_u32_e32 v239, vcc, 0, v249, vcc
	v_cvt_pk_bf16_f32 v100, v100, v101
	v_cvt_pk_bf16_f32 v101, v102, v103
	v_cvt_pk_bf16_f32 v92, v92, v93
	v_cvt_pk_bf16_f32 v93, v94, v95
	v_bfi_b32 v244, v237, v100, v92
	v_bfi_b32 v245, v237, v101, v93
	ds_swizzle_b32 v250, v244 offset:0x401f
	ds_swizzle_b32 v251, v245 offset:0x401f
	v_cvt_pk_bf16_f32 v80, v80, v81
	v_cvt_pk_bf16_f32 v81, v82, v83
	v_cvt_pk_bf16_f32 v72, v72, v73
	v_cvt_pk_bf16_f32 v73, v74, v75
	v_bfi_b32 v246, v237, v80, v72
	v_bfi_b32 v247, v237, v81, v73
	ds_swizzle_b32 v252, v246 offset:0x401f
	ds_swizzle_b32 v253, v247 offset:0x401f
	s_waitcnt lgkmcnt(0)
	v_bfi_b32 v240, v237, v250, v100
	v_bfi_b32 v241, v237, v251, v101
	v_bfi_b32 v242, v237, v92, v250
	v_bfi_b32 v243, v237, v93, v251
	global_store_dwordx4 v[238:239], v[240:243], off
	s_nop 1
	v_bfi_b32 v240, v237, v252, v80
	v_bfi_b32 v241, v237, v253, v81
	v_bfi_b32 v242, v237, v72, v252
	v_bfi_b32 v243, v237, v73, v253
	global_store_dwordx4 v[238:239], v[240:243], off offset:256
	s_nop 1
	v_add_co_u32_e32 v238, vcc, 0x18000, v248
	s_nop 1
	v_addc_co_u32_e32 v239, vcc, 0, v249, vcc
	v_cvt_pk_bf16_f32 v84, v84, v85
	v_cvt_pk_bf16_f32 v85, v86, v87
	v_cvt_pk_bf16_f32 v76, v76, v77
	v_cvt_pk_bf16_f32 v77, v78, v79
	v_bfi_b32 v244, v237, v84, v76
	v_bfi_b32 v245, v237, v85, v77
	ds_swizzle_b32 v250, v244 offset:0x401f
	ds_swizzle_b32 v251, v245 offset:0x401f
	v_cvt_pk_bf16_f32 v68, v68, v69
	v_cvt_pk_bf16_f32 v69, v70, v71
	v_cvt_pk_bf16_f32 v64, v64, v65
	v_cvt_pk_bf16_f32 v65, v66, v67
	v_bfi_b32 v246, v237, v68, v64
	v_bfi_b32 v247, v237, v69, v65
	ds_swizzle_b32 v252, v246 offset:0x401f
	ds_swizzle_b32 v253, v247 offset:0x401f
	s_waitcnt lgkmcnt(0)
	v_bfi_b32 v240, v237, v250, v84
	v_bfi_b32 v241, v237, v251, v85
	v_bfi_b32 v242, v237, v76, v250
	v_bfi_b32 v243, v237, v77, v251
	global_store_dwordx4 v[238:239], v[240:243], off
	s_nop 1
	v_bfi_b32 v240, v237, v252, v68
	v_bfi_b32 v241, v237, v253, v69
	v_bfi_b32 v242, v237, v64, v252
	v_bfi_b32 v243, v237, v65, v253
	global_store_dwordx4 v[238:239], v[240:243], off offset:256
	s_nop 1
	v_add_co_u32_e32 v238, vcc, 0x40000, v248
	s_nop 1
	v_addc_co_u32_e32 v239, vcc, 0, v249, vcc
	v_cvt_pk_bf16_f32 v60, v60, v61
	v_cvt_pk_bf16_f32 v61, v62, v63
	v_cvt_pk_bf16_f32 v56, v56, v57
	v_cvt_pk_bf16_f32 v57, v58, v59
	v_bfi_b32 v244, v237, v60, v56
	v_bfi_b32 v245, v237, v61, v57
	ds_swizzle_b32 v250, v244 offset:0x401f
	ds_swizzle_b32 v251, v245 offset:0x401f
	v_cvt_pk_bf16_f32 v48, v48, v49
	v_cvt_pk_bf16_f32 v49, v50, v51
	v_cvt_pk_bf16_f32 v40, v40, v41
	v_cvt_pk_bf16_f32 v41, v42, v43
	v_bfi_b32 v246, v237, v48, v40
	v_bfi_b32 v247, v237, v49, v41
	ds_swizzle_b32 v252, v246 offset:0x401f
	ds_swizzle_b32 v253, v247 offset:0x401f
	s_waitcnt lgkmcnt(0)
	v_bfi_b32 v240, v237, v250, v60
	v_bfi_b32 v241, v237, v251, v61
	v_bfi_b32 v242, v237, v56, v250
	v_bfi_b32 v243, v237, v57, v251
	global_store_dwordx4 v[238:239], v[240:243], off
	s_nop 1
	v_bfi_b32 v240, v237, v252, v48
	v_bfi_b32 v241, v237, v253, v49
	v_bfi_b32 v242, v237, v40, v252
	v_bfi_b32 v243, v237, v41, v253
	global_store_dwordx4 v[238:239], v[240:243], off offset:256
	s_nop 1
	v_add_co_u32_e32 v238, vcc, 0x48000, v248
	s_nop 1
	v_addc_co_u32_e32 v239, vcc, 0, v249, vcc
	v_cvt_pk_bf16_f32 v52, v52, v53
	v_cvt_pk_bf16_f32 v53, v54, v55
	v_cvt_pk_bf16_f32 v44, v44, v45
	v_cvt_pk_bf16_f32 v45, v46, v47
	v_bfi_b32 v244, v237, v52, v44
	v_bfi_b32 v245, v237, v53, v45
	ds_swizzle_b32 v250, v244 offset:0x401f
	ds_swizzle_b32 v251, v245 offset:0x401f
	v_cvt_pk_bf16_f32 v32, v32, v33
	v_cvt_pk_bf16_f32 v33, v34, v35
	v_cvt_pk_bf16_f32 v24, v24, v25
	v_cvt_pk_bf16_f32 v25, v26, v27
	v_bfi_b32 v246, v237, v32, v24
	v_bfi_b32 v247, v237, v33, v25
	ds_swizzle_b32 v252, v246 offset:0x401f
	ds_swizzle_b32 v253, v247 offset:0x401f
	s_waitcnt lgkmcnt(0)
	v_bfi_b32 v240, v237, v250, v52
	v_bfi_b32 v241, v237, v251, v53
	v_bfi_b32 v242, v237, v44, v250
	v_bfi_b32 v243, v237, v45, v251
	global_store_dwordx4 v[238:239], v[240:243], off
	s_nop 1
	v_bfi_b32 v240, v237, v252, v32
	v_bfi_b32 v241, v237, v253, v33
	v_bfi_b32 v242, v237, v24, v252
	v_bfi_b32 v243, v237, v25, v253
	global_store_dwordx4 v[238:239], v[240:243], off offset:256
	s_nop 1
	v_add_co_u32_e32 v238, vcc, 0x50000, v248
	s_nop 1
	v_addc_co_u32_e32 v239, vcc, 0, v249, vcc
	v_cvt_pk_bf16_f32 v36, v36, v37
	v_cvt_pk_bf16_f32 v37, v38, v39
	v_cvt_pk_bf16_f32 v28, v28, v29
	v_cvt_pk_bf16_f32 v29, v30, v31
	v_bfi_b32 v244, v237, v36, v28
	v_bfi_b32 v245, v237, v37, v29
	ds_swizzle_b32 v250, v244 offset:0x401f
	ds_swizzle_b32 v251, v245 offset:0x401f
	v_cvt_pk_bf16_f32 v16, v16, v17
	v_cvt_pk_bf16_f32 v17, v18, v19
	v_cvt_pk_bf16_f32 v8, v8, v9
	v_cvt_pk_bf16_f32 v9, v10, v11
	v_bfi_b32 v246, v237, v16, v8
	v_bfi_b32 v247, v237, v17, v9
	ds_swizzle_b32 v252, v246 offset:0x401f
	ds_swizzle_b32 v253, v247 offset:0x401f
	s_waitcnt lgkmcnt(0)
	v_bfi_b32 v240, v237, v250, v36
	v_bfi_b32 v241, v237, v251, v37
	v_bfi_b32 v242, v237, v28, v250
	v_bfi_b32 v243, v237, v29, v251
	global_store_dwordx4 v[238:239], v[240:243], off
	s_nop 1
	v_bfi_b32 v240, v237, v252, v16
	v_bfi_b32 v241, v237, v253, v17
	v_bfi_b32 v242, v237, v8, v252
	v_bfi_b32 v243, v237, v9, v253
	global_store_dwordx4 v[238:239], v[240:243], off offset:256
	s_nop 1
	v_add_co_u32_e32 v238, vcc, 0x58000, v248
	s_nop 1
	v_addc_co_u32_e32 v239, vcc, 0, v249, vcc
	v_cvt_pk_bf16_f32 v20, v20, v21
	v_cvt_pk_bf16_f32 v21, v22, v23
	v_cvt_pk_bf16_f32 v12, v12, v13
	v_cvt_pk_bf16_f32 v13, v14, v15
	v_bfi_b32 v244, v237, v20, v12
	v_bfi_b32 v245, v237, v21, v13
	ds_swizzle_b32 v250, v244 offset:0x401f
	ds_swizzle_b32 v251, v245 offset:0x401f
	v_cvt_pk_bf16_f32 v4, v4, v5
	v_cvt_pk_bf16_f32 v5, v6, v7
	v_cvt_pk_bf16_f32 v0, v0, v1
	v_cvt_pk_bf16_f32 v1, v2, v3
	v_bfi_b32 v246, v237, v4, v0
	v_bfi_b32 v247, v237, v5, v1
	ds_swizzle_b32 v252, v246 offset:0x401f
	ds_swizzle_b32 v253, v247 offset:0x401f
	s_waitcnt lgkmcnt(0)
	v_bfi_b32 v240, v237, v250, v20
	v_bfi_b32 v241, v237, v251, v21
	v_bfi_b32 v242, v237, v12, v250
	v_bfi_b32 v243, v237, v13, v251
	global_store_dwordx4 v[238:239], v[240:243], off
	s_nop 1
	v_bfi_b32 v240, v237, v252, v4
	v_bfi_b32 v241, v237, v253, v5
	v_bfi_b32 v242, v237, v0, v252
	v_bfi_b32 v243, v237, v1, v253
	global_store_dwordx4 v[238:239], v[240:243], off offset:256
	s_nop 1
	s_and_b64 vcc, exec, s[6:7]
	s_mov_b32 s40, s10
	s_mov_b32 s41, s39
	s_mov_b64 s[18:19], s[14:15]
	s_mov_b64 s[16:17], s[12:13]
	s_cbranch_vccz .LBB0_2041
	s_waitcnt vmcnt(0)
	s_cmpk_gt_u32 s22, 0xff
	s_cbranch_scc1 .LBB0_2050
	s_barrier

.LBB0_2183:
	ds_read_b128 v[146:149], v143
	ds_read_b128 v[150:153], v143 offset:1024
	ds_read_b128 v[154:157], v143 offset:2048
	ds_read_b128 v[158:161], v143 offset:3072
	s_add_u32 s8, s6, 0xfffc0080
	s_addc_u32 s9, s7, -1
	s_cmp_eq_u32 s44, 12
	s_cselect_b32 s11, s1, s9
	s_cselect_b32 s10, s35, s8
	s_cselect_b32 s9, s31, s43
	s_cselect_b32 s8, s41, s42
	v_lshl_add_u64 v[196:197], s[6:7], 0, v[134:135]
	s_add_i32 m0, s51, 0xc000
	ds_read_b128 v[162:165], v144
	ds_read_b128 v[166:169], v144 offset:1024
	ds_read_b128 v[172:175], v144 offset:2048
	ds_read_b128 v[176:179], v144 offset:3072
	ds_read_b128 v[180:183], v144 offset:4096
	ds_read_b128 v[184:187], v144 offset:5120
	ds_read_b128 v[188:191], v144 offset:6144
	ds_read_b128 v[192:195], v144 offset:7168
	global_load_lds_dwordx4 v[196:197], off
	v_lshl_add_u64 v[196:197], s[6:7], 0, v[132:133]
	s_add_i32 m0, s51, 0xe000
	s_nop 0
	global_load_lds_dwordx4 v[196:197], off
	s_waitcnt lgkmcnt(8)
	s_waitcnt vmcnt(10)
	s_barrier
	s_waitcnt lgkmcnt(0)
	s_setprio 1
	s_waitcnt lgkmcnt(0)
	v_mfma_f32_16x16x32_bf16 v[124:127], v[146:149], v[162:165], v[124:127]
	v_mfma_f32_16x16x32_bf16 v[108:111], v[154:157], v[162:165], v[108:111]
	v_mfma_f32_16x16x32_bf16 v[120:123], v[146:149], v[172:175], v[120:123]
	v_mfma_f32_16x16x32_bf16 v[96:99], v[154:157], v[172:175], v[96:99]
	v_mfma_f32_16x16x32_bf16 v[116:119], v[146:149], v[180:183], v[116:119]
	v_mfma_f32_16x16x32_bf16 v[88:91], v[154:157], v[180:183], v[88:91]
	v_mfma_f32_16x16x32_bf16 v[104:107], v[146:149], v[188:191], v[104:107]
	v_mfma_f32_16x16x32_bf16 v[76:79], v[154:157], v[188:191], v[76:79]
	v_mfma_f32_16x16x32_bf16 v[124:127], v[150:153], v[166:169], v[124:127]
	v_mfma_f32_16x16x32_bf16 v[108:111], v[158:161], v[166:169], v[108:111]
	v_mfma_f32_16x16x32_bf16 v[120:123], v[150:153], v[176:179], v[120:123]
	v_mfma_f32_16x16x32_bf16 v[96:99], v[158:161], v[176:179], v[96:99]
	v_mfma_f32_16x16x32_bf16 v[116:119], v[150:153], v[184:187], v[116:119]
	v_mfma_f32_16x16x32_bf16 v[88:91], v[158:161], v[184:187], v[88:91]
	v_mfma_f32_16x16x32_bf16 v[104:107], v[150:153], v[192:195], v[104:107]
	v_mfma_f32_16x16x32_bf16 v[76:79], v[158:161], v[192:195], v[76:79]
	s_setprio 0
	s_barrier
	s_add_i32 s45, s60, s50
	v_lshl_add_u64 v[212:213], s[8:9], 0, v[128:129]
	s_mov_b32 m0, s45
	ds_read_b128 v[196:199], v145
	ds_read_b128 v[200:203], v145 offset:1024
	ds_read_b128 v[204:207], v145 offset:2048
	ds_read_b128 v[208:211], v145 offset:3072
	global_load_lds_dwordx4 v[212:213], off
	v_lshl_add_u64 v[214:215], s[8:9], 0, v[130:131]
	s_add_i32 m0, s45, 0x2000
	s_nop 0
	global_load_lds_dwordx4 v[214:215], off
	s_waitcnt vmcnt(10)
	s_barrier
	s_waitcnt lgkmcnt(0)
	s_setprio 1
	s_waitcnt lgkmcnt(0)
	v_mfma_f32_16x16x32_bf16 v[112:115], v[196:199], v[162:165], v[112:115]
	v_mfma_f32_16x16x32_bf16 v[84:87], v[204:207], v[162:165], v[84:87]
	v_mfma_f32_16x16x32_bf16 v[100:103], v[196:199], v[172:175], v[100:103]
	v_mfma_f32_16x16x32_bf16 v[68:71], v[204:207], v[172:175], v[68:71]
	v_mfma_f32_16x16x32_bf16 v[92:95], v[196:199], v[180:183], v[92:95]
	v_mfma_f32_16x16x32_bf16 v[60:63], v[204:207], v[180:183], v[60:63]
	v_mfma_f32_16x16x32_bf16 v[80:83], v[196:199], v[188:191], v[80:83]
	v_mfma_f32_16x16x32_bf16 v[52:55], v[204:207], v[188:191], v[52:55]
	v_mfma_f32_16x16x32_bf16 v[112:115], v[200:203], v[166:169], v[112:115]
	v_mfma_f32_16x16x32_bf16 v[84:87], v[208:211], v[166:169], v[84:87]
	v_mfma_f32_16x16x32_bf16 v[100:103], v[200:203], v[176:179], v[100:103]
	v_mfma_f32_16x16x32_bf16 v[68:71], v[208:211], v[176:179], v[68:71]
	v_mfma_f32_16x16x32_bf16 v[92:95], v[200:203], v[184:187], v[92:95]
	v_mfma_f32_16x16x32_bf16 v[60:63], v[208:211], v[184:187], v[60:63]
	v_mfma_f32_16x16x32_bf16 v[80:83], v[200:203], v[192:195], v[80:83]
	v_mfma_f32_16x16x32_bf16 v[52:55], v[208:211], v[192:195], v[52:55]
	s_setprio 0
	s_mov_b32 m0, s51
	v_lshl_add_u64 v[216:217], s[10:11], 0, v[128:129]
	s_barrier
	ds_read_b128 v[162:165], v144 offset:16384
	ds_read_b128 v[166:169], v144 offset:17408
	ds_read_b128 v[172:175], v144 offset:18432
	ds_read_b128 v[176:179], v144 offset:19456
	ds_read_b128 v[180:183], v144 offset:20480
	ds_read_b128 v[184:187], v144 offset:21504
	ds_read_b128 v[188:191], v144 offset:22528
	ds_read_b128 v[192:195], v144 offset:23552
	global_load_lds_dwordx4 v[216:217], off
	v_lshl_add_u64 v[218:219], s[10:11], 0, v[130:131]
	s_mov_b32 m0, s52
	s_nop 0
	global_load_lds_dwordx4 v[218:219], off
	s_barrier
	s_waitcnt lgkmcnt(0)
	s_setprio 1
	s_waitcnt lgkmcnt(0)
	v_mfma_f32_16x16x32_bf16 v[72:75], v[146:149], v[162:165], v[72:75]
	v_mfma_f32_16x16x32_bf16 v[44:47], v[154:157], v[162:165], v[44:47]
	v_mfma_f32_16x16x32_bf16 v[64:67], v[146:149], v[172:175], v[64:67]
	v_mfma_f32_16x16x32_bf16 v[32:35], v[154:157], v[172:175], v[32:35]
	v_mfma_f32_16x16x32_bf16 v[56:59], v[146:149], v[180:183], v[56:59]
	v_mfma_f32_16x16x32_bf16 v[24:27], v[154:157], v[180:183], v[24:27]
	v_mfma_f32_16x16x32_bf16 v[40:43], v[146:149], v[188:191], v[40:43]
	v_mfma_f32_16x16x32_bf16 v[12:15], v[154:157], v[188:191], v[12:15]
	v_mfma_f32_16x16x32_bf16 v[72:75], v[150:153], v[166:169], v[72:75]
	v_mfma_f32_16x16x32_bf16 v[44:47], v[158:161], v[166:169], v[44:47]
	v_mfma_f32_16x16x32_bf16 v[64:67], v[150:153], v[176:179], v[64:67]
	v_mfma_f32_16x16x32_bf16 v[32:35], v[158:161], v[176:179], v[32:35]
	v_mfma_f32_16x16x32_bf16 v[56:59], v[150:153], v[184:187], v[56:59]
	v_mfma_f32_16x16x32_bf16 v[24:27], v[158:161], v[184:187], v[24:27]
	v_mfma_f32_16x16x32_bf16 v[40:43], v[150:153], v[192:195], v[40:43]
	v_mfma_f32_16x16x32_bf16 v[12:15], v[158:161], v[192:195], v[12:15]
	s_setprio 0
	s_barrier
	s_add_u32 s68, s8, 0x40000
	s_addc_u32 s69, s9, 0
	s_add_i32 s45, s61, s50
	v_lshl_add_u64 v[146:147], s[68:69], 0, v[128:129]
	s_mov_b32 m0, s45
	s_nop 0
	global_load_lds_dwordx4 v[146:147], off
	v_lshl_add_u64 v[146:147], s[68:69], 0, v[130:131]
	s_add_i32 m0, s45, 0x2000
	s_nop 0
	global_load_lds_dwordx4 v[146:147], off
	s_waitcnt vmcnt(10)
	s_barrier
	s_setprio 1
	v_mfma_f32_16x16x32_bf16 v[48:51], v[196:199], v[162:165], v[48:51]
	v_mfma_f32_16x16x32_bf16 v[20:23], v[204:207], v[162:165], v[20:23]
	v_mfma_f32_16x16x32_bf16 v[36:39], v[196:199], v[172:175], v[36:39]
	v_mfma_f32_16x16x32_bf16 v[8:11], v[204:207], v[172:175], v[8:11]
	v_mfma_f32_16x16x32_bf16 v[28:31], v[196:199], v[180:183], v[28:31]
	v_mfma_f32_16x16x32_bf16 v[4:7], v[204:207], v[180:183], v[4:7]
	v_mfma_f32_16x16x32_bf16 v[16:19], v[196:199], v[188:191], v[16:19]
	v_mfma_f32_16x16x32_bf16 v[0:3], v[204:207], v[188:191], v[0:3]
	v_mfma_f32_16x16x32_bf16 v[48:51], v[200:203], v[166:169], v[48:51]
	v_mfma_f32_16x16x32_bf16 v[20:23], v[208:211], v[166:169], v[20:23]
	v_mfma_f32_16x16x32_bf16 v[36:39], v[200:203], v[176:179], v[36:39]
	v_mfma_f32_16x16x32_bf16 v[8:11], v[208:211], v[176:179], v[8:11]
	v_mfma_f32_16x16x32_bf16 v[28:31], v[200:203], v[184:187], v[28:31]
	v_mfma_f32_16x16x32_bf16 v[4:7], v[208:211], v[184:187], v[4:7]
	v_mfma_f32_16x16x32_bf16 v[16:19], v[200:203], v[192:195], v[16:19]
	v_mfma_f32_16x16x32_bf16 v[0:3], v[208:211], v[192:195], v[0:3]
	s_setprio 0
	s_add_i32 s45, 0, 0x18000
	v_add_u32_e32 v158, s45, v141
	s_barrier
	ds_read_b128 v[146:149], v158
	ds_read_b128 v[150:153], v158 offset:1024
	ds_read_b128 v[154:157], v158 offset:2048
	ds_read_b128 v[158:161], v158 offset:3072
	s_add_u32 s10, s10, 0x40000
	s_addc_u32 s11, s11, 0
	s_mov_b32 m0, s53
	v_lshl_add_u64 v[196:197], s[10:11], 0, v[128:129]
	ds_read_b128 v[162:165], v144 offset:32768
	ds_read_b128 v[166:169], v144 offset:33792
	ds_read_b128 v[172:175], v144 offset:34816
	ds_read_b128 v[176:179], v144 offset:35840
	ds_read_b128 v[180:183], v144 offset:36864
	ds_read_b128 v[184:187], v144 offset:37888
	ds_read_b128 v[188:191], v144 offset:38912
	ds_read_b128 v[192:195], v144 offset:39936
	global_load_lds_dwordx4 v[196:197], off
	v_lshl_add_u64 v[196:197], s[10:11], 0, v[130:131]
	s_mov_b32 m0, s54
	s_nop 0
	global_load_lds_dwordx4 v[196:197], off
	s_waitcnt lgkmcnt(8)
	s_waitcnt vmcnt(10)
	s_barrier
	s_waitcnt lgkmcnt(0)
	s_setprio 1
	s_waitcnt lgkmcnt(0)
	v_mfma_f32_16x16x32_bf16 v[124:127], v[146:149], v[162:165], v[124:127]
	v_mfma_f32_16x16x32_bf16 v[108:111], v[154:157], v[162:165], v[108:111]
	v_mfma_f32_16x16x32_bf16 v[120:123], v[146:149], v[172:175], v[120:123]
	v_mfma_f32_16x16x32_bf16 v[96:99], v[154:157], v[172:175], v[96:99]
	v_mfma_f32_16x16x32_bf16 v[116:119], v[146:149], v[180:183], v[116:119]
	v_mfma_f32_16x16x32_bf16 v[88:91], v[154:157], v[180:183], v[88:91]
	v_mfma_f32_16x16x32_bf16 v[104:107], v[146:149], v[188:191], v[104:107]
	v_mfma_f32_16x16x32_bf16 v[76:79], v[154:157], v[188:191], v[76:79]
	v_mfma_f32_16x16x32_bf16 v[124:127], v[150:153], v[166:169], v[124:127]
	v_mfma_f32_16x16x32_bf16 v[108:111], v[158:161], v[166:169], v[108:111]
	v_mfma_f32_16x16x32_bf16 v[120:123], v[150:153], v[176:179], v[120:123]
	v_mfma_f32_16x16x32_bf16 v[96:99], v[158:161], v[176:179], v[96:99]
	v_mfma_f32_16x16x32_bf16 v[116:119], v[150:153], v[184:187], v[116:119]
	v_mfma_f32_16x16x32_bf16 v[88:91], v[158:161], v[184:187], v[88:91]
	v_mfma_f32_16x16x32_bf16 v[104:107], v[150:153], v[192:195], v[104:107]
	v_mfma_f32_16x16x32_bf16 v[76:79], v[158:161], v[192:195], v[76:79]
	s_setprio 0
	s_barrier
	s_add_i32 s10, 0, 0x1c000
	s_add_i32 s11, s45, s50
	v_add_u32_e32 v171, s10, v141
	v_lshl_add_u64 v[212:213], v[212:213], 0, s[18:19]
	s_mov_b32 m0, s11
	ds_read_b128 v[196:199], v171
	ds_read_b128 v[200:203], v171 offset:1024
	ds_read_b128 v[204:207], v171 offset:2048
	ds_read_b128 v[208:211], v171 offset:3072
	global_load_lds_dwordx4 v[212:213], off
	v_lshl_add_u64 v[212:213], v[214:215], 0, s[18:19]
	s_add_i32 m0, s11, 0x2000
	s_nop 0
	global_load_lds_dwordx4 v[212:213], off
	s_waitcnt vmcnt(10)
	s_barrier
	s_waitcnt lgkmcnt(0)
	s_setprio 1
	s_waitcnt lgkmcnt(0)
	v_mfma_f32_16x16x32_bf16 v[112:115], v[196:199], v[162:165], v[112:115]
	v_mfma_f32_16x16x32_bf16 v[84:87], v[204:207], v[162:165], v[84:87]
	v_mfma_f32_16x16x32_bf16 v[100:103], v[196:199], v[172:175], v[100:103]
	v_mfma_f32_16x16x32_bf16 v[68:71], v[204:207], v[172:175], v[68:71]
	v_mfma_f32_16x16x32_bf16 v[92:95], v[196:199], v[180:183], v[92:95]
	v_mfma_f32_16x16x32_bf16 v[60:63], v[204:207], v[180:183], v[60:63]
	v_mfma_f32_16x16x32_bf16 v[80:83], v[196:199], v[188:191], v[80:83]
	v_mfma_f32_16x16x32_bf16 v[52:55], v[204:207], v[188:191], v[52:55]
	v_mfma_f32_16x16x32_bf16 v[112:115], v[200:203], v[166:169], v[112:115]
	v_mfma_f32_16x16x32_bf16 v[84:87], v[208:211], v[166:169], v[84:87]
	v_mfma_f32_16x16x32_bf16 v[100:103], v[200:203], v[176:179], v[100:103]
	v_mfma_f32_16x16x32_bf16 v[68:71], v[208:211], v[176:179], v[68:71]
	v_mfma_f32_16x16x32_bf16 v[92:95], v[200:203], v[184:187], v[92:95]
	v_mfma_f32_16x16x32_bf16 v[60:63], v[208:211], v[184:187], v[60:63]
	v_mfma_f32_16x16x32_bf16 v[80:83], v[200:203], v[192:195], v[80:83]
	v_mfma_f32_16x16x32_bf16 v[52:55], v[208:211], v[192:195], v[52:55]
	s_setprio 0
	s_mov_b32 m0, s57
	v_lshl_add_u64 v[212:213], v[216:217], 0, s[18:19]
	s_barrier
	ds_read_b128 v[162:165], v144 offset:49152
	ds_read_b128 v[166:169], v144 offset:50176
	ds_read_b128 v[172:175], v144 offset:51200
	ds_read_b128 v[176:179], v144 offset:52224
	ds_read_b128 v[180:183], v144 offset:53248
	ds_read_b128 v[184:187], v144 offset:54272
	ds_read_b128 v[188:191], v144 offset:55296
	ds_read_b128 v[192:195], v144 offset:56320
	global_load_lds_dwordx4 v[212:213], off
	v_lshl_add_u64 v[212:213], v[218:219], 0, s[18:19]
	s_mov_b32 m0, s58
	s_nop 0
	global_load_lds_dwordx4 v[212:213], off
	s_barrier
	s_waitcnt lgkmcnt(0)
	s_setprio 1
	s_waitcnt lgkmcnt(0)
	v_mfma_f32_16x16x32_bf16 v[72:75], v[146:149], v[162:165], v[72:75]
	v_mfma_f32_16x16x32_bf16 v[44:47], v[154:157], v[162:165], v[44:47]
	v_mfma_f32_16x16x32_bf16 v[64:67], v[146:149], v[172:175], v[64:67]
	v_mfma_f32_16x16x32_bf16 v[32:35], v[154:157], v[172:175], v[32:35]
	v_mfma_f32_16x16x32_bf16 v[56:59], v[146:149], v[180:183], v[56:59]
	v_mfma_f32_16x16x32_bf16 v[24:27], v[154:157], v[180:183], v[24:27]
	v_mfma_f32_16x16x32_bf16 v[40:43], v[146:149], v[188:191], v[40:43]
	v_mfma_f32_16x16x32_bf16 v[12:15], v[154:157], v[188:191], v[12:15]
	v_mfma_f32_16x16x32_bf16 v[72:75], v[150:153], v[166:169], v[72:75]
	v_mfma_f32_16x16x32_bf16 v[44:47], v[158:161], v[166:169], v[44:47]
	v_mfma_f32_16x16x32_bf16 v[64:67], v[150:153], v[176:179], v[64:67]
	v_mfma_f32_16x16x32_bf16 v[32:35], v[158:161], v[176:179], v[32:35]
	v_mfma_f32_16x16x32_bf16 v[56:59], v[150:153], v[184:187], v[56:59]
	v_mfma_f32_16x16x32_bf16 v[24:27], v[158:161], v[184:187], v[24:27]
	v_mfma_f32_16x16x32_bf16 v[40:43], v[150:153], v[192:195], v[40:43]
	v_mfma_f32_16x16x32_bf16 v[12:15], v[158:161], v[192:195], v[12:15]
	s_setprio 0
	s_barrier
	s_add_u32 s8, s8, 0x40080
	s_addc_u32 s9, s9, 0
	s_add_i32 s10, s10, s50
	v_lshl_add_u64 v[146:147], s[8:9], 0, v[128:129]
	s_mov_b32 m0, s10
	s_nop 0
	global_load_lds_dwordx4 v[146:147], off
	v_lshl_add_u64 v[146:147], s[8:9], 0, v[130:131]
	s_add_i32 m0, s10, 0x2000
	s_nop 0
	global_load_lds_dwordx4 v[146:147], off
	s_waitcnt vmcnt(10)
	s_barrier
	s_setprio 1
	v_mfma_f32_16x16x32_bf16 v[48:51], v[196:199], v[162:165], v[48:51]
	v_mfma_f32_16x16x32_bf16 v[20:23], v[204:207], v[162:165], v[20:23]
	v_mfma_f32_16x16x32_bf16 v[36:39], v[196:199], v[172:175], v[36:39]
	v_mfma_f32_16x16x32_bf16 v[8:11], v[204:207], v[172:175], v[8:11]
	v_mfma_f32_16x16x32_bf16 v[28:31], v[196:199], v[180:183], v[28:31]
	v_mfma_f32_16x16x32_bf16 v[4:7], v[204:207], v[180:183], v[4:7]
	v_mfma_f32_16x16x32_bf16 v[16:19], v[196:199], v[188:191], v[16:19]
	v_mfma_f32_16x16x32_bf16 v[0:3], v[204:207], v[188:191], v[0:3]
	v_mfma_f32_16x16x32_bf16 v[48:51], v[200:203], v[166:169], v[48:51]
	v_mfma_f32_16x16x32_bf16 v[20:23], v[208:211], v[166:169], v[20:23]
	v_mfma_f32_16x16x32_bf16 v[36:39], v[200:203], v[176:179], v[36:39]
	v_mfma_f32_16x16x32_bf16 v[8:11], v[208:211], v[176:179], v[8:11]
	v_mfma_f32_16x16x32_bf16 v[28:31], v[200:203], v[184:187], v[28:31]
	v_mfma_f32_16x16x32_bf16 v[4:7], v[208:211], v[184:187], v[4:7]
	v_mfma_f32_16x16x32_bf16 v[16:19], v[200:203], v[192:195], v[16:19]
	v_mfma_f32_16x16x32_bf16 v[0:3], v[208:211], v[192:195], v[0:3]
	s_setprio 0
	s_add_i32 s44, s44, 2
	s_add_u32 s42, s42, 0x100
	s_addc_u32 s43, s43, 0
	s_add_u32 s6, s6, 0x100
	s_addc_u32 s7, s7, 0
	s_cmp_gt_u32 s44, 13
	s_barrier
	s_cbranch_scc0 .LBB0_2183
	v_mbcnt_lo_u32_b32 v146, -1, 0
	v_mbcnt_hi_u32_b32 v146, -1, v146
	s_mul_i32 s98, s0, 0xfe
	s_mulk_i32 s0, 0xfe
	v_or_b32_e32 v146, s33, v146
	v_mov_b32_e32 v150, 0
	v_ashrrev_i32_e32 v147, 1, v146
	v_add_u32_e32 v149, -1, v147
	v_add_u32_e32 v148, s0, v149
	v_cmp_gt_u32_e32 vcc, s62, v149
	v_cmp_gt_i32_e64 s[0:1], s56, v148
	s_and_b64 s[0:1], vcc, s[0:1]
	v_mov_b32_e32 v151, 0xfff
	s_and_saveexec_b64 s[6:7], s[0:1]
	s_cbranch_execz .LBB0_2190
	v_cmp_lt_i32_e32 vcc, s63, v148
	s_and_saveexec_b64 s[8:9], vcc
	s_xor_b64 s[8:9], exec, s[8:9]
	v_and_b32_e32 v150, 0x7ff, v148
	s_or_saveexec_b64 s[8:9], s[8:9]
	v_mov_b32_e32 v151, 0x7ff
	s_xor_b64 exec, exec, s[8:9]
	v_mov_b32_e32 v151, 0xfff
	v_and_b32_e32 v150, 0xfff, v148
	s_or_b64 exec, exec, s[8:9]

.LBB0_2279:
	ds_read_b128 v[148:151], v145
	ds_read_b128 v[152:155], v145 offset:1024
	ds_read_b128 v[156:159], v145 offset:2048
	ds_read_b128 v[160:163], v145 offset:3072
	s_add_u32 s14, s12, 0x100
	s_addc_u32 s15, s13, 0
	s_cmp_eq_u32 s43, 40
	s_cselect_b32 s19, s7, s15
	s_cselect_b32 s18, s6, s14
	s_cselect_b32 s17, s1, s42
	s_cselect_b32 s16, s0, s41
	s_mov_b32 m0, s36
	v_lshl_add_u64 v[168:169], s[12:13], 0, v[136:137]
	ds_read_b128 v[164:167], v146
	ds_read_b128 v[172:175], v146 offset:1024
	ds_read_b128 v[176:179], v146 offset:2048
	ds_read_b128 v[180:183], v146 offset:3072
	ds_read_b128 v[184:187], v146 offset:4096
	ds_read_b128 v[188:191], v146 offset:5120
	ds_read_b128 v[192:195], v146 offset:6144
	ds_read_b128 v[196:199], v146 offset:7168
	global_load_lds_dwordx4 v[168:169], off
	v_lshl_add_u64 v[168:169], s[12:13], 0, v[134:135]
	s_mov_b32 m0, s37
	s_nop 0
	global_load_lds_dwordx4 v[168:169], off
	s_waitcnt lgkmcnt(8)
	s_waitcnt vmcnt(10)
	s_barrier
	s_waitcnt lgkmcnt(0)
	s_setprio 1
	s_waitcnt lgkmcnt(0)
	v_mfma_f32_16x16x32_bf16 v[124:127], v[148:151], v[164:167], v[124:127]
	v_mfma_f32_16x16x32_bf16 v[120:123], v[156:159], v[164:167], v[120:123]
	v_mfma_f32_16x16x32_bf16 v[116:119], v[148:151], v[176:179], v[116:119]
	v_mfma_f32_16x16x32_bf16 v[108:111], v[156:159], v[176:179], v[108:111]
	v_mfma_f32_16x16x32_bf16 v[100:103], v[148:151], v[184:187], v[100:103]
	v_mfma_f32_16x16x32_bf16 v[92:95], v[156:159], v[184:187], v[92:95]
	v_mfma_f32_16x16x32_bf16 v[84:87], v[148:151], v[192:195], v[84:87]
	v_mfma_f32_16x16x32_bf16 v[76:79], v[156:159], v[192:195], v[76:79]
	v_mfma_f32_16x16x32_bf16 v[124:127], v[152:155], v[172:175], v[124:127]
	v_mfma_f32_16x16x32_bf16 v[120:123], v[160:163], v[172:175], v[120:123]
	v_mfma_f32_16x16x32_bf16 v[116:119], v[152:155], v[180:183], v[116:119]
	v_mfma_f32_16x16x32_bf16 v[108:111], v[160:163], v[180:183], v[108:111]
	v_mfma_f32_16x16x32_bf16 v[100:103], v[152:155], v[188:191], v[100:103]
	v_mfma_f32_16x16x32_bf16 v[92:95], v[160:163], v[188:191], v[92:95]
	v_mfma_f32_16x16x32_bf16 v[84:87], v[152:155], v[196:199], v[84:87]
	v_mfma_f32_16x16x32_bf16 v[76:79], v[160:163], v[196:199], v[76:79]
	s_setprio 0
	s_barrier
	s_add_i32 s12, s34, s25
	v_lshl_add_u64 v[168:169], s[16:17], 0, v[130:131]
	s_mov_b32 m0, s12
	ds_read_b128 v[200:203], v147
	ds_read_b128 v[204:207], v147 offset:1024
	ds_read_b128 v[208:211], v147 offset:2048
	ds_read_b128 v[212:215], v147 offset:3072
	global_load_lds_dwordx4 v[168:169], off
	v_lshl_add_u64 v[216:217], s[16:17], 0, v[128:129]
	s_add_i32 m0, s12, 0x2000
	s_nop 0
	global_load_lds_dwordx4 v[216:217], off
	s_waitcnt vmcnt(10)
	s_barrier
	s_waitcnt lgkmcnt(0)
	s_setprio 1
	s_waitcnt lgkmcnt(0)
	v_mfma_f32_16x16x32_bf16 v[112:115], v[200:203], v[164:167], v[112:115]
	v_mfma_f32_16x16x32_bf16 v[104:107], v[208:211], v[164:167], v[104:107]
	v_mfma_f32_16x16x32_bf16 v[96:99], v[200:203], v[176:179], v[96:99]
	v_mfma_f32_16x16x32_bf16 v[88:91], v[208:211], v[176:179], v[88:91]
	v_mfma_f32_16x16x32_bf16 v[80:83], v[200:203], v[184:187], v[80:83]
	v_mfma_f32_16x16x32_bf16 v[72:75], v[208:211], v[184:187], v[72:75]
	v_mfma_f32_16x16x32_bf16 v[68:71], v[200:203], v[192:195], v[68:71]
	v_mfma_f32_16x16x32_bf16 v[64:67], v[208:211], v[192:195], v[64:67]
	v_mfma_f32_16x16x32_bf16 v[112:115], v[204:207], v[172:175], v[112:115]
	v_mfma_f32_16x16x32_bf16 v[104:107], v[212:215], v[172:175], v[104:107]
	v_mfma_f32_16x16x32_bf16 v[96:99], v[204:207], v[180:183], v[96:99]
	v_mfma_f32_16x16x32_bf16 v[88:91], v[212:215], v[180:183], v[88:91]
	v_mfma_f32_16x16x32_bf16 v[80:83], v[204:207], v[188:191], v[80:83]
	v_mfma_f32_16x16x32_bf16 v[72:75], v[212:215], v[188:191], v[72:75]
	v_mfma_f32_16x16x32_bf16 v[68:71], v[204:207], v[196:199], v[68:71]
	v_mfma_f32_16x16x32_bf16 v[64:67], v[212:215], v[196:199], v[64:67]
	s_setprio 0
	s_mov_b32 m0, s26
	v_lshl_add_u64 v[218:219], s[18:19], 0, v[130:131]
	s_barrier
	ds_read_b128 v[164:167], v146 offset:16384
	ds_read_b128 v[172:175], v146 offset:17408
	ds_read_b128 v[176:179], v146 offset:18432
	ds_read_b128 v[180:183], v146 offset:19456
	ds_read_b128 v[184:187], v146 offset:20480
	ds_read_b128 v[188:191], v146 offset:21504
	ds_read_b128 v[192:195], v146 offset:22528
	ds_read_b128 v[196:199], v146 offset:23552
	global_load_lds_dwordx4 v[218:219], off
	v_lshl_add_u64 v[220:221], s[18:19], 0, v[128:129]
	s_mov_b32 m0, s27
	s_nop 0
	global_load_lds_dwordx4 v[220:221], off
	s_barrier
	s_waitcnt lgkmcnt(0)
	s_setprio 1
	s_waitcnt lgkmcnt(0)
	v_mfma_f32_16x16x32_bf16 v[60:63], v[148:151], v[164:167], v[60:63]
	v_mfma_f32_16x16x32_bf16 v[56:59], v[156:159], v[164:167], v[56:59]
	v_mfma_f32_16x16x32_bf16 v[52:55], v[148:151], v[176:179], v[52:55]
	v_mfma_f32_16x16x32_bf16 v[44:47], v[156:159], v[176:179], v[44:47]
	v_mfma_f32_16x16x32_bf16 v[36:39], v[148:151], v[184:187], v[36:39]
	v_mfma_f32_16x16x32_bf16 v[28:31], v[156:159], v[184:187], v[28:31]
	v_mfma_f32_16x16x32_bf16 v[20:23], v[148:151], v[192:195], v[20:23]
	v_mfma_f32_16x16x32_bf16 v[12:15], v[156:159], v[192:195], v[12:15]
	v_mfma_f32_16x16x32_bf16 v[60:63], v[152:155], v[172:175], v[60:63]
	v_mfma_f32_16x16x32_bf16 v[56:59], v[160:163], v[172:175], v[56:59]
	v_mfma_f32_16x16x32_bf16 v[52:55], v[152:155], v[180:183], v[52:55]
	v_mfma_f32_16x16x32_bf16 v[44:47], v[160:163], v[180:183], v[44:47]
	v_mfma_f32_16x16x32_bf16 v[36:39], v[152:155], v[188:191], v[36:39]
	v_mfma_f32_16x16x32_bf16 v[28:31], v[160:163], v[188:191], v[28:31]
	v_mfma_f32_16x16x32_bf16 v[20:23], v[152:155], v[196:199], v[20:23]
	v_mfma_f32_16x16x32_bf16 v[12:15], v[160:163], v[196:199], v[12:15]
	s_setprio 0
	s_barrier
	s_add_u32 s12, s16, 0xb0000
	s_addc_u32 s13, s17, 0
	s_add_i32 s44, s35, s25
	v_lshl_add_u64 v[148:149], s[12:13], 0, v[130:131]
	s_mov_b32 m0, s44
	s_nop 0
	global_load_lds_dwordx4 v[148:149], off
	v_lshl_add_u64 v[148:149], s[12:13], 0, v[128:129]
	s_add_i32 m0, s44, 0x2000
	s_nop 0
	global_load_lds_dwordx4 v[148:149], off
	s_waitcnt vmcnt(10)
	s_barrier
	s_setprio 1
	v_mfma_f32_16x16x32_bf16 v[48:51], v[200:203], v[164:167], v[48:51]
	v_mfma_f32_16x16x32_bf16 v[40:43], v[208:211], v[164:167], v[40:43]
	v_mfma_f32_16x16x32_bf16 v[32:35], v[200:203], v[176:179], v[32:35]
	v_mfma_f32_16x16x32_bf16 v[24:27], v[208:211], v[176:179], v[24:27]
	v_mfma_f32_16x16x32_bf16 v[16:19], v[200:203], v[184:187], v[16:19]
	v_mfma_f32_16x16x32_bf16 v[8:11], v[208:211], v[184:187], v[8:11]
	v_mfma_f32_16x16x32_bf16 v[4:7], v[200:203], v[192:195], v[4:7]
	v_mfma_f32_16x16x32_bf16 v[0:3], v[208:211], v[192:195], v[0:3]
	v_mfma_f32_16x16x32_bf16 v[48:51], v[204:207], v[172:175], v[48:51]
	v_mfma_f32_16x16x32_bf16 v[40:43], v[212:215], v[172:175], v[40:43]
	v_mfma_f32_16x16x32_bf16 v[32:35], v[204:207], v[180:183], v[32:35]
	v_mfma_f32_16x16x32_bf16 v[24:27], v[212:215], v[180:183], v[24:27]
	v_mfma_f32_16x16x32_bf16 v[16:19], v[204:207], v[188:191], v[16:19]
	v_mfma_f32_16x16x32_bf16 v[8:11], v[212:215], v[188:191], v[8:11]
	v_mfma_f32_16x16x32_bf16 v[4:7], v[204:207], v[196:199], v[4:7]
	v_mfma_f32_16x16x32_bf16 v[0:3], v[212:215], v[196:199], v[0:3]
	s_setprio 0
	s_add_i32 s44, 0, 0x18000
	v_add_u32_e32 v160, s44, v144
	s_barrier
	ds_read_b128 v[148:151], v160
	ds_read_b128 v[152:155], v160 offset:1024
	ds_read_b128 v[156:159], v160 offset:2048
	ds_read_b128 v[160:163], v160 offset:3072
	s_add_u32 s12, s18, 0xb0000
	s_addc_u32 s13, s19, 0
	s_mov_b32 m0, s28
	v_lshl_add_u64 v[200:201], s[12:13], 0, v[130:131]
	ds_read_b128 v[164:167], v146 offset:32768
	ds_read_b128 v[172:175], v146 offset:33792
	ds_read_b128 v[176:179], v146 offset:34816
	ds_read_b128 v[180:183], v146 offset:35840
	ds_read_b128 v[184:187], v146 offset:36864
	ds_read_b128 v[188:191], v146 offset:37888
	ds_read_b128 v[192:195], v146 offset:38912
	ds_read_b128 v[196:199], v146 offset:39936
	global_load_lds_dwordx4 v[200:201], off
	v_lshl_add_u64 v[200:201], s[12:13], 0, v[128:129]
	s_mov_b32 m0, s29
	s_nop 0
	global_load_lds_dwordx4 v[200:201], off
	s_waitcnt lgkmcnt(8)
	s_waitcnt vmcnt(10)
	s_barrier
	s_waitcnt lgkmcnt(0)
	s_setprio 1
	s_waitcnt lgkmcnt(0)
	v_mfma_f32_16x16x32_bf16 v[124:127], v[148:151], v[164:167], v[124:127]
	v_mfma_f32_16x16x32_bf16 v[120:123], v[156:159], v[164:167], v[120:123]
	v_mfma_f32_16x16x32_bf16 v[116:119], v[148:151], v[176:179], v[116:119]
	v_mfma_f32_16x16x32_bf16 v[108:111], v[156:159], v[176:179], v[108:111]
	v_mfma_f32_16x16x32_bf16 v[100:103], v[148:151], v[184:187], v[100:103]
	v_mfma_f32_16x16x32_bf16 v[92:95], v[156:159], v[184:187], v[92:95]
	v_mfma_f32_16x16x32_bf16 v[84:87], v[148:151], v[192:195], v[84:87]
	v_mfma_f32_16x16x32_bf16 v[76:79], v[156:159], v[192:195], v[76:79]
	v_mfma_f32_16x16x32_bf16 v[124:127], v[152:155], v[172:175], v[124:127]
	v_mfma_f32_16x16x32_bf16 v[120:123], v[160:163], v[172:175], v[120:123]
	v_mfma_f32_16x16x32_bf16 v[116:119], v[152:155], v[180:183], v[116:119]
	v_mfma_f32_16x16x32_bf16 v[108:111], v[160:163], v[180:183], v[108:111]
	v_mfma_f32_16x16x32_bf16 v[100:103], v[152:155], v[188:191], v[100:103]
	v_mfma_f32_16x16x32_bf16 v[92:95], v[160:163], v[188:191], v[92:95]
	v_mfma_f32_16x16x32_bf16 v[84:87], v[152:155], v[196:199], v[84:87]
	v_mfma_f32_16x16x32_bf16 v[76:79], v[160:163], v[196:199], v[76:79]
	s_setprio 0
	s_barrier
	s_add_i32 s18, 0, 0x1c000
	s_add_i32 s12, s44, s25
	v_add_u32_e32 v171, s18, v144
	v_lshl_add_u64 v[168:169], v[168:169], 0, s[10:11]
	s_mov_b32 m0, s12
	ds_read_b128 v[200:203], v171
	ds_read_b128 v[204:207], v171 offset:1024
	ds_read_b128 v[208:211], v171 offset:2048
	ds_read_b128 v[212:215], v171 offset:3072
	global_load_lds_dwordx4 v[168:169], off
	v_lshl_add_u64 v[168:169], v[216:217], 0, s[10:11]
	s_add_i32 m0, s12, 0x2000
	s_nop 0
	global_load_lds_dwordx4 v[168:169], off
	s_waitcnt vmcnt(10)
	s_barrier
	s_waitcnt lgkmcnt(0)
	s_setprio 1
	s_waitcnt lgkmcnt(0)
	v_mfma_f32_16x16x32_bf16 v[112:115], v[200:203], v[164:167], v[112:115]
	v_mfma_f32_16x16x32_bf16 v[104:107], v[208:211], v[164:167], v[104:107]
	v_mfma_f32_16x16x32_bf16 v[96:99], v[200:203], v[176:179], v[96:99]
	v_mfma_f32_16x16x32_bf16 v[88:91], v[208:211], v[176:179], v[88:91]
	v_mfma_f32_16x16x32_bf16 v[80:83], v[200:203], v[184:187], v[80:83]
	v_mfma_f32_16x16x32_bf16 v[72:75], v[208:211], v[184:187], v[72:75]
	v_mfma_f32_16x16x32_bf16 v[68:71], v[200:203], v[192:195], v[68:71]
	v_mfma_f32_16x16x32_bf16 v[64:67], v[208:211], v[192:195], v[64:67]
	v_mfma_f32_16x16x32_bf16 v[112:115], v[204:207], v[172:175], v[112:115]
	v_mfma_f32_16x16x32_bf16 v[104:107], v[212:215], v[172:175], v[104:107]
	v_mfma_f32_16x16x32_bf16 v[96:99], v[204:207], v[180:183], v[96:99]
	v_mfma_f32_16x16x32_bf16 v[88:91], v[212:215], v[180:183], v[88:91]
	v_mfma_f32_16x16x32_bf16 v[80:83], v[204:207], v[188:191], v[80:83]
	v_mfma_f32_16x16x32_bf16 v[72:75], v[212:215], v[188:191], v[72:75]
	v_mfma_f32_16x16x32_bf16 v[68:71], v[204:207], v[196:199], v[68:71]
	v_mfma_f32_16x16x32_bf16 v[64:67], v[212:215], v[196:199], v[64:67]
	s_setprio 0
	s_mov_b32 m0, s30
	v_lshl_add_u64 v[168:169], v[218:219], 0, s[10:11]
	s_barrier
	ds_read_b128 v[164:167], v146 offset:49152
	ds_read_b128 v[172:175], v146 offset:50176
	ds_read_b128 v[176:179], v146 offset:51200
	ds_read_b128 v[180:183], v146 offset:52224
	ds_read_b128 v[184:187], v146 offset:53248
	ds_read_b128 v[188:191], v146 offset:54272
	ds_read_b128 v[192:195], v146 offset:55296
	ds_read_b128 v[196:199], v146 offset:56320
	global_load_lds_dwordx4 v[168:169], off
	v_lshl_add_u64 v[168:169], v[220:221], 0, s[10:11]
	s_mov_b32 m0, s31
	s_nop 0
	global_load_lds_dwordx4 v[168:169], off
	s_barrier
	s_waitcnt lgkmcnt(0)
	s_setprio 1
	s_waitcnt lgkmcnt(0)
	v_mfma_f32_16x16x32_bf16 v[60:63], v[148:151], v[164:167], v[60:63]
	v_mfma_f32_16x16x32_bf16 v[56:59], v[156:159], v[164:167], v[56:59]
	v_mfma_f32_16x16x32_bf16 v[52:55], v[148:151], v[176:179], v[52:55]
	v_mfma_f32_16x16x32_bf16 v[44:47], v[156:159], v[176:179], v[44:47]
	v_mfma_f32_16x16x32_bf16 v[36:39], v[148:151], v[184:187], v[36:39]
	v_mfma_f32_16x16x32_bf16 v[28:31], v[156:159], v[184:187], v[28:31]
	v_mfma_f32_16x16x32_bf16 v[20:23], v[148:151], v[192:195], v[20:23]
	v_mfma_f32_16x16x32_bf16 v[12:15], v[156:159], v[192:195], v[12:15]
	v_mfma_f32_16x16x32_bf16 v[60:63], v[152:155], v[172:175], v[60:63]
	v_mfma_f32_16x16x32_bf16 v[56:59], v[160:163], v[172:175], v[56:59]
	v_mfma_f32_16x16x32_bf16 v[52:55], v[152:155], v[180:183], v[52:55]
	v_mfma_f32_16x16x32_bf16 v[44:47], v[160:163], v[180:183], v[44:47]
	v_mfma_f32_16x16x32_bf16 v[36:39], v[152:155], v[188:191], v[36:39]
	v_mfma_f32_16x16x32_bf16 v[28:31], v[160:163], v[188:191], v[28:31]
	v_mfma_f32_16x16x32_bf16 v[20:23], v[152:155], v[196:199], v[20:23]
	v_mfma_f32_16x16x32_bf16 v[12:15], v[160:163], v[196:199], v[12:15]
	s_setprio 0
	s_barrier
	s_add_u32 s12, s16, 0xb0080
	s_addc_u32 s13, s17, 0
	s_add_i32 s16, s18, s25
	v_lshl_add_u64 v[148:149], s[12:13], 0, v[130:131]
	s_mov_b32 m0, s16
	s_nop 0
	global_load_lds_dwordx4 v[148:149], off
	v_lshl_add_u64 v[148:149], s[12:13], 0, v[128:129]
	s_add_i32 m0, s16, 0x2000
	s_nop 0
	global_load_lds_dwordx4 v[148:149], off
	s_waitcnt vmcnt(10)
	s_barrier
	s_setprio 1
	v_mfma_f32_16x16x32_bf16 v[48:51], v[200:203], v[164:167], v[48:51]
	v_mfma_f32_16x16x32_bf16 v[40:43], v[208:211], v[164:167], v[40:43]
	v_mfma_f32_16x16x32_bf16 v[32:35], v[200:203], v[176:179], v[32:35]
	v_mfma_f32_16x16x32_bf16 v[24:27], v[208:211], v[176:179], v[24:27]
	v_mfma_f32_16x16x32_bf16 v[16:19], v[200:203], v[184:187], v[16:19]
	v_mfma_f32_16x16x32_bf16 v[8:11], v[208:211], v[184:187], v[8:11]
	v_mfma_f32_16x16x32_bf16 v[4:7], v[200:203], v[192:195], v[4:7]
	v_mfma_f32_16x16x32_bf16 v[0:3], v[208:211], v[192:195], v[0:3]
	v_mfma_f32_16x16x32_bf16 v[48:51], v[204:207], v[172:175], v[48:51]
	v_mfma_f32_16x16x32_bf16 v[40:43], v[212:215], v[172:175], v[40:43]
	v_mfma_f32_16x16x32_bf16 v[32:35], v[204:207], v[180:183], v[32:35]
	v_mfma_f32_16x16x32_bf16 v[24:27], v[212:215], v[180:183], v[24:27]
	v_mfma_f32_16x16x32_bf16 v[16:19], v[204:207], v[188:191], v[16:19]
	v_mfma_f32_16x16x32_bf16 v[8:11], v[212:215], v[188:191], v[8:11]
	v_mfma_f32_16x16x32_bf16 v[4:7], v[204:207], v[196:199], v[4:7]
	v_mfma_f32_16x16x32_bf16 v[0:3], v[212:215], v[196:199], v[0:3]
	s_setprio 0
	s_add_i32 s43, s43, 2
	s_add_u32 s41, s41, 0x100
	s_addc_u32 s42, s42, 0
	s_cmp_gt_u32 s43, 41
	s_mov_b64 s[12:13], s[14:15]
	s_barrier
	s_cbranch_scc0 .LBB0_2279
	v_readlane_b32 s12, v235, 24
	v_lshl_add_u32 v148, s12, 8, v143
	v_readlane_b32 s12, v235, 16
	s_lshl_b32 s12, s12, 8
	v_ashrrev_i32_e32 v149, 31, v148
	s_ashr_i32 s13, s12, 31
	v_lshlrev_b64 v[150:151], 11, v[148:149]
	v_lshl_add_u64 v[150:151], s[2:3], 0, v[150:151]
	s_lshl_b64 s[12:13], s[12:13], 1
	v_lshl_add_u64 v[150:151], v[150:151], 0, s[12:13]
	v_lshl_add_u64 v[150:151], v[150:151], 0, s[8:9]
	v_lshl_add_u64 v[150:151], v[150:151], 0, v[132:133]
	v_mbcnt_lo_u32_b32 v237, -1, 0
	v_mbcnt_hi_u32_b32 v237, -1, v237
	v_bfe_i32 v237, v237, 4, 1
	v_and_b32_e32 v244, 24, v237
	v_add_co_u32_e32 v248, vcc, v244, v150
	s_nop 1
	v_addc_co_u32_e32 v249, vcc, 0, v151, vcc
	v_cvt_pk_bf16_f32 v124, v124, v125
	v_cvt_pk_bf16_f32 v125, v126, v127
	v_cvt_pk_bf16_f32 v120, v120, v121
	v_cvt_pk_bf16_f32 v121, v122, v123
	v_bfi_b32 v244, v237, v124, v120
	v_bfi_b32 v245, v237, v125, v121
	ds_swizzle_b32 v250, v244 offset:0x401f
	ds_swizzle_b32 v251, v245 offset:0x401f
	v_cvt_pk_bf16_f32 v112, v112, v113
	v_cvt_pk_bf16_f32 v113, v114, v115
	v_cvt_pk_bf16_f32 v104, v104, v105
	v_cvt_pk_bf16_f32 v105, v106, v107
	v_bfi_b32 v246, v237, v112, v104
	v_bfi_b32 v247, v237, v113, v105
	ds_swizzle_b32 v252, v246 offset:0x401f
	ds_swizzle_b32 v253, v247 offset:0x401f
	s_waitcnt lgkmcnt(0)
	v_bfi_b32 v240, v237, v250, v124
	v_bfi_b32 v241, v237, v251, v125
	v_bfi_b32 v242, v237, v120, v250
	v_bfi_b32 v243, v237, v121, v251
	global_store_dwordx4 v[248:249], v[240:243], off
	s_nop 1
	v_bfi_b32 v240, v237, v252, v112
	v_bfi_b32 v241, v237, v253, v113
	v_bfi_b32 v242, v237, v104, v252
	v_bfi_b32 v243, v237, v105, v253
	global_store_dwordx4 v[248:249], v[240:243], off offset:256
	s_nop 1
	v_add_co_u32_e32 v238, vcc, 0x8000, v248
	s_nop 1
	v_addc_co_u32_e32 v239, vcc, 0, v249, vcc
	v_cvt_pk_bf16_f32 v116, v116, v117
	v_cvt_pk_bf16_f32 v117, v118, v119
	v_cvt_pk_bf16_f32 v108, v108, v109
	v_cvt_pk_bf16_f32 v109, v110, v111
	v_bfi_b32 v244, v237, v116, v108
	v_bfi_b32 v245, v237, v117, v109
	ds_swizzle_b32 v250, v244 offset:0x401f
	ds_swizzle_b32 v251, v245 offset:0x401f
	v_cvt_pk_bf16_f32 v96, v96, v97
	v_cvt_pk_bf16_f32 v97, v98, v99
	v_cvt_pk_bf16_f32 v88, v88, v89
	v_cvt_pk_bf16_f32 v89, v90, v91
	v_bfi_b32 v246, v237, v96, v88
	v_bfi_b32 v247, v237, v97, v89
	ds_swizzle_b32 v252, v246 offset:0x401f
	ds_swizzle_b32 v253, v247 offset:0x401f
	s_waitcnt lgkmcnt(0)
	v_bfi_b32 v240, v237, v250, v116
	v_bfi_b32 v241, v237, v251, v117
	v_bfi_b32 v242, v237, v108, v250
	v_bfi_b32 v243, v237, v109, v251
	global_store_dwordx4 v[238:239], v[240:243], off
	s_nop 1
	v_bfi_b32 v240, v237, v252, v96
	v_bfi_b32 v241, v237, v253, v97
	v_bfi_b32 v242, v237, v88, v252
	v_bfi_b32 v243, v237, v89, v253
	global_store_dwordx4 v[238:239], v[240:243], off offset:256
	s_nop 1
	v_add_co_u32_e32 v238, vcc, 0x10000, v248
	s_nop 1
	v_addc_co_u32_e32 v239, vcc, 0, v249, vcc
	v_cvt_pk_bf16_f32 v100, v100, v101
	v_cvt_pk_bf16_f32 v101, v102, v103
	v_cvt_pk_bf16_f32 v92, v92, v93
	v_cvt_pk_bf16_f32 v93, v94, v95
	v_bfi_b32 v244, v237, v100, v92
	v_bfi_b32 v245, v237, v101, v93
	ds_swizzle_b32 v250, v244 offset:0x401f
	ds_swizzle_b32 v251, v245 offset:0x401f
	v_cvt_pk_bf16_f32 v80, v80, v81
	v_cvt_pk_bf16_f32 v81, v82, v83
	v_cvt_pk_bf16_f32 v72, v72, v73
	v_cvt_pk_bf16_f32 v73, v74, v75
	v_bfi_b32 v246, v237, v80, v72
	v_bfi_b32 v247, v237, v81, v73
	ds_swizzle_b32 v252, v246 offset:0x401f
	ds_swizzle_b32 v253, v247 offset:0x401f
	s_waitcnt lgkmcnt(0)
	v_bfi_b32 v240, v237, v250, v100
	v_bfi_b32 v241, v237, v251, v101
	v_bfi_b32 v242, v237, v92, v250
	v_bfi_b32 v243, v237, v93, v251
	global_store_dwordx4 v[238:239], v[240:243], off
	s_nop 1
	v_bfi_b32 v240, v237, v252, v80
	v_bfi_b32 v241, v237, v253, v81
	v_bfi_b32 v242, v237, v72, v252
	v_bfi_b32 v243, v237, v73, v253
	global_store_dwordx4 v[238:239], v[240:243], off offset:256
	s_nop 1
	v_add_co_u32_e32 v238, vcc, 0x18000, v248
	s_nop 1
	v_addc_co_u32_e32 v239, vcc, 0, v249, vcc
	v_cvt_pk_bf16_f32 v84, v84, v85
	v_cvt_pk_bf16_f32 v85, v86, v87
	v_cvt_pk_bf16_f32 v76, v76, v77
	v_cvt_pk_bf16_f32 v77, v78, v79
	v_bfi_b32 v244, v237, v84, v76
	v_bfi_b32 v245, v237, v85, v77
	ds_swizzle_b32 v250, v244 offset:0x401f
	ds_swizzle_b32 v251, v245 offset:0x401f
	v_cvt_pk_bf16_f32 v68, v68, v69
	v_cvt_pk_bf16_f32 v69, v70, v71
	v_cvt_pk_bf16_f32 v64, v64, v65
	v_cvt_pk_bf16_f32 v65, v66, v67
	v_bfi_b32 v246, v237, v68, v64
	v_bfi_b32 v247, v237, v69, v65
	ds_swizzle_b32 v252, v246 offset:0x401f
	ds_swizzle_b32 v253, v247 offset:0x401f
	s_waitcnt lgkmcnt(0)
	v_bfi_b32 v240, v237, v250, v84
	v_bfi_b32 v241, v237, v251, v85
	v_bfi_b32 v242, v237, v76, v250
	v_bfi_b32 v243, v237, v77, v251
	global_store_dwordx4 v[238:239], v[240:243], off
	s_nop 1
	v_bfi_b32 v240, v237, v252, v68
	v_bfi_b32 v241, v237, v253, v69
	v_bfi_b32 v242, v237, v64, v252
	v_bfi_b32 v243, v237, v65, v253
	global_store_dwordx4 v[238:239], v[240:243], off offset:256
	s_nop 1
	v_add_co_u32_e32 v238, vcc, 0x40000, v248
	s_nop 1
	v_addc_co_u32_e32 v239, vcc, 0, v249, vcc
	v_cvt_pk_bf16_f32 v60, v60, v61
	v_cvt_pk_bf16_f32 v61, v62, v63
	v_cvt_pk_bf16_f32 v56, v56, v57
	v_cvt_pk_bf16_f32 v57, v58, v59
	v_bfi_b32 v244, v237, v60, v56
	v_bfi_b32 v245, v237, v61, v57
	ds_swizzle_b32 v250, v244 offset:0x401f
	ds_swizzle_b32 v251, v245 offset:0x401f
	v_cvt_pk_bf16_f32 v48, v48, v49
	v_cvt_pk_bf16_f32 v49, v50, v51
	v_cvt_pk_bf16_f32 v40, v40, v41
	v_cvt_pk_bf16_f32 v41, v42, v43
	v_bfi_b32 v246, v237, v48, v40
	v_bfi_b32 v247, v237, v49, v41
	ds_swizzle_b32 v252, v246 offset:0x401f
	ds_swizzle_b32 v253, v247 offset:0x401f
	s_waitcnt lgkmcnt(0)
	v_bfi_b32 v240, v237, v250, v60
	v_bfi_b32 v241, v237, v251, v61
	v_bfi_b32 v242, v237, v56, v250
	v_bfi_b32 v243, v237, v57, v251
	global_store_dwordx4 v[238:239], v[240:243], off
	s_nop 1
	v_bfi_b32 v240, v237, v252, v48
	v_bfi_b32 v241, v237, v253, v49
	v_bfi_b32 v242, v237, v40, v252
	v_bfi_b32 v243, v237, v41, v253
	global_store_dwordx4 v[238:239], v[240:243], off offset:256
	s_nop 1
	v_add_co_u32_e32 v238, vcc, 0x48000, v248
	s_nop 1
	v_addc_co_u32_e32 v239, vcc, 0, v249, vcc
	v_cvt_pk_bf16_f32 v52, v52, v53
	v_cvt_pk_bf16_f32 v53, v54, v55
	v_cvt_pk_bf16_f32 v44, v44, v45
	v_cvt_pk_bf16_f32 v45, v46, v47
	v_bfi_b32 v244, v237, v52, v44
	v_bfi_b32 v245, v237, v53, v45
	ds_swizzle_b32 v250, v244 offset:0x401f
	ds_swizzle_b32 v251, v245 offset:0x401f
	v_cvt_pk_bf16_f32 v32, v32, v33
	v_cvt_pk_bf16_f32 v33, v34, v35
	v_cvt_pk_bf16_f32 v24, v24, v25
	v_cvt_pk_bf16_f32 v25, v26, v27
	v_bfi_b32 v246, v237, v32, v24
	v_bfi_b32 v247, v237, v33, v25
	ds_swizzle_b32 v252, v246 offset:0x401f
	ds_swizzle_b32 v253, v247 offset:0x401f
	s_waitcnt lgkmcnt(0)
	v_bfi_b32 v240, v237, v250, v52
	v_bfi_b32 v241, v237, v251, v53
	v_bfi_b32 v242, v237, v44, v250
	v_bfi_b32 v243, v237, v45, v251
	global_store_dwordx4 v[238:239], v[240:243], off
	s_nop 1
	v_bfi_b32 v240, v237, v252, v32
	v_bfi_b32 v241, v237, v253, v33
	v_bfi_b32 v242, v237, v24, v252
	v_bfi_b32 v243, v237, v25, v253
	global_store_dwordx4 v[238:239], v[240:243], off offset:256
	s_nop 1
	v_add_co_u32_e32 v238, vcc, 0x50000, v248
	s_nop 1
	v_addc_co_u32_e32 v239, vcc, 0, v249, vcc
	v_cvt_pk_bf16_f32 v36, v36, v37
	v_cvt_pk_bf16_f32 v37, v38, v39
	v_cvt_pk_bf16_f32 v28, v28, v29
	v_cvt_pk_bf16_f32 v29, v30, v31
	v_bfi_b32 v244, v237, v36, v28
	v_bfi_b32 v245, v237, v37, v29
	ds_swizzle_b32 v250, v244 offset:0x401f
	ds_swizzle_b32 v251, v245 offset:0x401f
	v_cvt_pk_bf16_f32 v16, v16, v17
	v_cvt_pk_bf16_f32 v17, v18, v19
	v_cvt_pk_bf16_f32 v8, v8, v9
	v_cvt_pk_bf16_f32 v9, v10, v11
	v_bfi_b32 v246, v237, v16, v8
	v_bfi_b32 v247, v237, v17, v9
	ds_swizzle_b32 v252, v246 offset:0x401f
	ds_swizzle_b32 v253, v247 offset:0x401f
	s_waitcnt lgkmcnt(0)
	v_bfi_b32 v240, v237, v250, v36
	v_bfi_b32 v241, v237, v251, v37
	v_bfi_b32 v242, v237, v28, v250
	v_bfi_b32 v243, v237, v29, v251
	global_store_dwordx4 v[238:239], v[240:243], off
	s_nop 1
	v_bfi_b32 v240, v237, v252, v16
	v_bfi_b32 v241, v237, v253, v17
	v_bfi_b32 v242, v237, v8, v252
	v_bfi_b32 v243, v237, v9, v253
	global_store_dwordx4 v[238:239], v[240:243], off offset:256
	s_nop 1
	v_add_co_u32_e32 v238, vcc, 0x58000, v248
	s_nop 1
	v_addc_co_u32_e32 v239, vcc, 0, v249, vcc
	v_cvt_pk_bf16_f32 v20, v20, v21
	v_cvt_pk_bf16_f32 v21, v22, v23
	v_cvt_pk_bf16_f32 v12, v12, v13
	v_cvt_pk_bf16_f32 v13, v14, v15
	v_bfi_b32 v244, v237, v20, v12
	v_bfi_b32 v245, v237, v21, v13
	ds_swizzle_b32 v250, v244 offset:0x401f
	ds_swizzle_b32 v251, v245 offset:0x401f
	v_cvt_pk_bf16_f32 v4, v4, v5
	v_cvt_pk_bf16_f32 v5, v6, v7
	v_cvt_pk_bf16_f32 v0, v0, v1
	v_cvt_pk_bf16_f32 v1, v2, v3
	v_bfi_b32 v246, v237, v4, v0
	v_bfi_b32 v247, v237, v5, v1
	ds_swizzle_b32 v252, v246 offset:0x401f
	ds_swizzle_b32 v253, v247 offset:0x401f
	s_waitcnt lgkmcnt(0)
	v_bfi_b32 v240, v237, v250, v20
	v_bfi_b32 v241, v237, v251, v21
	v_bfi_b32 v242, v237, v12, v250
	v_bfi_b32 v243, v237, v13, v251
	global_store_dwordx4 v[238:239], v[240:243], off
	s_nop 1
	v_bfi_b32 v240, v237, v252, v4
	v_bfi_b32 v241, v237, v253, v5
	v_bfi_b32 v242, v237, v0, v252
	v_bfi_b32 v243, v237, v1, v253
	global_store_dwordx4 v[238:239], v[240:243], off offset:256
	s_nop 1
	s_and_b64 vcc, exec, s[4:5]
	v_writelane_b32 v235, s39, 16
	s_mov_b64 s[14:15], s[0:1]
	s_mov_b64 s[12:13], s[6:7]
	v_writelane_b32 v235, s40, 24
	s_cbranch_vccz .LBB0_2272
	s_waitcnt vmcnt(0)
	s_cmpk_gt_u32 s20, 0xff
	s_cbranch_scc1 .LBB0_2283
	s_barrier
